# GEMM K-loops: LDS-DMA loads use SGPR base + 32-bit lane offset instead of a per-load 64-bit VALU add
# speedup vs baseline: 1.0236x; 1.0021x over previous
.LBB0_359:
	ds_read_b128 v[130:133], v185
	ds_read_b128 v[134:137], v185 offset:1024
	ds_read_b128 v[138:141], v185 offset:2048
	ds_read_b128 v[142:145], v185 offset:3072
	ds_read_b128 v[146:149], v187
	ds_read_b128 v[150:153], v187 offset:1024
	ds_read_b128 v[154:157], v187 offset:2048
	ds_read_b128 v[192:195], v187 offset:3072
	s_add_u32 s30, s28, 0xfff80080
	s_addc_u32 s31, s29, -1
	s_cmp_eq_u32 s76, 28
	s_cselect_b32 s35, s6, s31
	s_cselect_b32 s34, s21, s30
	s_cselect_b32 s31, s19, s75
	s_cselect_b32 s30, s73, s74
	s_add_i32 m0, s27, 0xc000
	ds_read_b128 v[196:199], v189
	ds_read_b128 v[200:203], v189 offset:1024
	ds_read_b128 v[204:207], v189 offset:2048
	ds_read_b128 v[208:211], v189 offset:3072
	ds_read_b128 v[212:215], v189 offset:4096
	ds_read_b128 v[216:219], v189 offset:5120
	ds_read_b128 v[220:223], v189 offset:6144
	ds_read_b128 v[224:227], v189 offset:7168
	global_load_lds_dwordx4 v174, s[28:29]
	s_add_i32 m0, s27, 0xe000
	s_nop 0
	global_load_lds_dwordx4 v172, s[28:29]
	s_waitcnt vmcnt(8)
	s_waitcnt lgkmcnt(0)
	s_barrier
	s_setprio 1
	s_waitcnt lgkmcnt(0)
	v_mfma_f32_16x16x32_bf16 v[124:127], v[130:133], v[196:199], v[124:127]
	v_mfma_f32_16x16x32_bf16 v[120:123], v[138:141], v[196:199], v[120:123]
	v_mfma_f32_16x16x32_bf16 v[112:115], v[130:133], v[204:207], v[112:115]
	v_mfma_f32_16x16x32_bf16 v[104:107], v[138:141], v[204:207], v[104:107]
	v_mfma_f32_16x16x32_bf16 v[96:99], v[130:133], v[212:215], v[96:99]
	v_mfma_f32_16x16x32_bf16 v[88:91], v[138:141], v[212:215], v[88:91]
	v_mfma_f32_16x16x32_bf16 v[80:83], v[130:133], v[220:223], v[80:83]
	v_mfma_f32_16x16x32_bf16 v[72:75], v[138:141], v[220:223], v[72:75]
	v_mfma_f32_16x16x32_bf16 v[124:127], v[134:137], v[200:203], v[124:127]
	v_mfma_f32_16x16x32_bf16 v[120:123], v[142:145], v[200:203], v[120:123]
	v_mfma_f32_16x16x32_bf16 v[112:115], v[134:137], v[208:211], v[112:115]
	v_mfma_f32_16x16x32_bf16 v[104:107], v[142:145], v[208:211], v[104:107]
	v_mfma_f32_16x16x32_bf16 v[96:99], v[134:137], v[216:219], v[96:99]
	v_mfma_f32_16x16x32_bf16 v[88:91], v[142:145], v[216:219], v[88:91]
	v_mfma_f32_16x16x32_bf16 v[80:83], v[134:137], v[224:227], v[80:83]
	v_mfma_f32_16x16x32_bf16 v[72:75], v[142:145], v[224:227], v[72:75]
	s_setprio 0
	s_setprio 1
	v_mfma_f32_16x16x32_bf16 v[116:119], v[146:149], v[196:199], v[116:119]
	v_mfma_f32_16x16x32_bf16 v[108:111], v[154:157], v[196:199], v[108:111]
	v_mfma_f32_16x16x32_bf16 v[100:103], v[146:149], v[204:207], v[100:103]
	v_mfma_f32_16x16x32_bf16 v[92:95], v[154:157], v[204:207], v[92:95]
	v_mfma_f32_16x16x32_bf16 v[84:87], v[146:149], v[212:215], v[84:87]
	v_mfma_f32_16x16x32_bf16 v[76:79], v[154:157], v[212:215], v[76:79]
	v_mfma_f32_16x16x32_bf16 v[68:71], v[146:149], v[220:223], v[68:71]
	v_mfma_f32_16x16x32_bf16 v[64:67], v[154:157], v[220:223], v[64:67]
	v_mfma_f32_16x16x32_bf16 v[116:119], v[150:153], v[200:203], v[116:119]
	v_mfma_f32_16x16x32_bf16 v[108:111], v[192:195], v[200:203], v[108:111]
	v_mfma_f32_16x16x32_bf16 v[100:103], v[150:153], v[208:211], v[100:103]
	v_mfma_f32_16x16x32_bf16 v[92:95], v[192:195], v[208:211], v[92:95]
	s_barrier
	s_setprio 2
	v_mfma_f32_16x16x32_bf16 v[84:87], v[150:153], v[216:219], v[84:87]
	v_mfma_f32_16x16x32_bf16 v[76:79], v[192:195], v[216:219], v[76:79]
	v_mfma_f32_16x16x32_bf16 v[68:71], v[150:153], v[224:227], v[68:71]
	v_mfma_f32_16x16x32_bf16 v[64:67], v[192:195], v[224:227], v[64:67]
	s_setprio 0
	s_add_i32 s77, s57, s67
	v_lshl_add_u64 v[158:159], s[30:31], 0, v[162:163]
	s_mov_b32 m0, s77
	ds_read_b128 v[196:199], v189 offset:16384
	ds_read_b128 v[200:203], v189 offset:17408
	ds_read_b128 v[204:207], v189 offset:18432
	ds_read_b128 v[208:211], v189 offset:19456
	ds_read_b128 v[212:215], v189 offset:20480
	ds_read_b128 v[216:219], v189 offset:21504
	ds_read_b128 v[220:223], v189 offset:22528
	ds_read_b128 v[224:227], v189 offset:23552
	global_load_lds_dwordx4 v162, s[30:31]
	s_add_i32 m0, s77, 0x2000
	s_add_u32 s78, s30, 0x80000
	v_lshl_add_u64 v[228:229], s[30:31], 0, v[166:167]
	s_addc_u32 s79, s31, 0
	s_add_i32 s77, s58, s67
	global_load_lds_dwordx4 v166, s[30:31]
	s_mov_b32 m0, s77
	v_lshl_add_u64 v[232:233], s[34:35], 0, v[164:165]
	global_load_lds_dwordx4 v162, s[78:79]
	s_add_i32 m0, s77, 0x2000
	s_nop 0
	global_load_lds_dwordx4 v166, s[78:79]
	v_lshl_add_u64 v[230:231], s[34:35], 0, v[160:161]
	s_mov_b32 m0, s27
	s_nop 0
	global_load_lds_dwordx4 v160, s[34:35]
	s_mov_b32 m0, s41
	s_nop 0
	global_load_lds_dwordx4 v164, s[34:35]
	s_waitcnt vmcnt(8)
	s_waitcnt lgkmcnt(0)
	s_barrier
	s_setprio 1
	s_waitcnt lgkmcnt(0)
	v_mfma_f32_16x16x32_bf16 v[60:63], v[130:133], v[196:199], v[60:63]
	v_mfma_f32_16x16x32_bf16 v[56:59], v[138:141], v[196:199], v[56:59]
	v_mfma_f32_16x16x32_bf16 v[48:51], v[130:133], v[204:207], v[48:51]
	v_mfma_f32_16x16x32_bf16 v[40:43], v[138:141], v[204:207], v[40:43]
	v_mfma_f32_16x16x32_bf16 v[32:35], v[130:133], v[212:215], v[32:35]
	v_mfma_f32_16x16x32_bf16 v[24:27], v[138:141], v[212:215], v[24:27]
	v_mfma_f32_16x16x32_bf16 v[16:19], v[130:133], v[220:223], v[16:19]
	v_mfma_f32_16x16x32_bf16 v[8:11], v[138:141], v[220:223], v[8:11]
	v_mfma_f32_16x16x32_bf16 v[60:63], v[134:137], v[200:203], v[60:63]
	v_mfma_f32_16x16x32_bf16 v[56:59], v[142:145], v[200:203], v[56:59]
	v_mfma_f32_16x16x32_bf16 v[48:51], v[134:137], v[208:211], v[48:51]
	v_mfma_f32_16x16x32_bf16 v[40:43], v[142:145], v[208:211], v[40:43]
	v_mfma_f32_16x16x32_bf16 v[32:35], v[134:137], v[216:219], v[32:35]
	v_mfma_f32_16x16x32_bf16 v[24:27], v[142:145], v[216:219], v[24:27]
	v_mfma_f32_16x16x32_bf16 v[16:19], v[134:137], v[224:227], v[16:19]
	v_mfma_f32_16x16x32_bf16 v[8:11], v[142:145], v[224:227], v[8:11]
	s_setprio 0
	s_setprio 1
	v_mfma_f32_16x16x32_bf16 v[52:55], v[146:149], v[196:199], v[52:55]
	v_mfma_f32_16x16x32_bf16 v[44:47], v[154:157], v[196:199], v[44:47]
	v_mfma_f32_16x16x32_bf16 v[36:39], v[146:149], v[204:207], v[36:39]
	v_mfma_f32_16x16x32_bf16 v[28:31], v[154:157], v[204:207], v[28:31]
	v_mfma_f32_16x16x32_bf16 v[20:23], v[146:149], v[212:215], v[20:23]
	v_mfma_f32_16x16x32_bf16 v[12:15], v[154:157], v[212:215], v[12:15]
	v_mfma_f32_16x16x32_bf16 v[4:7], v[146:149], v[220:223], v[4:7]
	v_mfma_f32_16x16x32_bf16 v[0:3], v[154:157], v[220:223], v[0:3]
	v_mfma_f32_16x16x32_bf16 v[52:55], v[150:153], v[200:203], v[52:55]
	v_mfma_f32_16x16x32_bf16 v[44:47], v[192:195], v[200:203], v[44:47]
	v_mfma_f32_16x16x32_bf16 v[36:39], v[150:153], v[208:211], v[36:39]
	v_mfma_f32_16x16x32_bf16 v[28:31], v[192:195], v[208:211], v[28:31]
	s_barrier
	s_setprio 2
	v_mfma_f32_16x16x32_bf16 v[20:23], v[150:153], v[216:219], v[20:23]
	v_mfma_f32_16x16x32_bf16 v[12:15], v[192:195], v[216:219], v[12:15]
	v_mfma_f32_16x16x32_bf16 v[4:7], v[150:153], v[224:227], v[4:7]
	v_mfma_f32_16x16x32_bf16 v[0:3], v[192:195], v[224:227], v[0:3]
	s_setprio 0
	s_add_i32 s77, 0, 0x18000
	v_add_u32_e32 v129, s77, v181
	s_add_i32 s78, 0, 0x1c000
	ds_read_b128 v[130:133], v129
	ds_read_b128 v[134:137], v129 offset:1024
	ds_read_b128 v[138:141], v129 offset:2048
	ds_read_b128 v[142:145], v129 offset:3072
	v_add_u32_e32 v129, s78, v181
	ds_read_b128 v[146:149], v129
	ds_read_b128 v[150:153], v129 offset:1024
	ds_read_b128 v[154:157], v129 offset:2048
	ds_read_b128 v[192:195], v129 offset:3072
	s_add_u32 s34, s34, 0x80000
	s_addc_u32 s35, s35, 0
	s_mov_b32 m0, s42
	ds_read_b128 v[196:199], v189 offset:32768
	ds_read_b128 v[200:203], v189 offset:33792
	ds_read_b128 v[204:207], v189 offset:34816
	ds_read_b128 v[208:211], v189 offset:35840
	ds_read_b128 v[212:215], v189 offset:36864
	ds_read_b128 v[216:219], v189 offset:37888
	ds_read_b128 v[220:223], v189 offset:38912
	ds_read_b128 v[224:227], v189 offset:39936
	global_load_lds_dwordx4 v160, s[34:35]
	s_mov_b32 m0, s43
	s_nop 0
	global_load_lds_dwordx4 v164, s[34:35]
	s_waitcnt vmcnt(8)
	s_waitcnt lgkmcnt(0)
	s_barrier
	s_setprio 1
	s_waitcnt lgkmcnt(0)
	v_mfma_f32_16x16x32_bf16 v[124:127], v[130:133], v[196:199], v[124:127]
	v_mfma_f32_16x16x32_bf16 v[120:123], v[138:141], v[196:199], v[120:123]
	v_mfma_f32_16x16x32_bf16 v[112:115], v[130:133], v[204:207], v[112:115]
	v_mfma_f32_16x16x32_bf16 v[104:107], v[138:141], v[204:207], v[104:107]
	v_mfma_f32_16x16x32_bf16 v[96:99], v[130:133], v[212:215], v[96:99]
	v_mfma_f32_16x16x32_bf16 v[88:91], v[138:141], v[212:215], v[88:91]
	v_mfma_f32_16x16x32_bf16 v[80:83], v[130:133], v[220:223], v[80:83]
	v_mfma_f32_16x16x32_bf16 v[72:75], v[138:141], v[220:223], v[72:75]
	v_mfma_f32_16x16x32_bf16 v[124:127], v[134:137], v[200:203], v[124:127]
	v_mfma_f32_16x16x32_bf16 v[120:123], v[142:145], v[200:203], v[120:123]
	v_mfma_f32_16x16x32_bf16 v[112:115], v[134:137], v[208:211], v[112:115]
	v_mfma_f32_16x16x32_bf16 v[104:107], v[142:145], v[208:211], v[104:107]
	v_mfma_f32_16x16x32_bf16 v[96:99], v[134:137], v[216:219], v[96:99]
	v_mfma_f32_16x16x32_bf16 v[88:91], v[142:145], v[216:219], v[88:91]
	v_mfma_f32_16x16x32_bf16 v[80:83], v[134:137], v[224:227], v[80:83]
	v_mfma_f32_16x16x32_bf16 v[72:75], v[142:145], v[224:227], v[72:75]
	s_setprio 0
	s_setprio 1
	v_mfma_f32_16x16x32_bf16 v[116:119], v[146:149], v[196:199], v[116:119]
	v_mfma_f32_16x16x32_bf16 v[108:111], v[154:157], v[196:199], v[108:111]
	v_mfma_f32_16x16x32_bf16 v[100:103], v[146:149], v[204:207], v[100:103]
	v_mfma_f32_16x16x32_bf16 v[92:95], v[154:157], v[204:207], v[92:95]
	v_mfma_f32_16x16x32_bf16 v[84:87], v[146:149], v[212:215], v[84:87]
	v_mfma_f32_16x16x32_bf16 v[76:79], v[154:157], v[212:215], v[76:79]
	v_mfma_f32_16x16x32_bf16 v[68:71], v[146:149], v[220:223], v[68:71]
	v_mfma_f32_16x16x32_bf16 v[64:67], v[154:157], v[220:223], v[64:67]
	v_mfma_f32_16x16x32_bf16 v[116:119], v[150:153], v[200:203], v[116:119]
	v_mfma_f32_16x16x32_bf16 v[108:111], v[192:195], v[200:203], v[108:111]
	v_mfma_f32_16x16x32_bf16 v[100:103], v[150:153], v[208:211], v[100:103]
	v_mfma_f32_16x16x32_bf16 v[92:95], v[192:195], v[208:211], v[92:95]
	s_barrier
	s_setprio 2
	v_mfma_f32_16x16x32_bf16 v[84:87], v[150:153], v[216:219], v[84:87]
	v_mfma_f32_16x16x32_bf16 v[76:79], v[192:195], v[216:219], v[76:79]
	v_mfma_f32_16x16x32_bf16 v[68:71], v[150:153], v[224:227], v[68:71]
	v_mfma_f32_16x16x32_bf16 v[64:67], v[192:195], v[224:227], v[64:67]
	s_setprio 0
	s_add_i32 s34, s77, s67
	v_lshl_add_u64 v[158:159], v[158:159], 0, s[12:13]
	s_mov_b32 m0, s34
	ds_read_b128 v[196:199], v189 offset:49152
	ds_read_b128 v[200:203], v189 offset:50176
	ds_read_b128 v[204:207], v189 offset:51200
	ds_read_b128 v[208:211], v189 offset:52224
	ds_read_b128 v[212:215], v189 offset:53248
	ds_read_b128 v[216:219], v189 offset:54272
	ds_read_b128 v[220:223], v189 offset:55296
	ds_read_b128 v[224:227], v189 offset:56320
	global_load_lds_dwordx4 v[158:159], off
	s_add_i32 m0, s34, 0x2000
	s_add_u32 s30, s30, 0x80080
	v_lshl_add_u64 v[158:159], v[228:229], 0, s[12:13]
	s_addc_u32 s31, s31, 0
	s_add_i32 s34, s78, s67
	global_load_lds_dwordx4 v[158:159], off
	s_mov_b32 m0, s34
	s_nop 0
	global_load_lds_dwordx4 v162, s[30:31]
	s_add_i32 m0, s34, 0x2000
	s_nop 0
	global_load_lds_dwordx4 v166, s[30:31]
	v_lshl_add_u64 v[158:159], v[230:231], 0, s[12:13]
	s_mov_b32 m0, s45
	s_nop 0
	global_load_lds_dwordx4 v[158:159], off
	v_lshl_add_u64 v[158:159], v[232:233], 0, s[12:13]
	s_mov_b32 m0, s47
	s_nop 0
	global_load_lds_dwordx4 v[158:159], off
	s_waitcnt vmcnt(8)
	s_waitcnt lgkmcnt(0)
	s_barrier
	s_setprio 1
	s_waitcnt lgkmcnt(0)
	v_mfma_f32_16x16x32_bf16 v[60:63], v[130:133], v[196:199], v[60:63]
	v_mfma_f32_16x16x32_bf16 v[56:59], v[138:141], v[196:199], v[56:59]
	v_mfma_f32_16x16x32_bf16 v[48:51], v[130:133], v[204:207], v[48:51]
	v_mfma_f32_16x16x32_bf16 v[40:43], v[138:141], v[204:207], v[40:43]
	v_mfma_f32_16x16x32_bf16 v[32:35], v[130:133], v[212:215], v[32:35]
	v_mfma_f32_16x16x32_bf16 v[24:27], v[138:141], v[212:215], v[24:27]
	v_mfma_f32_16x16x32_bf16 v[16:19], v[130:133], v[220:223], v[16:19]
	v_mfma_f32_16x16x32_bf16 v[8:11], v[138:141], v[220:223], v[8:11]
	v_mfma_f32_16x16x32_bf16 v[60:63], v[134:137], v[200:203], v[60:63]
	v_mfma_f32_16x16x32_bf16 v[56:59], v[142:145], v[200:203], v[56:59]
	v_mfma_f32_16x16x32_bf16 v[48:51], v[134:137], v[208:211], v[48:51]
	v_mfma_f32_16x16x32_bf16 v[40:43], v[142:145], v[208:211], v[40:43]
	v_mfma_f32_16x16x32_bf16 v[32:35], v[134:137], v[216:219], v[32:35]
	v_mfma_f32_16x16x32_bf16 v[24:27], v[142:145], v[216:219], v[24:27]
	v_mfma_f32_16x16x32_bf16 v[16:19], v[134:137], v[224:227], v[16:19]
	v_mfma_f32_16x16x32_bf16 v[8:11], v[142:145], v[224:227], v[8:11]
	s_setprio 0
	s_setprio 1
	v_mfma_f32_16x16x32_bf16 v[52:55], v[146:149], v[196:199], v[52:55]
	v_mfma_f32_16x16x32_bf16 v[44:47], v[154:157], v[196:199], v[44:47]
	v_mfma_f32_16x16x32_bf16 v[36:39], v[146:149], v[204:207], v[36:39]
	v_mfma_f32_16x16x32_bf16 v[28:31], v[154:157], v[204:207], v[28:31]
	v_mfma_f32_16x16x32_bf16 v[20:23], v[146:149], v[212:215], v[20:23]
	v_mfma_f32_16x16x32_bf16 v[12:15], v[154:157], v[212:215], v[12:15]
	v_mfma_f32_16x16x32_bf16 v[4:7], v[146:149], v[220:223], v[4:7]
	v_mfma_f32_16x16x32_bf16 v[0:3], v[154:157], v[220:223], v[0:3]
	v_mfma_f32_16x16x32_bf16 v[52:55], v[150:153], v[200:203], v[52:55]
	v_mfma_f32_16x16x32_bf16 v[44:47], v[192:195], v[200:203], v[44:47]
	v_mfma_f32_16x16x32_bf16 v[36:39], v[150:153], v[208:211], v[36:39]
	v_mfma_f32_16x16x32_bf16 v[28:31], v[192:195], v[208:211], v[28:31]
	s_barrier
	s_setprio 2
	v_mfma_f32_16x16x32_bf16 v[20:23], v[150:153], v[216:219], v[20:23]
	v_mfma_f32_16x16x32_bf16 v[12:15], v[192:195], v[216:219], v[12:15]
	v_mfma_f32_16x16x32_bf16 v[4:7], v[150:153], v[224:227], v[4:7]
	v_mfma_f32_16x16x32_bf16 v[0:3], v[192:195], v[224:227], v[0:3]
	s_setprio 0
	s_add_i32 s76, s76, 2
	s_add_u32 s74, s74, 0x100
	s_addc_u32 s75, s75, 0
	s_add_u32 s28, s28, 0x100
	s_addc_u32 s29, s29, 0
	s_cmp_gt_u32 s76, 29
	s_cbranch_scc0 .LBB0_359
	s_and_b64 vcc, exec, s[14:15]
	s_cbranch_vccz .LBB0_362
	s_barrier

.LBB0_1192:
	ds_read_b128 v[128:131], v215
	ds_read_b128 v[132:135], v215 offset:1024
	ds_read_b128 v[136:139], v215 offset:2048
	ds_read_b128 v[158:161], v215 offset:3072
	ds_read_b128 v[162:165], v216
	ds_read_b128 v[166:169], v216 offset:1024
	ds_read_b128 v[170:173], v216 offset:2048
	ds_read_b128 v[174:177], v216 offset:3072
	s_add_u32 s24, s22, 0xfff80080
	s_addc_u32 s25, s23, -1
	s_cmp_eq_u32 s30, 28
	s_cselect_b32 s27, s3, s25
	s_cselect_b32 s26, s15, s24
	s_cselect_b32 s25, s13, s29
	s_cselect_b32 s24, s21, s28
	s_add_i32 m0, s38, 0xc000
	ds_read_b128 v[178:181], v217
	ds_read_b128 v[182:185], v217 offset:1024
	ds_read_b128 v[186:189], v217 offset:2048
	ds_read_b128 v[190:193], v217 offset:3072
	ds_read_b128 v[194:197], v217 offset:4096
	ds_read_b128 v[198:201], v217 offset:5120
	ds_read_b128 v[202:205], v217 offset:6144
	ds_read_b128 v[206:209], v217 offset:7168
	global_load_lds_dwordx4 v152, s[22:23]
	s_add_i32 m0, s38, 0xe000
	s_nop 0
	global_load_lds_dwordx4 v150, s[22:23]
	s_waitcnt vmcnt(8)
	s_waitcnt lgkmcnt(0)
	s_barrier
	s_setprio 1
	s_waitcnt lgkmcnt(0)
	v_mfma_f32_16x16x32_bf16 v[124:127], v[128:131], v[178:181], v[124:127]
	v_mfma_f32_16x16x32_bf16 v[120:123], v[136:139], v[178:181], v[120:123]
	v_mfma_f32_16x16x32_bf16 v[116:119], v[128:131], v[186:189], v[116:119]
	v_mfma_f32_16x16x32_bf16 v[112:115], v[136:139], v[186:189], v[112:115]
	v_mfma_f32_16x16x32_bf16 v[108:111], v[128:131], v[194:197], v[108:111]
	v_mfma_f32_16x16x32_bf16 v[104:107], v[136:139], v[194:197], v[104:107]
	v_mfma_f32_16x16x32_bf16 v[100:103], v[128:131], v[202:205], v[100:103]
	v_mfma_f32_16x16x32_bf16 v[96:99], v[136:139], v[202:205], v[96:99]
	v_mfma_f32_16x16x32_bf16 v[124:127], v[132:135], v[182:185], v[124:127]
	v_mfma_f32_16x16x32_bf16 v[120:123], v[158:161], v[182:185], v[120:123]
	v_mfma_f32_16x16x32_bf16 v[116:119], v[132:135], v[190:193], v[116:119]
	v_mfma_f32_16x16x32_bf16 v[112:115], v[158:161], v[190:193], v[112:115]
	v_mfma_f32_16x16x32_bf16 v[108:111], v[132:135], v[198:201], v[108:111]
	v_mfma_f32_16x16x32_bf16 v[104:107], v[158:161], v[198:201], v[104:107]
	v_mfma_f32_16x16x32_bf16 v[100:103], v[132:135], v[206:209], v[100:103]
	v_mfma_f32_16x16x32_bf16 v[96:99], v[158:161], v[206:209], v[96:99]
	s_setprio 0
	s_setprio 1
	v_mfma_f32_16x16x32_bf16 v[60:63], v[162:165], v[178:181], v[60:63]
	v_mfma_f32_16x16x32_bf16 v[56:59], v[170:173], v[178:181], v[56:59]
	v_mfma_f32_16x16x32_bf16 v[52:55], v[162:165], v[186:189], v[52:55]
	v_mfma_f32_16x16x32_bf16 v[48:51], v[170:173], v[186:189], v[48:51]
	v_mfma_f32_16x16x32_bf16 v[44:47], v[162:165], v[194:197], v[44:47]
	v_mfma_f32_16x16x32_bf16 v[40:43], v[170:173], v[194:197], v[40:43]
	v_mfma_f32_16x16x32_bf16 v[36:39], v[162:165], v[202:205], v[36:39]
	v_mfma_f32_16x16x32_bf16 v[32:35], v[170:173], v[202:205], v[32:35]
	v_mfma_f32_16x16x32_bf16 v[60:63], v[166:169], v[182:185], v[60:63]
	v_mfma_f32_16x16x32_bf16 v[56:59], v[174:177], v[182:185], v[56:59]
	v_mfma_f32_16x16x32_bf16 v[52:55], v[166:169], v[190:193], v[52:55]
	v_mfma_f32_16x16x32_bf16 v[48:51], v[174:177], v[190:193], v[48:51]
	s_barrier
	s_setprio 2
	v_mfma_f32_16x16x32_bf16 v[44:47], v[166:169], v[198:201], v[44:47]
	v_mfma_f32_16x16x32_bf16 v[40:43], v[174:177], v[198:201], v[40:43]
	v_mfma_f32_16x16x32_bf16 v[36:39], v[166:169], v[206:209], v[36:39]
	v_mfma_f32_16x16x32_bf16 v[32:35], v[174:177], v[206:209], v[32:35]
	s_setprio 0
	s_add_i32 s31, s60, s67
	v_lshl_add_u64 v[210:211], s[24:25], 0, v[142:143]
	s_mov_b32 m0, s31
	ds_read_b128 v[178:181], v217 offset:16384
	ds_read_b128 v[182:185], v217 offset:17408
	ds_read_b128 v[186:189], v217 offset:18432
	ds_read_b128 v[190:193], v217 offset:19456
	ds_read_b128 v[194:197], v217 offset:20480
	ds_read_b128 v[198:201], v217 offset:21504
	ds_read_b128 v[202:205], v217 offset:22528
	ds_read_b128 v[206:209], v217 offset:23552
	global_load_lds_dwordx4 v142, s[24:25]
	s_add_i32 m0, s31, 0x2000
	s_add_u32 s74, s24, 0x80000
	v_lshl_add_u64 v[212:213], s[24:25], 0, v[146:147]
	s_addc_u32 s75, s25, 0
	s_add_i32 s31, s61, s67
	global_load_lds_dwordx4 v146, s[24:25]
	s_mov_b32 m0, s31
	v_lshl_add_u64 v[222:223], s[26:27], 0, v[144:145]
	global_load_lds_dwordx4 v142, s[74:75]
	s_add_i32 m0, s31, 0x2000
	s_nop 0
	global_load_lds_dwordx4 v146, s[74:75]
	v_lshl_add_u64 v[220:221], s[26:27], 0, v[140:141]
	s_mov_b32 m0, s38
	s_nop 0
	global_load_lds_dwordx4 v140, s[26:27]
	s_mov_b32 m0, s39
	s_nop 0
	global_load_lds_dwordx4 v144, s[26:27]
	s_waitcnt vmcnt(8)
	s_waitcnt lgkmcnt(0)
	s_barrier
	s_setprio 1
	s_waitcnt lgkmcnt(0)
	v_mfma_f32_16x16x32_bf16 v[92:95], v[128:131], v[178:181], v[92:95]
	v_mfma_f32_16x16x32_bf16 v[88:91], v[136:139], v[178:181], v[88:91]
	v_mfma_f32_16x16x32_bf16 v[84:87], v[128:131], v[186:189], v[84:87]
	v_mfma_f32_16x16x32_bf16 v[80:83], v[136:139], v[186:189], v[80:83]
	v_mfma_f32_16x16x32_bf16 v[76:79], v[128:131], v[194:197], v[76:79]
	v_mfma_f32_16x16x32_bf16 v[72:75], v[136:139], v[194:197], v[72:75]
	v_mfma_f32_16x16x32_bf16 v[68:71], v[128:131], v[202:205], v[68:71]
	v_mfma_f32_16x16x32_bf16 v[64:67], v[136:139], v[202:205], v[64:67]
	v_mfma_f32_16x16x32_bf16 v[92:95], v[132:135], v[182:185], v[92:95]
	v_mfma_f32_16x16x32_bf16 v[88:91], v[158:161], v[182:185], v[88:91]
	v_mfma_f32_16x16x32_bf16 v[84:87], v[132:135], v[190:193], v[84:87]
	v_mfma_f32_16x16x32_bf16 v[80:83], v[158:161], v[190:193], v[80:83]
	v_mfma_f32_16x16x32_bf16 v[76:79], v[132:135], v[198:201], v[76:79]
	v_mfma_f32_16x16x32_bf16 v[72:75], v[158:161], v[198:201], v[72:75]
	v_mfma_f32_16x16x32_bf16 v[68:71], v[132:135], v[206:209], v[68:71]
	v_mfma_f32_16x16x32_bf16 v[64:67], v[158:161], v[206:209], v[64:67]
	s_setprio 0
	s_setprio 1
	v_mfma_f32_16x16x32_bf16 v[28:31], v[162:165], v[178:181], v[28:31]
	v_mfma_f32_16x16x32_bf16 v[24:27], v[170:173], v[178:181], v[24:27]
	v_mfma_f32_16x16x32_bf16 v[20:23], v[162:165], v[186:189], v[20:23]
	v_mfma_f32_16x16x32_bf16 v[16:19], v[170:173], v[186:189], v[16:19]
	v_mfma_f32_16x16x32_bf16 v[12:15], v[162:165], v[194:197], v[12:15]
	v_mfma_f32_16x16x32_bf16 v[8:11], v[170:173], v[194:197], v[8:11]
	v_mfma_f32_16x16x32_bf16 v[4:7], v[162:165], v[202:205], v[4:7]
	v_mfma_f32_16x16x32_bf16 v[0:3], v[170:173], v[202:205], v[0:3]
	v_mfma_f32_16x16x32_bf16 v[28:31], v[166:169], v[182:185], v[28:31]
	v_mfma_f32_16x16x32_bf16 v[24:27], v[174:177], v[182:185], v[24:27]
	v_mfma_f32_16x16x32_bf16 v[20:23], v[166:169], v[190:193], v[20:23]
	v_mfma_f32_16x16x32_bf16 v[16:19], v[174:177], v[190:193], v[16:19]
	s_barrier
	s_setprio 2
	v_mfma_f32_16x16x32_bf16 v[12:15], v[166:169], v[198:201], v[12:15]
	v_mfma_f32_16x16x32_bf16 v[8:11], v[174:177], v[198:201], v[8:11]
	v_mfma_f32_16x16x32_bf16 v[4:7], v[166:169], v[206:209], v[4:7]
	v_mfma_f32_16x16x32_bf16 v[0:3], v[174:177], v[206:209], v[0:3]
	s_setprio 0
	s_add_i32 s31, 0, 0x18000
	v_add_u32_e32 v148, s31, v214
	s_add_i32 s74, 0, 0x1c000
	ds_read_b128 v[128:131], v148
	ds_read_b128 v[132:135], v148 offset:1024
	ds_read_b128 v[136:139], v148 offset:2048
	ds_read_b128 v[158:161], v148 offset:3072
	v_add_u32_e32 v148, s74, v214
	ds_read_b128 v[162:165], v148
	ds_read_b128 v[166:169], v148 offset:1024
	ds_read_b128 v[170:173], v148 offset:2048
	ds_read_b128 v[174:177], v148 offset:3072
	s_add_u32 s26, s26, 0x80000
	s_addc_u32 s27, s27, 0
	s_mov_b32 m0, s40
	ds_read_b128 v[178:181], v217 offset:32768
	ds_read_b128 v[182:185], v217 offset:33792
	ds_read_b128 v[186:189], v217 offset:34816
	ds_read_b128 v[190:193], v217 offset:35840
	ds_read_b128 v[194:197], v217 offset:36864
	ds_read_b128 v[198:201], v217 offset:37888
	ds_read_b128 v[202:205], v217 offset:38912
	ds_read_b128 v[206:209], v217 offset:39936
	global_load_lds_dwordx4 v140, s[26:27]
	s_mov_b32 m0, s41
	s_nop 0
	global_load_lds_dwordx4 v144, s[26:27]
	s_waitcnt vmcnt(8)
	s_waitcnt lgkmcnt(0)
	s_barrier
	s_setprio 1
	s_waitcnt lgkmcnt(0)
	v_mfma_f32_16x16x32_bf16 v[124:127], v[128:131], v[178:181], v[124:127]
	v_mfma_f32_16x16x32_bf16 v[120:123], v[136:139], v[178:181], v[120:123]
	v_mfma_f32_16x16x32_bf16 v[116:119], v[128:131], v[186:189], v[116:119]
	v_mfma_f32_16x16x32_bf16 v[112:115], v[136:139], v[186:189], v[112:115]
	v_mfma_f32_16x16x32_bf16 v[108:111], v[128:131], v[194:197], v[108:111]
	v_mfma_f32_16x16x32_bf16 v[104:107], v[136:139], v[194:197], v[104:107]
	v_mfma_f32_16x16x32_bf16 v[100:103], v[128:131], v[202:205], v[100:103]
	v_mfma_f32_16x16x32_bf16 v[96:99], v[136:139], v[202:205], v[96:99]
	v_mfma_f32_16x16x32_bf16 v[124:127], v[132:135], v[182:185], v[124:127]
	v_mfma_f32_16x16x32_bf16 v[120:123], v[158:161], v[182:185], v[120:123]
	v_mfma_f32_16x16x32_bf16 v[116:119], v[132:135], v[190:193], v[116:119]
	v_mfma_f32_16x16x32_bf16 v[112:115], v[158:161], v[190:193], v[112:115]
	v_mfma_f32_16x16x32_bf16 v[108:111], v[132:135], v[198:201], v[108:111]
	v_mfma_f32_16x16x32_bf16 v[104:107], v[158:161], v[198:201], v[104:107]
	v_mfma_f32_16x16x32_bf16 v[100:103], v[132:135], v[206:209], v[100:103]
	v_mfma_f32_16x16x32_bf16 v[96:99], v[158:161], v[206:209], v[96:99]
	s_setprio 0
	s_setprio 1
	v_mfma_f32_16x16x32_bf16 v[60:63], v[162:165], v[178:181], v[60:63]
	v_mfma_f32_16x16x32_bf16 v[56:59], v[170:173], v[178:181], v[56:59]
	v_mfma_f32_16x16x32_bf16 v[52:55], v[162:165], v[186:189], v[52:55]
	v_mfma_f32_16x16x32_bf16 v[48:51], v[170:173], v[186:189], v[48:51]
	v_mfma_f32_16x16x32_bf16 v[44:47], v[162:165], v[194:197], v[44:47]
	v_mfma_f32_16x16x32_bf16 v[40:43], v[170:173], v[194:197], v[40:43]
	v_mfma_f32_16x16x32_bf16 v[36:39], v[162:165], v[202:205], v[36:39]
	v_mfma_f32_16x16x32_bf16 v[32:35], v[170:173], v[202:205], v[32:35]
	v_mfma_f32_16x16x32_bf16 v[60:63], v[166:169], v[182:185], v[60:63]
	v_mfma_f32_16x16x32_bf16 v[56:59], v[174:177], v[182:185], v[56:59]
	v_mfma_f32_16x16x32_bf16 v[52:55], v[166:169], v[190:193], v[52:55]
	v_mfma_f32_16x16x32_bf16 v[48:51], v[174:177], v[190:193], v[48:51]
	s_barrier
	s_setprio 2
	v_mfma_f32_16x16x32_bf16 v[44:47], v[166:169], v[198:201], v[44:47]
	v_mfma_f32_16x16x32_bf16 v[40:43], v[174:177], v[198:201], v[40:43]
	v_mfma_f32_16x16x32_bf16 v[36:39], v[166:169], v[206:209], v[36:39]
	v_mfma_f32_16x16x32_bf16 v[32:35], v[174:177], v[206:209], v[32:35]
	s_setprio 0
	s_add_i32 s26, s31, s67
	v_lshl_add_u64 v[210:211], v[210:211], 0, s[6:7]
	s_mov_b32 m0, s26
	ds_read_b128 v[178:181], v217 offset:49152
	ds_read_b128 v[182:185], v217 offset:50176
	ds_read_b128 v[186:189], v217 offset:51200
	ds_read_b128 v[190:193], v217 offset:52224
	ds_read_b128 v[194:197], v217 offset:53248
	ds_read_b128 v[198:201], v217 offset:54272
	ds_read_b128 v[202:205], v217 offset:55296
	ds_read_b128 v[206:209], v217 offset:56320
	global_load_lds_dwordx4 v[210:211], off
	s_add_i32 m0, s26, 0x2000
	s_add_u32 s24, s24, 0x80080
	v_lshl_add_u64 v[210:211], v[212:213], 0, s[6:7]
	s_addc_u32 s25, s25, 0
	s_add_i32 s26, s74, s67
	global_load_lds_dwordx4 v[210:211], off
	s_mov_b32 m0, s26
	s_nop 0
	global_load_lds_dwordx4 v142, s[24:25]
	s_add_i32 m0, s26, 0x2000
	s_nop 0
	global_load_lds_dwordx4 v146, s[24:25]
	v_lshl_add_u64 v[210:211], v[220:221], 0, s[6:7]
	s_mov_b32 m0, s55
	s_nop 0
	global_load_lds_dwordx4 v[210:211], off
	v_lshl_add_u64 v[210:211], v[222:223], 0, s[6:7]
	s_mov_b32 m0, s56
	s_nop 0
	global_load_lds_dwordx4 v[210:211], off
	s_waitcnt vmcnt(8)
	s_waitcnt lgkmcnt(0)
	s_barrier
	s_setprio 1
	s_waitcnt lgkmcnt(0)
	v_mfma_f32_16x16x32_bf16 v[92:95], v[128:131], v[178:181], v[92:95]
	v_mfma_f32_16x16x32_bf16 v[88:91], v[136:139], v[178:181], v[88:91]
	v_mfma_f32_16x16x32_bf16 v[84:87], v[128:131], v[186:189], v[84:87]
	v_mfma_f32_16x16x32_bf16 v[80:83], v[136:139], v[186:189], v[80:83]
	v_mfma_f32_16x16x32_bf16 v[76:79], v[128:131], v[194:197], v[76:79]
	v_mfma_f32_16x16x32_bf16 v[72:75], v[136:139], v[194:197], v[72:75]
	v_mfma_f32_16x16x32_bf16 v[68:71], v[128:131], v[202:205], v[68:71]
	v_mfma_f32_16x16x32_bf16 v[64:67], v[136:139], v[202:205], v[64:67]
	v_mfma_f32_16x16x32_bf16 v[92:95], v[132:135], v[182:185], v[92:95]
	v_mfma_f32_16x16x32_bf16 v[88:91], v[158:161], v[182:185], v[88:91]
	v_mfma_f32_16x16x32_bf16 v[84:87], v[132:135], v[190:193], v[84:87]
	v_mfma_f32_16x16x32_bf16 v[80:83], v[158:161], v[190:193], v[80:83]
	v_mfma_f32_16x16x32_bf16 v[76:79], v[132:135], v[198:201], v[76:79]
	v_mfma_f32_16x16x32_bf16 v[72:75], v[158:161], v[198:201], v[72:75]
	v_mfma_f32_16x16x32_bf16 v[68:71], v[132:135], v[206:209], v[68:71]
	v_mfma_f32_16x16x32_bf16 v[64:67], v[158:161], v[206:209], v[64:67]
	s_setprio 0
	s_setprio 1
	v_mfma_f32_16x16x32_bf16 v[28:31], v[162:165], v[178:181], v[28:31]
	v_mfma_f32_16x16x32_bf16 v[24:27], v[170:173], v[178:181], v[24:27]
	v_mfma_f32_16x16x32_bf16 v[20:23], v[162:165], v[186:189], v[20:23]
	v_mfma_f32_16x16x32_bf16 v[16:19], v[170:173], v[186:189], v[16:19]
	v_mfma_f32_16x16x32_bf16 v[12:15], v[162:165], v[194:197], v[12:15]
	v_mfma_f32_16x16x32_bf16 v[8:11], v[170:173], v[194:197], v[8:11]
	v_mfma_f32_16x16x32_bf16 v[4:7], v[162:165], v[202:205], v[4:7]
	v_mfma_f32_16x16x32_bf16 v[0:3], v[170:173], v[202:205], v[0:3]
	v_mfma_f32_16x16x32_bf16 v[28:31], v[166:169], v[182:185], v[28:31]
	v_mfma_f32_16x16x32_bf16 v[24:27], v[174:177], v[182:185], v[24:27]
	v_mfma_f32_16x16x32_bf16 v[20:23], v[166:169], v[190:193], v[20:23]
	v_mfma_f32_16x16x32_bf16 v[16:19], v[174:177], v[190:193], v[16:19]
	s_barrier
	s_setprio 2
	v_mfma_f32_16x16x32_bf16 v[12:15], v[166:169], v[198:201], v[12:15]
	v_mfma_f32_16x16x32_bf16 v[8:11], v[174:177], v[198:201], v[8:11]
	v_mfma_f32_16x16x32_bf16 v[4:7], v[166:169], v[206:209], v[4:7]
	v_mfma_f32_16x16x32_bf16 v[0:3], v[174:177], v[206:209], v[0:3]
	s_setprio 0
	s_add_i32 s30, s30, 2
	s_add_u32 s28, s28, 0x100
	s_addc_u32 s29, s29, 0
	s_add_u32 s22, s22, 0x100
	s_addc_u32 s23, s23, 0
	s_cmp_gt_u32 s30, 29
	s_cbranch_scc0 .LBB0_1192
	s_and_b64 vcc, exec, s[8:9]
	s_cbranch_vccz .LBB0_1195
	s_barrier

.LBB0_1304:
	ds_read_b128 v[124:127], v163
	ds_read_b128 v[156:159], v163 offset:1024
	ds_read_b128 v[170:173], v163 offset:2048
	ds_read_b128 v[174:177], v163 offset:3072
	ds_read_b128 v[178:181], v165
	ds_read_b128 v[182:185], v165 offset:1024
	ds_read_b128 v[186:189], v165 offset:2048
	ds_read_b128 v[190:193], v165 offset:3072
	s_add_u32 s26, s24, 0xfff80080
	s_addc_u32 s27, s25, -1
	s_cmp_eq_u32 s55, 28
	s_cselect_b32 s29, s17, s27
	s_cselect_b32 s28, s51, s26
	s_cselect_b32 s27, s15, s54
	s_cselect_b32 s26, s52, s53
	s_add_i32 m0, s23, 0xc000
	ds_read_b128 v[194:197], v167
	ds_read_b128 v[198:201], v167 offset:1024
	ds_read_b128 v[202:205], v167 offset:2048
	ds_read_b128 v[206:209], v167 offset:3072
	ds_read_b128 v[210:213], v167 offset:4096
	ds_read_b128 v[214:217], v167 offset:5120
	ds_read_b128 v[218:221], v167 offset:6144
	ds_read_b128 v[222:225], v167 offset:7168
	global_load_lds_dwordx4 v148, s[24:25]
	s_add_i32 m0, s23, 0xe000
	s_nop 0
	global_load_lds_dwordx4 v146, s[24:25]
	s_waitcnt vmcnt(8)
	s_waitcnt lgkmcnt(0)
	s_barrier
	s_setprio 1
	s_waitcnt lgkmcnt(0)
	v_mfma_f32_16x16x32_bf16 v[132:135], v[124:127], v[194:197], v[132:135]
	v_mfma_f32_16x16x32_bf16 v[120:123], v[170:173], v[194:197], v[120:123]
	v_mfma_f32_16x16x32_bf16 v[108:111], v[124:127], v[202:205], v[108:111]
	v_mfma_f32_16x16x32_bf16 v[100:103], v[170:173], v[202:205], v[100:103]
	v_mfma_f32_16x16x32_bf16 v[92:95], v[124:127], v[210:213], v[92:95]
	v_mfma_f32_16x16x32_bf16 v[84:87], v[170:173], v[210:213], v[84:87]
	v_mfma_f32_16x16x32_bf16 v[76:79], v[124:127], v[218:221], v[76:79]
	v_mfma_f32_16x16x32_bf16 v[68:71], v[170:173], v[218:221], v[68:71]
	v_mfma_f32_16x16x32_bf16 v[132:135], v[156:159], v[198:201], v[132:135]
	v_mfma_f32_16x16x32_bf16 v[120:123], v[174:177], v[198:201], v[120:123]
	v_mfma_f32_16x16x32_bf16 v[108:111], v[156:159], v[206:209], v[108:111]
	v_mfma_f32_16x16x32_bf16 v[100:103], v[174:177], v[206:209], v[100:103]
	v_mfma_f32_16x16x32_bf16 v[92:95], v[156:159], v[214:217], v[92:95]
	v_mfma_f32_16x16x32_bf16 v[84:87], v[174:177], v[214:217], v[84:87]
	v_mfma_f32_16x16x32_bf16 v[76:79], v[156:159], v[222:225], v[76:79]
	v_mfma_f32_16x16x32_bf16 v[68:71], v[174:177], v[222:225], v[68:71]
	s_setprio 0
	s_setprio 1
	v_mfma_f32_16x16x32_bf16 v[128:131], v[178:181], v[194:197], v[128:131]
	v_mfma_f32_16x16x32_bf16 v[114:117], v[186:189], v[194:197], v[116:119]
	v_mfma_f32_16x16x32_bf16 v[104:107], v[178:181], v[202:205], v[104:107]
	v_mfma_f32_16x16x32_bf16 v[96:99], v[186:189], v[202:205], v[96:99]
	v_mfma_f32_16x16x32_bf16 v[88:91], v[178:181], v[210:213], v[88:91]
	v_mfma_f32_16x16x32_bf16 v[80:83], v[186:189], v[210:213], v[80:83]
	v_mfma_f32_16x16x32_bf16 v[72:75], v[178:181], v[218:221], v[72:75]
	v_mfma_f32_16x16x32_bf16 v[64:67], v[186:189], v[218:221], v[64:67]
	v_mfma_f32_16x16x32_bf16 v[128:131], v[182:185], v[198:201], v[128:131]
	v_mfma_f32_16x16x32_bf16 v[114:117], v[190:193], v[198:201], v[114:117]
	v_mfma_f32_16x16x32_bf16 v[104:107], v[182:185], v[206:209], v[104:107]
	v_mfma_f32_16x16x32_bf16 v[96:99], v[190:193], v[206:209], v[96:99]
	s_barrier
	s_setprio 2
	v_mfma_f32_16x16x32_bf16 v[88:91], v[182:185], v[214:217], v[88:91]
	v_mfma_f32_16x16x32_bf16 v[80:83], v[190:193], v[214:217], v[80:83]
	v_mfma_f32_16x16x32_bf16 v[72:75], v[182:185], v[222:225], v[72:75]
	v_mfma_f32_16x16x32_bf16 v[64:67], v[190:193], v[222:225], v[64:67]
	s_setprio 0
	s_add_i32 s56, s47, s67
	v_lshl_add_u64 v[226:227], s[26:27], 0, v[138:139]
	s_mov_b32 m0, s56
	ds_read_b128 v[194:197], v167 offset:16384
	ds_read_b128 v[198:201], v167 offset:17408
	ds_read_b128 v[202:205], v167 offset:18432
	ds_read_b128 v[206:209], v167 offset:19456
	ds_read_b128 v[210:213], v167 offset:20480
	ds_read_b128 v[214:217], v167 offset:21504
	ds_read_b128 v[218:221], v167 offset:22528
	ds_read_b128 v[222:225], v167 offset:23552
	global_load_lds_dwordx4 v138, s[26:27]
	s_add_i32 m0, s56, 0x2000
	s_add_u32 s56, s26, 0x80000
	v_lshl_add_u64 v[228:229], s[26:27], 0, v[142:143]
	s_addc_u32 s57, s27, 0
	s_add_i32 s58, s48, s67
	global_load_lds_dwordx4 v142, s[26:27]
	s_mov_b32 m0, s58
	v_lshl_add_u64 v[230:231], s[28:29], 0, v[136:137]
	global_load_lds_dwordx4 v138, s[56:57]
	s_add_i32 m0, s58, 0x2000
	v_lshl_add_u64 v[232:233], s[28:29], 0, v[140:141]
	global_load_lds_dwordx4 v142, s[56:57]
	s_mov_b32 m0, s23
	s_nop 0
	global_load_lds_dwordx4 v136, s[28:29]
	s_mov_b32 m0, s37
	s_nop 0
	global_load_lds_dwordx4 v140, s[28:29]
	s_waitcnt vmcnt(8)
	s_waitcnt lgkmcnt(0)
	s_barrier
	s_setprio 1
	s_waitcnt lgkmcnt(0)
	v_mfma_f32_16x16x32_bf16 v[60:63], v[124:127], v[194:197], v[60:63]
	v_mfma_f32_16x16x32_bf16 v[52:55], v[170:173], v[194:197], v[52:55]
	v_mfma_f32_16x16x32_bf16 v[44:47], v[124:127], v[202:205], v[44:47]
	v_mfma_f32_16x16x32_bf16 v[36:39], v[170:173], v[202:205], v[36:39]
	v_mfma_f32_16x16x32_bf16 v[28:31], v[124:127], v[210:213], v[28:31]
	v_mfma_f32_16x16x32_bf16 v[20:23], v[170:173], v[210:213], v[20:23]
	v_mfma_f32_16x16x32_bf16 v[12:15], v[124:127], v[218:221], v[12:15]
	v_mfma_f32_16x16x32_bf16 v[4:7], v[170:173], v[218:221], v[4:7]
	v_mfma_f32_16x16x32_bf16 v[60:63], v[156:159], v[198:201], v[60:63]
	v_mfma_f32_16x16x32_bf16 v[52:55], v[174:177], v[198:201], v[52:55]
	v_mfma_f32_16x16x32_bf16 v[44:47], v[156:159], v[206:209], v[44:47]
	v_mfma_f32_16x16x32_bf16 v[36:39], v[174:177], v[206:209], v[36:39]
	v_mfma_f32_16x16x32_bf16 v[28:31], v[156:159], v[214:217], v[28:31]
	v_mfma_f32_16x16x32_bf16 v[20:23], v[174:177], v[214:217], v[20:23]
	v_mfma_f32_16x16x32_bf16 v[12:15], v[156:159], v[222:225], v[12:15]
	v_mfma_f32_16x16x32_bf16 v[4:7], v[174:177], v[222:225], v[4:7]
	s_setprio 0
	s_setprio 1
	v_mfma_f32_16x16x32_bf16 v[56:59], v[178:181], v[194:197], v[56:59]
	v_mfma_f32_16x16x32_bf16 v[48:51], v[186:189], v[194:197], v[48:51]
	v_mfma_f32_16x16x32_bf16 v[40:43], v[178:181], v[202:205], v[40:43]
	v_mfma_f32_16x16x32_bf16 v[32:35], v[186:189], v[202:205], v[32:35]
	v_mfma_f32_16x16x32_bf16 v[24:27], v[178:181], v[210:213], v[24:27]
	v_mfma_f32_16x16x32_bf16 v[16:19], v[186:189], v[210:213], v[16:19]
	v_mfma_f32_16x16x32_bf16 v[8:11], v[178:181], v[218:221], v[8:11]
	v_mfma_f32_16x16x32_bf16 v[0:3], v[186:189], v[218:221], v[0:3]
	v_mfma_f32_16x16x32_bf16 v[56:59], v[182:185], v[198:201], v[56:59]
	v_mfma_f32_16x16x32_bf16 v[48:51], v[190:193], v[198:201], v[48:51]
	v_mfma_f32_16x16x32_bf16 v[40:43], v[182:185], v[206:209], v[40:43]
	v_mfma_f32_16x16x32_bf16 v[32:35], v[190:193], v[206:209], v[32:35]
	s_barrier
	s_setprio 2
	v_mfma_f32_16x16x32_bf16 v[24:27], v[182:185], v[214:217], v[24:27]
	v_mfma_f32_16x16x32_bf16 v[16:19], v[190:193], v[214:217], v[16:19]
	v_mfma_f32_16x16x32_bf16 v[8:11], v[182:185], v[222:225], v[8:11]
	v_mfma_f32_16x16x32_bf16 v[0:3], v[190:193], v[222:225], v[0:3]
	s_setprio 0
	s_add_i32 s56, 0, 0x18000
	v_add_u32_e32 v113, s56, v155
	s_add_i32 s57, 0, 0x1c000
	ds_read_b128 v[124:127], v113
	ds_read_b128 v[156:159], v113 offset:1024
	ds_read_b128 v[170:173], v113 offset:2048
	ds_read_b128 v[174:177], v113 offset:3072
	v_add_u32_e32 v113, s57, v155
	ds_read_b128 v[178:181], v113
	ds_read_b128 v[182:185], v113 offset:1024
	ds_read_b128 v[186:189], v113 offset:2048
	ds_read_b128 v[190:193], v113 offset:3072
	s_add_u32 s28, s28, 0x80000
	s_addc_u32 s29, s29, 0
	s_mov_b32 m0, s38
	ds_read_b128 v[194:197], v167 offset:32768
	ds_read_b128 v[198:201], v167 offset:33792
	ds_read_b128 v[202:205], v167 offset:34816
	ds_read_b128 v[206:209], v167 offset:35840
	ds_read_b128 v[210:213], v167 offset:36864
	ds_read_b128 v[214:217], v167 offset:37888
	ds_read_b128 v[218:221], v167 offset:38912
	ds_read_b128 v[222:225], v167 offset:39936
	global_load_lds_dwordx4 v136, s[28:29]
	s_mov_b32 m0, s39
	s_nop 0
	global_load_lds_dwordx4 v140, s[28:29]
	s_waitcnt vmcnt(8)
	s_waitcnt lgkmcnt(0)
	s_barrier
	s_setprio 1
	s_waitcnt lgkmcnt(0)
	v_mfma_f32_16x16x32_bf16 v[132:135], v[124:127], v[194:197], v[132:135]
	v_mfma_f32_16x16x32_bf16 v[118:121], v[170:173], v[194:197], v[120:123]
	v_mfma_f32_16x16x32_bf16 v[108:111], v[124:127], v[202:205], v[108:111]
	v_mfma_f32_16x16x32_bf16 v[100:103], v[170:173], v[202:205], v[100:103]
	v_mfma_f32_16x16x32_bf16 v[92:95], v[124:127], v[210:213], v[92:95]
	v_mfma_f32_16x16x32_bf16 v[84:87], v[170:173], v[210:213], v[84:87]
	v_mfma_f32_16x16x32_bf16 v[76:79], v[124:127], v[218:221], v[76:79]
	v_mfma_f32_16x16x32_bf16 v[68:71], v[170:173], v[218:221], v[68:71]
	v_mfma_f32_16x16x32_bf16 v[132:135], v[156:159], v[198:201], v[132:135]
	v_mfma_f32_16x16x32_bf16 v[120:123], v[174:177], v[198:201], v[118:121]
	v_mfma_f32_16x16x32_bf16 v[108:111], v[156:159], v[206:209], v[108:111]
	v_mfma_f32_16x16x32_bf16 v[100:103], v[174:177], v[206:209], v[100:103]
	v_mfma_f32_16x16x32_bf16 v[92:95], v[156:159], v[214:217], v[92:95]
	v_mfma_f32_16x16x32_bf16 v[84:87], v[174:177], v[214:217], v[84:87]
	v_mfma_f32_16x16x32_bf16 v[76:79], v[156:159], v[222:225], v[76:79]
	v_mfma_f32_16x16x32_bf16 v[68:71], v[174:177], v[222:225], v[68:71]
	s_setprio 0
	s_setprio 1
	v_mfma_f32_16x16x32_bf16 v[128:131], v[178:181], v[194:197], v[128:131]
	v_mfma_f32_16x16x32_bf16 v[114:117], v[186:189], v[194:197], v[114:117]
	v_mfma_f32_16x16x32_bf16 v[104:107], v[178:181], v[202:205], v[104:107]
	v_mfma_f32_16x16x32_bf16 v[96:99], v[186:189], v[202:205], v[96:99]
	v_mfma_f32_16x16x32_bf16 v[88:91], v[178:181], v[210:213], v[88:91]
	v_mfma_f32_16x16x32_bf16 v[80:83], v[186:189], v[210:213], v[80:83]
	v_mfma_f32_16x16x32_bf16 v[72:75], v[178:181], v[218:221], v[72:75]
	v_mfma_f32_16x16x32_bf16 v[64:67], v[186:189], v[218:221], v[64:67]
	v_mfma_f32_16x16x32_bf16 v[128:131], v[182:185], v[198:201], v[128:131]
	v_mfma_f32_16x16x32_bf16 v[116:119], v[190:193], v[198:201], v[114:117]
	v_mfma_f32_16x16x32_bf16 v[104:107], v[182:185], v[206:209], v[104:107]
	v_mfma_f32_16x16x32_bf16 v[96:99], v[190:193], v[206:209], v[96:99]
	s_barrier
	s_setprio 2
	v_mfma_f32_16x16x32_bf16 v[88:91], v[182:185], v[214:217], v[88:91]
	v_mfma_f32_16x16x32_bf16 v[80:83], v[190:193], v[214:217], v[80:83]
	v_mfma_f32_16x16x32_bf16 v[72:75], v[182:185], v[222:225], v[72:75]
	v_mfma_f32_16x16x32_bf16 v[64:67], v[190:193], v[222:225], v[64:67]
	s_setprio 0
	s_add_i32 s28, s56, s67
	v_lshl_add_u64 v[114:115], v[226:227], 0, s[10:11]
	s_mov_b32 m0, s28
	ds_read_b128 v[194:197], v167 offset:49152
	ds_read_b128 v[198:201], v167 offset:50176
	ds_read_b128 v[202:205], v167 offset:51200
	ds_read_b128 v[206:209], v167 offset:52224
	ds_read_b128 v[210:213], v167 offset:53248
	ds_read_b128 v[214:217], v167 offset:54272
	ds_read_b128 v[218:221], v167 offset:55296
	ds_read_b128 v[222:225], v167 offset:56320
	global_load_lds_dwordx4 v[114:115], off
	s_add_i32 m0, s28, 0x2000
	s_add_u32 s26, s26, 0x80080
	v_lshl_add_u64 v[114:115], v[228:229], 0, s[10:11]
	s_addc_u32 s27, s27, 0
	s_add_i32 s28, s57, s67
	global_load_lds_dwordx4 v[114:115], off
	s_mov_b32 m0, s28
	s_nop 0
	global_load_lds_dwordx4 v138, s[26:27]
	s_add_i32 m0, s28, 0x2000
	s_nop 0
	global_load_lds_dwordx4 v142, s[26:27]
	v_lshl_add_u64 v[114:115], v[230:231], 0, s[10:11]
	s_mov_b32 m0, s41
	s_nop 0
	global_load_lds_dwordx4 v[114:115], off
	v_lshl_add_u64 v[114:115], v[232:233], 0, s[10:11]
	s_mov_b32 m0, s42
	s_nop 0
	global_load_lds_dwordx4 v[114:115], off
	s_waitcnt vmcnt(8)
	s_waitcnt lgkmcnt(0)
	s_barrier
	s_setprio 1
	s_waitcnt lgkmcnt(0)
	v_mfma_f32_16x16x32_bf16 v[60:63], v[124:127], v[194:197], v[60:63]
	v_mfma_f32_16x16x32_bf16 v[52:55], v[170:173], v[194:197], v[52:55]
	v_mfma_f32_16x16x32_bf16 v[44:47], v[124:127], v[202:205], v[44:47]
	v_mfma_f32_16x16x32_bf16 v[36:39], v[170:173], v[202:205], v[36:39]
	v_mfma_f32_16x16x32_bf16 v[28:31], v[124:127], v[210:213], v[28:31]
	v_mfma_f32_16x16x32_bf16 v[20:23], v[170:173], v[210:213], v[20:23]
	v_mfma_f32_16x16x32_bf16 v[12:15], v[124:127], v[218:221], v[12:15]
	v_mfma_f32_16x16x32_bf16 v[4:7], v[170:173], v[218:221], v[4:7]
	v_mfma_f32_16x16x32_bf16 v[60:63], v[156:159], v[198:201], v[60:63]
	v_mfma_f32_16x16x32_bf16 v[52:55], v[174:177], v[198:201], v[52:55]
	v_mfma_f32_16x16x32_bf16 v[44:47], v[156:159], v[206:209], v[44:47]
	v_mfma_f32_16x16x32_bf16 v[36:39], v[174:177], v[206:209], v[36:39]
	v_mfma_f32_16x16x32_bf16 v[28:31], v[156:159], v[214:217], v[28:31]
	v_mfma_f32_16x16x32_bf16 v[20:23], v[174:177], v[214:217], v[20:23]
	v_mfma_f32_16x16x32_bf16 v[12:15], v[156:159], v[222:225], v[12:15]
	v_mfma_f32_16x16x32_bf16 v[4:7], v[174:177], v[222:225], v[4:7]
	s_setprio 0
	s_setprio 1
	v_mfma_f32_16x16x32_bf16 v[56:59], v[178:181], v[194:197], v[56:59]
	v_mfma_f32_16x16x32_bf16 v[48:51], v[186:189], v[194:197], v[48:51]
	v_mfma_f32_16x16x32_bf16 v[40:43], v[178:181], v[202:205], v[40:43]
	v_mfma_f32_16x16x32_bf16 v[32:35], v[186:189], v[202:205], v[32:35]
	v_mfma_f32_16x16x32_bf16 v[24:27], v[178:181], v[210:213], v[24:27]
	v_mfma_f32_16x16x32_bf16 v[16:19], v[186:189], v[210:213], v[16:19]
	v_mfma_f32_16x16x32_bf16 v[8:11], v[178:181], v[218:221], v[8:11]
	v_mfma_f32_16x16x32_bf16 v[0:3], v[186:189], v[218:221], v[0:3]
	v_mfma_f32_16x16x32_bf16 v[56:59], v[182:185], v[198:201], v[56:59]
	v_mfma_f32_16x16x32_bf16 v[48:51], v[190:193], v[198:201], v[48:51]
	v_mfma_f32_16x16x32_bf16 v[40:43], v[182:185], v[206:209], v[40:43]
	v_mfma_f32_16x16x32_bf16 v[32:35], v[190:193], v[206:209], v[32:35]
	s_barrier
	s_setprio 2
	v_mfma_f32_16x16x32_bf16 v[24:27], v[182:185], v[214:217], v[24:27]
	v_mfma_f32_16x16x32_bf16 v[16:19], v[190:193], v[214:217], v[16:19]
	v_mfma_f32_16x16x32_bf16 v[8:11], v[182:185], v[222:225], v[8:11]
	v_mfma_f32_16x16x32_bf16 v[0:3], v[190:193], v[222:225], v[0:3]
	s_setprio 0
	s_add_i32 s55, s55, 2
	s_add_u32 s53, s53, 0x100
	s_addc_u32 s54, s54, 0
	s_add_u32 s24, s24, 0x100
	s_addc_u32 s25, s25, 0
	s_cmp_gt_u32 s55, 29
	s_cbranch_scc0 .LBB0_1304
	s_and_b64 vcc, exec, s[12:13]
	s_cbranch_vccz .LBB0_1307
	s_barrier

.LBB0_1412:
	ds_read_b128 v[128:131], v215
	ds_read_b128 v[132:135], v215 offset:1024
	ds_read_b128 v[136:139], v215 offset:2048
	ds_read_b128 v[158:161], v215 offset:3072
	ds_read_b128 v[162:165], v216
	ds_read_b128 v[166:169], v216 offset:1024
	ds_read_b128 v[170:173], v216 offset:2048
	ds_read_b128 v[174:177], v216 offset:3072
	s_add_u32 s18, s16, 0x100
	s_addc_u32 s19, s17, 0
	s_cmpk_eq_i32 s26, 0x54
	s_cselect_b32 s23, s3, s19
	s_cselect_b32 s22, s2, s18
	s_cselect_b32 s21, s15, s25
	s_cselect_b32 s20, s14, s24
	v_lshl_add_u64 v[210:211], s[16:17], 0, v[152:153]
	s_add_i32 m0, s34, 0xc000
	ds_read_b128 v[178:181], v217
	ds_read_b128 v[182:185], v217 offset:1024
	ds_read_b128 v[186:189], v217 offset:2048
	ds_read_b128 v[190:193], v217 offset:3072
	ds_read_b128 v[194:197], v217 offset:4096
	ds_read_b128 v[198:201], v217 offset:5120
	ds_read_b128 v[202:205], v217 offset:6144
	ds_read_b128 v[206:209], v217 offset:7168
	global_load_lds_dwordx4 v[210:211], off
	v_lshl_add_u64 v[210:211], s[16:17], 0, v[150:151]
	s_add_i32 m0, s34, 0xe000
	s_nop 0
	global_load_lds_dwordx4 v[210:211], off
	s_waitcnt vmcnt(8)
	s_waitcnt lgkmcnt(0)
	s_barrier
	s_setprio 1
	s_waitcnt lgkmcnt(0)
	v_mfma_f32_16x16x32_bf16 v[124:127], v[128:131], v[178:181], v[124:127]
	v_mfma_f32_16x16x32_bf16 v[120:123], v[136:139], v[178:181], v[120:123]
	v_mfma_f32_16x16x32_bf16 v[116:119], v[128:131], v[186:189], v[116:119]
	v_mfma_f32_16x16x32_bf16 v[112:115], v[136:139], v[186:189], v[112:115]
	v_mfma_f32_16x16x32_bf16 v[108:111], v[128:131], v[194:197], v[108:111]
	v_mfma_f32_16x16x32_bf16 v[104:107], v[136:139], v[194:197], v[104:107]
	v_mfma_f32_16x16x32_bf16 v[100:103], v[128:131], v[202:205], v[100:103]
	v_mfma_f32_16x16x32_bf16 v[96:99], v[136:139], v[202:205], v[96:99]
	v_mfma_f32_16x16x32_bf16 v[124:127], v[132:135], v[182:185], v[124:127]
	v_mfma_f32_16x16x32_bf16 v[120:123], v[158:161], v[182:185], v[120:123]
	v_mfma_f32_16x16x32_bf16 v[116:119], v[132:135], v[190:193], v[116:119]
	v_mfma_f32_16x16x32_bf16 v[112:115], v[158:161], v[190:193], v[112:115]
	v_mfma_f32_16x16x32_bf16 v[108:111], v[132:135], v[198:201], v[108:111]
	v_mfma_f32_16x16x32_bf16 v[104:107], v[158:161], v[198:201], v[104:107]
	v_mfma_f32_16x16x32_bf16 v[100:103], v[132:135], v[206:209], v[100:103]
	v_mfma_f32_16x16x32_bf16 v[96:99], v[158:161], v[206:209], v[96:99]
	s_setprio 0
	s_setprio 1
	v_mfma_f32_16x16x32_bf16 v[60:63], v[162:165], v[178:181], v[60:63]
	v_mfma_f32_16x16x32_bf16 v[56:59], v[170:173], v[178:181], v[56:59]
	v_mfma_f32_16x16x32_bf16 v[52:55], v[162:165], v[186:189], v[52:55]
	v_mfma_f32_16x16x32_bf16 v[48:51], v[170:173], v[186:189], v[48:51]
	v_mfma_f32_16x16x32_bf16 v[44:47], v[162:165], v[194:197], v[44:47]
	v_mfma_f32_16x16x32_bf16 v[40:43], v[170:173], v[194:197], v[40:43]
	v_mfma_f32_16x16x32_bf16 v[36:39], v[162:165], v[202:205], v[36:39]
	v_mfma_f32_16x16x32_bf16 v[32:35], v[170:173], v[202:205], v[32:35]
	v_mfma_f32_16x16x32_bf16 v[60:63], v[166:169], v[182:185], v[60:63]
	v_mfma_f32_16x16x32_bf16 v[56:59], v[174:177], v[182:185], v[56:59]
	v_mfma_f32_16x16x32_bf16 v[52:55], v[166:169], v[190:193], v[52:55]
	v_mfma_f32_16x16x32_bf16 v[48:51], v[174:177], v[190:193], v[48:51]
	s_barrier
	s_setprio 2
	v_mfma_f32_16x16x32_bf16 v[44:47], v[166:169], v[198:201], v[44:47]
	v_mfma_f32_16x16x32_bf16 v[40:43], v[174:177], v[198:201], v[40:43]
	v_mfma_f32_16x16x32_bf16 v[36:39], v[166:169], v[206:209], v[36:39]
	v_mfma_f32_16x16x32_bf16 v[32:35], v[174:177], v[206:209], v[32:35]
	s_setprio 0
	s_add_i32 s16, s56, s67
	v_lshl_add_u64 v[210:211], s[20:21], 0, v[142:143]
	s_mov_b32 m0, s16
	ds_read_b128 v[178:181], v217 offset:16384
	ds_read_b128 v[182:185], v217 offset:17408
	ds_read_b128 v[186:189], v217 offset:18432
	ds_read_b128 v[190:193], v217 offset:19456
	ds_read_b128 v[194:197], v217 offset:20480
	ds_read_b128 v[198:201], v217 offset:21504
	ds_read_b128 v[202:205], v217 offset:22528
	ds_read_b128 v[206:209], v217 offset:23552
	global_load_lds_dwordx4 v142, s[20:21]
	s_add_i32 m0, s16, 0x2000
	s_add_u32 s16, s20, 0x160000
	v_lshl_add_u64 v[212:213], s[20:21], 0, v[146:147]
	s_addc_u32 s17, s21, 0
	s_add_i32 s27, s57, s67
	global_load_lds_dwordx4 v146, s[20:21]
	s_mov_b32 m0, s27
	v_lshl_add_u64 v[222:223], s[22:23], 0, v[144:145]
	global_load_lds_dwordx4 v142, s[16:17]
	s_add_i32 m0, s27, 0x2000
	s_nop 0
	global_load_lds_dwordx4 v146, s[16:17]
	v_lshl_add_u64 v[220:221], s[22:23], 0, v[140:141]
	s_mov_b32 m0, s34
	s_nop 0
	global_load_lds_dwordx4 v140, s[22:23]
	s_mov_b32 m0, s35
	s_nop 0
	global_load_lds_dwordx4 v144, s[22:23]
	s_waitcnt vmcnt(8)
	s_waitcnt lgkmcnt(0)
	s_barrier
	s_setprio 1
	s_waitcnt lgkmcnt(0)
	v_mfma_f32_16x16x32_bf16 v[92:95], v[128:131], v[178:181], v[92:95]
	v_mfma_f32_16x16x32_bf16 v[88:91], v[136:139], v[178:181], v[88:91]
	v_mfma_f32_16x16x32_bf16 v[84:87], v[128:131], v[186:189], v[84:87]
	v_mfma_f32_16x16x32_bf16 v[80:83], v[136:139], v[186:189], v[80:83]
	v_mfma_f32_16x16x32_bf16 v[76:79], v[128:131], v[194:197], v[76:79]
	v_mfma_f32_16x16x32_bf16 v[72:75], v[136:139], v[194:197], v[72:75]
	v_mfma_f32_16x16x32_bf16 v[68:71], v[128:131], v[202:205], v[68:71]
	v_mfma_f32_16x16x32_bf16 v[64:67], v[136:139], v[202:205], v[64:67]
	v_mfma_f32_16x16x32_bf16 v[92:95], v[132:135], v[182:185], v[92:95]
	v_mfma_f32_16x16x32_bf16 v[88:91], v[158:161], v[182:185], v[88:91]
	v_mfma_f32_16x16x32_bf16 v[84:87], v[132:135], v[190:193], v[84:87]
	v_mfma_f32_16x16x32_bf16 v[80:83], v[158:161], v[190:193], v[80:83]
	v_mfma_f32_16x16x32_bf16 v[76:79], v[132:135], v[198:201], v[76:79]
	v_mfma_f32_16x16x32_bf16 v[72:75], v[158:161], v[198:201], v[72:75]
	v_mfma_f32_16x16x32_bf16 v[68:71], v[132:135], v[206:209], v[68:71]
	v_mfma_f32_16x16x32_bf16 v[64:67], v[158:161], v[206:209], v[64:67]
	s_setprio 0
	s_setprio 1
	v_mfma_f32_16x16x32_bf16 v[28:31], v[162:165], v[178:181], v[28:31]
	v_mfma_f32_16x16x32_bf16 v[24:27], v[170:173], v[178:181], v[24:27]
	v_mfma_f32_16x16x32_bf16 v[20:23], v[162:165], v[186:189], v[20:23]
	v_mfma_f32_16x16x32_bf16 v[16:19], v[170:173], v[186:189], v[16:19]
	v_mfma_f32_16x16x32_bf16 v[12:15], v[162:165], v[194:197], v[12:15]
	v_mfma_f32_16x16x32_bf16 v[8:11], v[170:173], v[194:197], v[8:11]
	v_mfma_f32_16x16x32_bf16 v[4:7], v[162:165], v[202:205], v[4:7]
	v_mfma_f32_16x16x32_bf16 v[0:3], v[170:173], v[202:205], v[0:3]
	v_mfma_f32_16x16x32_bf16 v[28:31], v[166:169], v[182:185], v[28:31]
	v_mfma_f32_16x16x32_bf16 v[24:27], v[174:177], v[182:185], v[24:27]
	v_mfma_f32_16x16x32_bf16 v[20:23], v[166:169], v[190:193], v[20:23]
	v_mfma_f32_16x16x32_bf16 v[16:19], v[174:177], v[190:193], v[16:19]
	s_barrier
	s_setprio 2
	v_mfma_f32_16x16x32_bf16 v[12:15], v[166:169], v[198:201], v[12:15]
	v_mfma_f32_16x16x32_bf16 v[8:11], v[174:177], v[198:201], v[8:11]
	v_mfma_f32_16x16x32_bf16 v[4:7], v[166:169], v[206:209], v[4:7]
	v_mfma_f32_16x16x32_bf16 v[0:3], v[174:177], v[206:209], v[0:3]
	s_setprio 0
	s_add_i32 s27, 0, 0x18000
	v_add_u32_e32 v148, s27, v214
	s_add_i32 s72, 0, 0x1c000
	ds_read_b128 v[128:131], v148
	ds_read_b128 v[132:135], v148 offset:1024
	ds_read_b128 v[136:139], v148 offset:2048
	ds_read_b128 v[158:161], v148 offset:3072
	v_add_u32_e32 v148, s72, v214
	ds_read_b128 v[162:165], v148
	ds_read_b128 v[166:169], v148 offset:1024
	ds_read_b128 v[170:173], v148 offset:2048
	ds_read_b128 v[174:177], v148 offset:3072
	s_add_u32 s16, s22, 0x160000
	s_addc_u32 s17, s23, 0
	s_mov_b32 m0, s36
	ds_read_b128 v[178:181], v217 offset:32768
	ds_read_b128 v[182:185], v217 offset:33792
	ds_read_b128 v[186:189], v217 offset:34816
	ds_read_b128 v[190:193], v217 offset:35840
	ds_read_b128 v[194:197], v217 offset:36864
	ds_read_b128 v[198:201], v217 offset:37888
	ds_read_b128 v[202:205], v217 offset:38912
	ds_read_b128 v[206:209], v217 offset:39936
	global_load_lds_dwordx4 v140, s[16:17]
	s_mov_b32 m0, s37
	s_nop 0
	global_load_lds_dwordx4 v144, s[16:17]
	s_waitcnt vmcnt(8)
	s_waitcnt lgkmcnt(0)
	s_barrier
	s_setprio 1
	s_waitcnt lgkmcnt(0)
	v_mfma_f32_16x16x32_bf16 v[124:127], v[128:131], v[178:181], v[124:127]
	v_mfma_f32_16x16x32_bf16 v[120:123], v[136:139], v[178:181], v[120:123]
	v_mfma_f32_16x16x32_bf16 v[116:119], v[128:131], v[186:189], v[116:119]
	v_mfma_f32_16x16x32_bf16 v[112:115], v[136:139], v[186:189], v[112:115]
	v_mfma_f32_16x16x32_bf16 v[108:111], v[128:131], v[194:197], v[108:111]
	v_mfma_f32_16x16x32_bf16 v[104:107], v[136:139], v[194:197], v[104:107]
	v_mfma_f32_16x16x32_bf16 v[100:103], v[128:131], v[202:205], v[100:103]
	v_mfma_f32_16x16x32_bf16 v[96:99], v[136:139], v[202:205], v[96:99]
	v_mfma_f32_16x16x32_bf16 v[124:127], v[132:135], v[182:185], v[124:127]
	v_mfma_f32_16x16x32_bf16 v[120:123], v[158:161], v[182:185], v[120:123]
	v_mfma_f32_16x16x32_bf16 v[116:119], v[132:135], v[190:193], v[116:119]
	v_mfma_f32_16x16x32_bf16 v[112:115], v[158:161], v[190:193], v[112:115]
	v_mfma_f32_16x16x32_bf16 v[108:111], v[132:135], v[198:201], v[108:111]
	v_mfma_f32_16x16x32_bf16 v[104:107], v[158:161], v[198:201], v[104:107]
	v_mfma_f32_16x16x32_bf16 v[100:103], v[132:135], v[206:209], v[100:103]
	v_mfma_f32_16x16x32_bf16 v[96:99], v[158:161], v[206:209], v[96:99]
	s_setprio 0
	s_setprio 1
	v_mfma_f32_16x16x32_bf16 v[60:63], v[162:165], v[178:181], v[60:63]
	v_mfma_f32_16x16x32_bf16 v[56:59], v[170:173], v[178:181], v[56:59]
	v_mfma_f32_16x16x32_bf16 v[52:55], v[162:165], v[186:189], v[52:55]
	v_mfma_f32_16x16x32_bf16 v[48:51], v[170:173], v[186:189], v[48:51]
	v_mfma_f32_16x16x32_bf16 v[44:47], v[162:165], v[194:197], v[44:47]
	v_mfma_f32_16x16x32_bf16 v[40:43], v[170:173], v[194:197], v[40:43]
	v_mfma_f32_16x16x32_bf16 v[36:39], v[162:165], v[202:205], v[36:39]
	v_mfma_f32_16x16x32_bf16 v[32:35], v[170:173], v[202:205], v[32:35]
	v_mfma_f32_16x16x32_bf16 v[60:63], v[166:169], v[182:185], v[60:63]
	v_mfma_f32_16x16x32_bf16 v[56:59], v[174:177], v[182:185], v[56:59]
	v_mfma_f32_16x16x32_bf16 v[52:55], v[166:169], v[190:193], v[52:55]
	v_mfma_f32_16x16x32_bf16 v[48:51], v[174:177], v[190:193], v[48:51]
	s_barrier
	s_setprio 2
	v_mfma_f32_16x16x32_bf16 v[44:47], v[166:169], v[198:201], v[44:47]
	v_mfma_f32_16x16x32_bf16 v[40:43], v[174:177], v[198:201], v[40:43]
	v_mfma_f32_16x16x32_bf16 v[36:39], v[166:169], v[206:209], v[36:39]
	v_mfma_f32_16x16x32_bf16 v[32:35], v[174:177], v[206:209], v[32:35]
	s_setprio 0
	s_add_i32 s16, s27, s67
	v_lshl_add_u64 v[210:211], v[210:211], 0, s[8:9]
	s_mov_b32 m0, s16
	ds_read_b128 v[178:181], v217 offset:49152
	ds_read_b128 v[182:185], v217 offset:50176
	ds_read_b128 v[186:189], v217 offset:51200
	ds_read_b128 v[190:193], v217 offset:52224
	ds_read_b128 v[194:197], v217 offset:53248
	ds_read_b128 v[198:201], v217 offset:54272
	ds_read_b128 v[202:205], v217 offset:55296
	ds_read_b128 v[206:209], v217 offset:56320
	global_load_lds_dwordx4 v[210:211], off
	s_add_i32 m0, s16, 0x2000
	s_add_u32 s16, s20, 0x160080
	v_lshl_add_u64 v[210:211], v[212:213], 0, s[8:9]
	s_addc_u32 s17, s21, 0
	s_add_i32 s20, s72, s67
	global_load_lds_dwordx4 v[210:211], off
	s_mov_b32 m0, s20
	s_nop 0
	global_load_lds_dwordx4 v142, s[16:17]
	s_add_i32 m0, s20, 0x2000
	s_nop 0
	global_load_lds_dwordx4 v146, s[16:17]
	v_lshl_add_u64 v[210:211], v[220:221], 0, s[8:9]
	s_mov_b32 m0, s51
	s_nop 0
	global_load_lds_dwordx4 v[210:211], off
	v_lshl_add_u64 v[210:211], v[222:223], 0, s[8:9]
	s_mov_b32 m0, s52
	s_nop 0
	global_load_lds_dwordx4 v[210:211], off
	s_waitcnt vmcnt(8)
	s_waitcnt lgkmcnt(0)
	s_barrier
	s_setprio 1
	s_waitcnt lgkmcnt(0)
	v_mfma_f32_16x16x32_bf16 v[92:95], v[128:131], v[178:181], v[92:95]
	v_mfma_f32_16x16x32_bf16 v[88:91], v[136:139], v[178:181], v[88:91]
	v_mfma_f32_16x16x32_bf16 v[84:87], v[128:131], v[186:189], v[84:87]
	v_mfma_f32_16x16x32_bf16 v[80:83], v[136:139], v[186:189], v[80:83]
	v_mfma_f32_16x16x32_bf16 v[76:79], v[128:131], v[194:197], v[76:79]
	v_mfma_f32_16x16x32_bf16 v[72:75], v[136:139], v[194:197], v[72:75]
	v_mfma_f32_16x16x32_bf16 v[68:71], v[128:131], v[202:205], v[68:71]
	v_mfma_f32_16x16x32_bf16 v[64:67], v[136:139], v[202:205], v[64:67]
	v_mfma_f32_16x16x32_bf16 v[92:95], v[132:135], v[182:185], v[92:95]
	v_mfma_f32_16x16x32_bf16 v[88:91], v[158:161], v[182:185], v[88:91]
	v_mfma_f32_16x16x32_bf16 v[84:87], v[132:135], v[190:193], v[84:87]
	v_mfma_f32_16x16x32_bf16 v[80:83], v[158:161], v[190:193], v[80:83]
	v_mfma_f32_16x16x32_bf16 v[76:79], v[132:135], v[198:201], v[76:79]
	v_mfma_f32_16x16x32_bf16 v[72:75], v[158:161], v[198:201], v[72:75]
	v_mfma_f32_16x16x32_bf16 v[68:71], v[132:135], v[206:209], v[68:71]
	v_mfma_f32_16x16x32_bf16 v[64:67], v[158:161], v[206:209], v[64:67]
	s_setprio 0
	s_setprio 1
	v_mfma_f32_16x16x32_bf16 v[28:31], v[162:165], v[178:181], v[28:31]
	v_mfma_f32_16x16x32_bf16 v[24:27], v[170:173], v[178:181], v[24:27]
	v_mfma_f32_16x16x32_bf16 v[20:23], v[162:165], v[186:189], v[20:23]
	v_mfma_f32_16x16x32_bf16 v[16:19], v[170:173], v[186:189], v[16:19]
	v_mfma_f32_16x16x32_bf16 v[12:15], v[162:165], v[194:197], v[12:15]
	v_mfma_f32_16x16x32_bf16 v[8:11], v[170:173], v[194:197], v[8:11]
	v_mfma_f32_16x16x32_bf16 v[4:7], v[162:165], v[202:205], v[4:7]
	v_mfma_f32_16x16x32_bf16 v[0:3], v[170:173], v[202:205], v[0:3]
	v_mfma_f32_16x16x32_bf16 v[28:31], v[166:169], v[182:185], v[28:31]
	v_mfma_f32_16x16x32_bf16 v[24:27], v[174:177], v[182:185], v[24:27]
	v_mfma_f32_16x16x32_bf16 v[20:23], v[166:169], v[190:193], v[20:23]
	v_mfma_f32_16x16x32_bf16 v[16:19], v[174:177], v[190:193], v[16:19]
	s_barrier
	s_setprio 2
	v_mfma_f32_16x16x32_bf16 v[12:15], v[166:169], v[198:201], v[12:15]
	v_mfma_f32_16x16x32_bf16 v[8:11], v[174:177], v[198:201], v[8:11]
	v_mfma_f32_16x16x32_bf16 v[4:7], v[166:169], v[206:209], v[4:7]
	v_mfma_f32_16x16x32_bf16 v[0:3], v[174:177], v[206:209], v[0:3]
	s_setprio 0
	s_add_i32 s26, s26, 2
	s_add_u32 s24, s24, 0x100
	s_addc_u32 s25, s25, 0
	s_cmpk_gt_u32 s26, 0x55
	s_mov_b64 s[16:17], s[18:19]
	s_cbranch_scc0 .LBB0_1412
	s_and_b64 vcc, exec, s[10:11]
	s_cbranch_vccz .LBB0_1415
	s_barrier

.LBB0_1502:
	ds_read_b128 v[130:133], v177
	ds_read_b128 v[134:137], v177 offset:1024
	ds_read_b128 v[138:141], v177 offset:2048
	ds_read_b128 v[142:145], v177 offset:3072
	ds_read_b128 v[146:149], v179
	ds_read_b128 v[184:187], v179 offset:1024
	ds_read_b128 v[188:191], v179 offset:2048
	ds_read_b128 v[192:195], v179 offset:3072
	s_add_u32 s30, s28, 0xfff80080
	s_addc_u32 s31, s29, -1
	s_cmp_eq_u32 s60, 28
	s_cselect_b32 s35, s6, s31
	s_cselect_b32 s34, s21, s30
	s_cselect_b32 s31, s19, s59
	s_cselect_b32 s30, s27, s58
	s_add_i32 m0, s41, 0xc000
	ds_read_b128 v[196:199], v181
	ds_read_b128 v[200:203], v181 offset:1024
	ds_read_b128 v[204:207], v181 offset:2048
	ds_read_b128 v[208:211], v181 offset:3072
	ds_read_b128 v[212:215], v181 offset:4096
	ds_read_b128 v[216:219], v181 offset:5120
	ds_read_b128 v[220:223], v181 offset:6144
	ds_read_b128 v[224:227], v181 offset:7168
	global_load_lds_dwordx4 v166, s[28:29]
	s_add_i32 m0, s41, 0xe000
	s_nop 0
	global_load_lds_dwordx4 v164, s[28:29]
	s_waitcnt vmcnt(8)
	s_waitcnt lgkmcnt(0)
	s_barrier
	s_setprio 1
	s_waitcnt lgkmcnt(0)
	v_mfma_f32_16x16x32_bf16 v[124:127], v[130:133], v[196:199], v[124:127]
	v_mfma_f32_16x16x32_bf16 v[120:123], v[138:141], v[196:199], v[120:123]
	v_mfma_f32_16x16x32_bf16 v[108:111], v[130:133], v[204:207], v[108:111]
	v_mfma_f32_16x16x32_bf16 v[100:103], v[138:141], v[204:207], v[100:103]
	v_mfma_f32_16x16x32_bf16 v[92:95], v[130:133], v[212:215], v[92:95]
	v_mfma_f32_16x16x32_bf16 v[84:87], v[138:141], v[212:215], v[84:87]
	v_mfma_f32_16x16x32_bf16 v[76:79], v[130:133], v[220:223], v[76:79]
	v_mfma_f32_16x16x32_bf16 v[68:71], v[138:141], v[220:223], v[68:71]
	v_mfma_f32_16x16x32_bf16 v[124:127], v[134:137], v[200:203], v[124:127]
	v_mfma_f32_16x16x32_bf16 v[120:123], v[142:145], v[200:203], v[120:123]
	v_mfma_f32_16x16x32_bf16 v[108:111], v[134:137], v[208:211], v[108:111]
	v_mfma_f32_16x16x32_bf16 v[100:103], v[142:145], v[208:211], v[100:103]
	v_mfma_f32_16x16x32_bf16 v[92:95], v[134:137], v[216:219], v[92:95]
	v_mfma_f32_16x16x32_bf16 v[84:87], v[142:145], v[216:219], v[84:87]
	v_mfma_f32_16x16x32_bf16 v[76:79], v[134:137], v[224:227], v[76:79]
	v_mfma_f32_16x16x32_bf16 v[68:71], v[142:145], v[224:227], v[68:71]
	s_setprio 0
	s_setprio 1
	v_mfma_f32_16x16x32_bf16 v[116:119], v[146:149], v[196:199], v[116:119]
	v_mfma_f32_16x16x32_bf16 v[112:115], v[188:191], v[196:199], v[112:115]
	v_mfma_f32_16x16x32_bf16 v[104:107], v[146:149], v[204:207], v[104:107]
	v_mfma_f32_16x16x32_bf16 v[96:99], v[188:191], v[204:207], v[96:99]
	v_mfma_f32_16x16x32_bf16 v[88:91], v[146:149], v[212:215], v[88:91]
	v_mfma_f32_16x16x32_bf16 v[80:83], v[188:191], v[212:215], v[80:83]
	v_mfma_f32_16x16x32_bf16 v[72:75], v[146:149], v[220:223], v[72:75]
	v_mfma_f32_16x16x32_bf16 v[64:67], v[188:191], v[220:223], v[64:67]
	v_mfma_f32_16x16x32_bf16 v[116:119], v[184:187], v[200:203], v[116:119]
	v_mfma_f32_16x16x32_bf16 v[112:115], v[192:195], v[200:203], v[112:115]
	v_mfma_f32_16x16x32_bf16 v[104:107], v[184:187], v[208:211], v[104:107]
	v_mfma_f32_16x16x32_bf16 v[96:99], v[192:195], v[208:211], v[96:99]
	s_barrier
	s_setprio 2
	v_mfma_f32_16x16x32_bf16 v[88:91], v[184:187], v[216:219], v[88:91]
	v_mfma_f32_16x16x32_bf16 v[80:83], v[192:195], v[216:219], v[80:83]
	v_mfma_f32_16x16x32_bf16 v[72:75], v[184:187], v[224:227], v[72:75]
	v_mfma_f32_16x16x32_bf16 v[64:67], v[192:195], v[224:227], v[64:67]
	s_setprio 0
	s_add_i32 s61, s53, s67
	v_lshl_add_u64 v[150:151], s[30:31], 0, v[154:155]
	s_mov_b32 m0, s61
	ds_read_b128 v[196:199], v181 offset:16384
	ds_read_b128 v[200:203], v181 offset:17408
	ds_read_b128 v[204:207], v181 offset:18432
	ds_read_b128 v[208:211], v181 offset:19456
	ds_read_b128 v[212:215], v181 offset:20480
	ds_read_b128 v[216:219], v181 offset:21504
	ds_read_b128 v[220:223], v181 offset:22528
	ds_read_b128 v[224:227], v181 offset:23552
	global_load_lds_dwordx4 v154, s[30:31]
	s_add_i32 m0, s61, 0x2000
	s_add_u32 s62, s30, 0x80000
	v_lshl_add_u64 v[228:229], s[30:31], 0, v[158:159]
	s_addc_u32 s63, s31, 0
	s_add_i32 s61, s54, s67
	global_load_lds_dwordx4 v158, s[30:31]
	s_mov_b32 m0, s61
	v_lshl_add_u64 v[232:233], s[34:35], 0, v[156:157]
	global_load_lds_dwordx4 v154, s[62:63]
	s_add_i32 m0, s61, 0x2000
	s_nop 0
	global_load_lds_dwordx4 v158, s[62:63]
	v_lshl_add_u64 v[230:231], s[34:35], 0, v[152:153]
	s_mov_b32 m0, s41
	s_nop 0
	global_load_lds_dwordx4 v152, s[34:35]
	s_mov_b32 m0, s42
	s_nop 0
	global_load_lds_dwordx4 v156, s[34:35]
	s_waitcnt vmcnt(8)
	s_waitcnt lgkmcnt(0)
	s_barrier
	s_setprio 1
	s_waitcnt lgkmcnt(0)
	v_mfma_f32_16x16x32_bf16 v[60:63], v[130:133], v[196:199], v[60:63]
	v_mfma_f32_16x16x32_bf16 v[52:55], v[138:141], v[196:199], v[52:55]
	v_mfma_f32_16x16x32_bf16 v[44:47], v[130:133], v[204:207], v[44:47]
	v_mfma_f32_16x16x32_bf16 v[36:39], v[138:141], v[204:207], v[36:39]
	v_mfma_f32_16x16x32_bf16 v[28:31], v[130:133], v[212:215], v[28:31]
	v_mfma_f32_16x16x32_bf16 v[20:23], v[138:141], v[212:215], v[20:23]
	v_mfma_f32_16x16x32_bf16 v[12:15], v[130:133], v[220:223], v[12:15]
	v_mfma_f32_16x16x32_bf16 v[4:7], v[138:141], v[220:223], v[4:7]
	v_mfma_f32_16x16x32_bf16 v[60:63], v[134:137], v[200:203], v[60:63]
	v_mfma_f32_16x16x32_bf16 v[52:55], v[142:145], v[200:203], v[52:55]
	v_mfma_f32_16x16x32_bf16 v[44:47], v[134:137], v[208:211], v[44:47]
	v_mfma_f32_16x16x32_bf16 v[36:39], v[142:145], v[208:211], v[36:39]
	v_mfma_f32_16x16x32_bf16 v[28:31], v[134:137], v[216:219], v[28:31]
	v_mfma_f32_16x16x32_bf16 v[20:23], v[142:145], v[216:219], v[20:23]
	v_mfma_f32_16x16x32_bf16 v[12:15], v[134:137], v[224:227], v[12:15]
	v_mfma_f32_16x16x32_bf16 v[4:7], v[142:145], v[224:227], v[4:7]
	s_setprio 0
	s_setprio 1
	v_mfma_f32_16x16x32_bf16 v[56:59], v[146:149], v[196:199], v[56:59]
	v_mfma_f32_16x16x32_bf16 v[48:51], v[188:191], v[196:199], v[48:51]
	v_mfma_f32_16x16x32_bf16 v[40:43], v[146:149], v[204:207], v[40:43]
	v_mfma_f32_16x16x32_bf16 v[32:35], v[188:191], v[204:207], v[32:35]
	v_mfma_f32_16x16x32_bf16 v[24:27], v[146:149], v[212:215], v[24:27]
	v_mfma_f32_16x16x32_bf16 v[16:19], v[188:191], v[212:215], v[16:19]
	v_mfma_f32_16x16x32_bf16 v[8:11], v[146:149], v[220:223], v[8:11]
	v_mfma_f32_16x16x32_bf16 v[0:3], v[188:191], v[220:223], v[0:3]
	v_mfma_f32_16x16x32_bf16 v[56:59], v[184:187], v[200:203], v[56:59]
	v_mfma_f32_16x16x32_bf16 v[48:51], v[192:195], v[200:203], v[48:51]
	v_mfma_f32_16x16x32_bf16 v[40:43], v[184:187], v[208:211], v[40:43]
	v_mfma_f32_16x16x32_bf16 v[32:35], v[192:195], v[208:211], v[32:35]
	s_barrier
	s_setprio 2
	v_mfma_f32_16x16x32_bf16 v[24:27], v[184:187], v[216:219], v[24:27]
	v_mfma_f32_16x16x32_bf16 v[16:19], v[192:195], v[216:219], v[16:19]
	v_mfma_f32_16x16x32_bf16 v[8:11], v[184:187], v[224:227], v[8:11]
	v_mfma_f32_16x16x32_bf16 v[0:3], v[192:195], v[224:227], v[0:3]
	s_setprio 0
	s_add_i32 s61, 0, 0x18000
	v_add_u32_e32 v129, s61, v173
	s_add_i32 s62, 0, 0x1c000
	ds_read_b128 v[130:133], v129
	ds_read_b128 v[134:137], v129 offset:1024
	ds_read_b128 v[138:141], v129 offset:2048
	ds_read_b128 v[142:145], v129 offset:3072
	v_add_u32_e32 v129, s62, v173
	ds_read_b128 v[146:149], v129
	ds_read_b128 v[184:187], v129 offset:1024
	ds_read_b128 v[188:191], v129 offset:2048
	ds_read_b128 v[192:195], v129 offset:3072
	s_add_u32 s34, s34, 0x80000
	s_addc_u32 s35, s35, 0
	s_mov_b32 m0, s43
	ds_read_b128 v[196:199], v181 offset:32768
	ds_read_b128 v[200:203], v181 offset:33792
	ds_read_b128 v[204:207], v181 offset:34816
	ds_read_b128 v[208:211], v181 offset:35840
	ds_read_b128 v[212:215], v181 offset:36864
	ds_read_b128 v[216:219], v181 offset:37888
	ds_read_b128 v[220:223], v181 offset:38912
	ds_read_b128 v[224:227], v181 offset:39936
	global_load_lds_dwordx4 v152, s[34:35]
	s_mov_b32 m0, s44
	s_nop 0
	global_load_lds_dwordx4 v156, s[34:35]
	s_waitcnt vmcnt(8)
	s_waitcnt lgkmcnt(0)
	s_barrier
	s_setprio 1
	s_waitcnt lgkmcnt(0)
	v_mfma_f32_16x16x32_bf16 v[124:127], v[130:133], v[196:199], v[124:127]
	v_mfma_f32_16x16x32_bf16 v[120:123], v[138:141], v[196:199], v[120:123]
	v_mfma_f32_16x16x32_bf16 v[108:111], v[130:133], v[204:207], v[108:111]
	v_mfma_f32_16x16x32_bf16 v[100:103], v[138:141], v[204:207], v[100:103]
	v_mfma_f32_16x16x32_bf16 v[92:95], v[130:133], v[212:215], v[92:95]
	v_mfma_f32_16x16x32_bf16 v[84:87], v[138:141], v[212:215], v[84:87]
	v_mfma_f32_16x16x32_bf16 v[76:79], v[130:133], v[220:223], v[76:79]
	v_mfma_f32_16x16x32_bf16 v[68:71], v[138:141], v[220:223], v[68:71]
	v_mfma_f32_16x16x32_bf16 v[124:127], v[134:137], v[200:203], v[124:127]
	v_mfma_f32_16x16x32_bf16 v[120:123], v[142:145], v[200:203], v[120:123]
	v_mfma_f32_16x16x32_bf16 v[108:111], v[134:137], v[208:211], v[108:111]
	v_mfma_f32_16x16x32_bf16 v[100:103], v[142:145], v[208:211], v[100:103]
	v_mfma_f32_16x16x32_bf16 v[92:95], v[134:137], v[216:219], v[92:95]
	v_mfma_f32_16x16x32_bf16 v[84:87], v[142:145], v[216:219], v[84:87]
	v_mfma_f32_16x16x32_bf16 v[76:79], v[134:137], v[224:227], v[76:79]
	v_mfma_f32_16x16x32_bf16 v[68:71], v[142:145], v[224:227], v[68:71]
	s_setprio 0
	s_setprio 1
	v_mfma_f32_16x16x32_bf16 v[116:119], v[146:149], v[196:199], v[116:119]
	v_mfma_f32_16x16x32_bf16 v[112:115], v[188:191], v[196:199], v[112:115]
	v_mfma_f32_16x16x32_bf16 v[104:107], v[146:149], v[204:207], v[104:107]
	v_mfma_f32_16x16x32_bf16 v[96:99], v[188:191], v[204:207], v[96:99]
	v_mfma_f32_16x16x32_bf16 v[88:91], v[146:149], v[212:215], v[88:91]
	v_mfma_f32_16x16x32_bf16 v[80:83], v[188:191], v[212:215], v[80:83]
	v_mfma_f32_16x16x32_bf16 v[72:75], v[146:149], v[220:223], v[72:75]
	v_mfma_f32_16x16x32_bf16 v[64:67], v[188:191], v[220:223], v[64:67]
	v_mfma_f32_16x16x32_bf16 v[116:119], v[184:187], v[200:203], v[116:119]
	v_mfma_f32_16x16x32_bf16 v[112:115], v[192:195], v[200:203], v[112:115]
	v_mfma_f32_16x16x32_bf16 v[104:107], v[184:187], v[208:211], v[104:107]
	v_mfma_f32_16x16x32_bf16 v[96:99], v[192:195], v[208:211], v[96:99]
	s_barrier
	s_setprio 2
	v_mfma_f32_16x16x32_bf16 v[88:91], v[184:187], v[216:219], v[88:91]
	v_mfma_f32_16x16x32_bf16 v[80:83], v[192:195], v[216:219], v[80:83]
	v_mfma_f32_16x16x32_bf16 v[72:75], v[184:187], v[224:227], v[72:75]
	v_mfma_f32_16x16x32_bf16 v[64:67], v[192:195], v[224:227], v[64:67]
	s_setprio 0
	s_add_i32 s34, s61, s67
	v_lshl_add_u64 v[150:151], v[150:151], 0, s[12:13]
	s_mov_b32 m0, s34
	ds_read_b128 v[196:199], v181 offset:49152
	ds_read_b128 v[200:203], v181 offset:50176
	ds_read_b128 v[204:207], v181 offset:51200
	ds_read_b128 v[208:211], v181 offset:52224
	ds_read_b128 v[212:215], v181 offset:53248
	ds_read_b128 v[216:219], v181 offset:54272
	ds_read_b128 v[220:223], v181 offset:55296
	ds_read_b128 v[224:227], v181 offset:56320
	global_load_lds_dwordx4 v[150:151], off
	s_add_i32 m0, s34, 0x2000
	s_add_u32 s30, s30, 0x80080
	v_lshl_add_u64 v[150:151], v[228:229], 0, s[12:13]
	s_addc_u32 s31, s31, 0
	s_add_i32 s34, s62, s67
	global_load_lds_dwordx4 v[150:151], off
	s_mov_b32 m0, s34
	s_nop 0
	global_load_lds_dwordx4 v154, s[30:31]
	s_add_i32 m0, s34, 0x2000
	s_nop 0
	global_load_lds_dwordx4 v158, s[30:31]
	v_lshl_add_u64 v[150:151], v[230:231], 0, s[12:13]
	s_mov_b32 m0, s47
	s_nop 0
	global_load_lds_dwordx4 v[150:151], off
	v_lshl_add_u64 v[150:151], v[232:233], 0, s[12:13]
	s_mov_b32 m0, s48
	s_nop 0
	global_load_lds_dwordx4 v[150:151], off
	s_waitcnt vmcnt(8)
	s_waitcnt lgkmcnt(0)
	s_barrier
	s_setprio 1
	s_waitcnt lgkmcnt(0)
	v_mfma_f32_16x16x32_bf16 v[60:63], v[130:133], v[196:199], v[60:63]
	v_mfma_f32_16x16x32_bf16 v[52:55], v[138:141], v[196:199], v[52:55]
	v_mfma_f32_16x16x32_bf16 v[44:47], v[130:133], v[204:207], v[44:47]
	v_mfma_f32_16x16x32_bf16 v[36:39], v[138:141], v[204:207], v[36:39]
	v_mfma_f32_16x16x32_bf16 v[28:31], v[130:133], v[212:215], v[28:31]
	v_mfma_f32_16x16x32_bf16 v[20:23], v[138:141], v[212:215], v[20:23]
	v_mfma_f32_16x16x32_bf16 v[12:15], v[130:133], v[220:223], v[12:15]
	v_mfma_f32_16x16x32_bf16 v[4:7], v[138:141], v[220:223], v[4:7]
	v_mfma_f32_16x16x32_bf16 v[60:63], v[134:137], v[200:203], v[60:63]
	v_mfma_f32_16x16x32_bf16 v[52:55], v[142:145], v[200:203], v[52:55]
	v_mfma_f32_16x16x32_bf16 v[44:47], v[134:137], v[208:211], v[44:47]
	v_mfma_f32_16x16x32_bf16 v[36:39], v[142:145], v[208:211], v[36:39]
	v_mfma_f32_16x16x32_bf16 v[28:31], v[134:137], v[216:219], v[28:31]
	v_mfma_f32_16x16x32_bf16 v[20:23], v[142:145], v[216:219], v[20:23]
	v_mfma_f32_16x16x32_bf16 v[12:15], v[134:137], v[224:227], v[12:15]
	v_mfma_f32_16x16x32_bf16 v[4:7], v[142:145], v[224:227], v[4:7]
	s_setprio 0
	s_setprio 1
	v_mfma_f32_16x16x32_bf16 v[56:59], v[146:149], v[196:199], v[56:59]
	v_mfma_f32_16x16x32_bf16 v[48:51], v[188:191], v[196:199], v[48:51]
	v_mfma_f32_16x16x32_bf16 v[40:43], v[146:149], v[204:207], v[40:43]
	v_mfma_f32_16x16x32_bf16 v[32:35], v[188:191], v[204:207], v[32:35]
	v_mfma_f32_16x16x32_bf16 v[24:27], v[146:149], v[212:215], v[24:27]
	v_mfma_f32_16x16x32_bf16 v[16:19], v[188:191], v[212:215], v[16:19]
	v_mfma_f32_16x16x32_bf16 v[8:11], v[146:149], v[220:223], v[8:11]
	v_mfma_f32_16x16x32_bf16 v[0:3], v[188:191], v[220:223], v[0:3]
	v_mfma_f32_16x16x32_bf16 v[56:59], v[184:187], v[200:203], v[56:59]
	v_mfma_f32_16x16x32_bf16 v[48:51], v[192:195], v[200:203], v[48:51]
	v_mfma_f32_16x16x32_bf16 v[40:43], v[184:187], v[208:211], v[40:43]
	v_mfma_f32_16x16x32_bf16 v[32:35], v[192:195], v[208:211], v[32:35]
	s_barrier
	s_setprio 2
	v_mfma_f32_16x16x32_bf16 v[24:27], v[184:187], v[216:219], v[24:27]
	v_mfma_f32_16x16x32_bf16 v[16:19], v[192:195], v[216:219], v[16:19]
	v_mfma_f32_16x16x32_bf16 v[8:11], v[184:187], v[224:227], v[8:11]
	v_mfma_f32_16x16x32_bf16 v[0:3], v[192:195], v[224:227], v[0:3]
	s_setprio 0
	s_add_i32 s60, s60, 2
	s_add_u32 s58, s58, 0x100
	s_addc_u32 s59, s59, 0
	s_add_u32 s28, s28, 0x100
	s_addc_u32 s29, s29, 0
	s_cmp_gt_u32 s60, 29
	s_cbranch_scc0 .LBB0_1502
	s_and_b64 vcc, exec, s[14:15]
	s_cbranch_vccz .LBB0_1505
	s_barrier

.LBB0_1661:
	ds_read_b128 v[128:131], v243
	ds_read_b128 v[132:135], v243 offset:1024
	ds_read_b128 v[136:139], v243 offset:2048
	ds_read_b128 v[140:143], v243 offset:3072
	ds_read_b128 v[144:147], v244
	ds_read_b128 v[148:151], v244 offset:1024
	ds_read_b128 v[152:155], v244 offset:2048
	ds_read_b128 v[156:159], v244 offset:3072
	s_add_u32 s26, s24, 0xfff80080
	s_addc_u32 s27, s25, -1
	s_cmp_eq_u32 s75, 28
	s_cselect_b32 s29, s3, s27
	s_cselect_b32 s28, s5, s26
	s_cselect_b32 s27, s17, s31
	s_cselect_b32 s26, s19, s30
	s_add_i32 m0, s38, 0xc000
	ds_read_b128 v[160:163], v245
	ds_read_b128 v[164:167], v245 offset:1024
	ds_read_b128 v[186:189], v245 offset:2048
	ds_read_b128 v[190:193], v245 offset:3072
	ds_read_b128 v[194:197], v245 offset:4096
	ds_read_b128 v[198:201], v245 offset:5120
	ds_read_b128 v[202:205], v245 offset:6144
	ds_read_b128 v[206:209], v245 offset:7168
	global_load_lds_dwordx4 v180, s[24:25]
	s_add_i32 m0, s38, 0xe000
	s_nop 0
	global_load_lds_dwordx4 v178, s[24:25]
	s_waitcnt vmcnt(8)
	s_waitcnt lgkmcnt(0)
	s_barrier
	s_setprio 1
	s_waitcnt lgkmcnt(0)
	v_mfma_f32_16x16x32_bf16 v[124:127], v[128:131], v[160:163], v[124:127]
	v_mfma_f32_16x16x32_bf16 v[120:123], v[136:139], v[160:163], v[120:123]
	v_mfma_f32_16x16x32_bf16 v[116:119], v[128:131], v[186:189], v[116:119]
	v_mfma_f32_16x16x32_bf16 v[112:115], v[136:139], v[186:189], v[112:115]
	v_mfma_f32_16x16x32_bf16 v[108:111], v[128:131], v[194:197], v[108:111]
	v_mfma_f32_16x16x32_bf16 v[104:107], v[136:139], v[194:197], v[104:107]
	v_mfma_f32_16x16x32_bf16 v[100:103], v[128:131], v[202:205], v[100:103]
	v_mfma_f32_16x16x32_bf16 v[96:99], v[136:139], v[202:205], v[96:99]
	v_mfma_f32_16x16x32_bf16 v[124:127], v[132:135], v[164:167], v[124:127]
	v_mfma_f32_16x16x32_bf16 v[120:123], v[140:143], v[164:167], v[120:123]
	v_mfma_f32_16x16x32_bf16 v[116:119], v[132:135], v[190:193], v[116:119]
	v_mfma_f32_16x16x32_bf16 v[112:115], v[140:143], v[190:193], v[112:115]
	v_mfma_f32_16x16x32_bf16 v[108:111], v[132:135], v[198:201], v[108:111]
	v_mfma_f32_16x16x32_bf16 v[104:107], v[140:143], v[198:201], v[104:107]
	v_mfma_f32_16x16x32_bf16 v[100:103], v[132:135], v[206:209], v[100:103]
	v_mfma_f32_16x16x32_bf16 v[96:99], v[140:143], v[206:209], v[96:99]
	s_setprio 0
	s_setprio 1
	v_mfma_f32_16x16x32_bf16 v[60:63], v[144:147], v[160:163], v[60:63]
	v_mfma_f32_16x16x32_bf16 v[56:59], v[152:155], v[160:163], v[56:59]
	v_mfma_f32_16x16x32_bf16 v[52:55], v[144:147], v[186:189], v[52:55]
	v_mfma_f32_16x16x32_bf16 v[48:51], v[152:155], v[186:189], v[48:51]
	v_mfma_f32_16x16x32_bf16 v[44:47], v[144:147], v[194:197], v[44:47]
	v_mfma_f32_16x16x32_bf16 v[40:43], v[152:155], v[194:197], v[40:43]
	v_mfma_f32_16x16x32_bf16 v[36:39], v[144:147], v[202:205], v[36:39]
	v_mfma_f32_16x16x32_bf16 v[32:35], v[152:155], v[202:205], v[32:35]
	v_mfma_f32_16x16x32_bf16 v[60:63], v[148:151], v[164:167], v[60:63]
	v_mfma_f32_16x16x32_bf16 v[56:59], v[156:159], v[164:167], v[56:59]
	v_mfma_f32_16x16x32_bf16 v[52:55], v[148:151], v[190:193], v[52:55]
	v_mfma_f32_16x16x32_bf16 v[48:51], v[156:159], v[190:193], v[48:51]
	s_barrier
	s_setprio 2
	v_mfma_f32_16x16x32_bf16 v[44:47], v[148:151], v[198:201], v[44:47]
	v_mfma_f32_16x16x32_bf16 v[40:43], v[156:159], v[198:201], v[40:43]
	v_mfma_f32_16x16x32_bf16 v[36:39], v[148:151], v[206:209], v[36:39]
	v_mfma_f32_16x16x32_bf16 v[32:35], v[156:159], v[206:209], v[32:35]
	s_setprio 0
	s_add_i32 s76, s62, s67
	v_lshl_add_u64 v[210:211], s[26:27], 0, v[170:171]
	s_mov_b32 m0, s76
	ds_read_b128 v[160:163], v245 offset:16384
	ds_read_b128 v[164:167], v245 offset:17408
	ds_read_b128 v[186:189], v245 offset:18432
	ds_read_b128 v[190:193], v245 offset:19456
	ds_read_b128 v[194:197], v245 offset:20480
	ds_read_b128 v[198:201], v245 offset:21504
	ds_read_b128 v[202:205], v245 offset:22528
	ds_read_b128 v[206:209], v245 offset:23552
	global_load_lds_dwordx4 v170, s[26:27]
	s_add_i32 m0, s76, 0x2000
	s_add_u32 s76, s26, 0x80000
	v_lshl_add_u64 v[212:213], s[26:27], 0, v[174:175]
	s_addc_u32 s77, s27, 0
	s_add_i32 s78, s63, s67
	global_load_lds_dwordx4 v174, s[26:27]
	s_mov_b32 m0, s78
	v_lshl_add_u64 v[216:217], s[28:29], 0, v[172:173]
	global_load_lds_dwordx4 v170, s[76:77]
	s_add_i32 m0, s78, 0x2000
	s_nop 0
	global_load_lds_dwordx4 v174, s[76:77]
	v_lshl_add_u64 v[214:215], s[28:29], 0, v[168:169]
	s_mov_b32 m0, s38
	s_nop 0
	global_load_lds_dwordx4 v168, s[28:29]
	s_mov_b32 m0, s39
	s_nop 0
	global_load_lds_dwordx4 v172, s[28:29]
	s_waitcnt vmcnt(8)
	s_waitcnt lgkmcnt(0)
	s_barrier
	s_setprio 1
	s_waitcnt lgkmcnt(0)
	v_mfma_f32_16x16x32_bf16 v[92:95], v[128:131], v[160:163], v[92:95]
	v_mfma_f32_16x16x32_bf16 v[88:91], v[136:139], v[160:163], v[88:91]
	v_mfma_f32_16x16x32_bf16 v[84:87], v[128:131], v[186:189], v[84:87]
	v_mfma_f32_16x16x32_bf16 v[80:83], v[136:139], v[186:189], v[80:83]
	v_mfma_f32_16x16x32_bf16 v[76:79], v[128:131], v[194:197], v[76:79]
	v_mfma_f32_16x16x32_bf16 v[72:75], v[136:139], v[194:197], v[72:75]
	v_mfma_f32_16x16x32_bf16 v[68:71], v[128:131], v[202:205], v[68:71]
	v_mfma_f32_16x16x32_bf16 v[64:67], v[136:139], v[202:205], v[64:67]
	v_mfma_f32_16x16x32_bf16 v[92:95], v[132:135], v[164:167], v[92:95]
	v_mfma_f32_16x16x32_bf16 v[88:91], v[140:143], v[164:167], v[88:91]
	v_mfma_f32_16x16x32_bf16 v[84:87], v[132:135], v[190:193], v[84:87]
	v_mfma_f32_16x16x32_bf16 v[80:83], v[140:143], v[190:193], v[80:83]
	v_mfma_f32_16x16x32_bf16 v[76:79], v[132:135], v[198:201], v[76:79]
	v_mfma_f32_16x16x32_bf16 v[72:75], v[140:143], v[198:201], v[72:75]
	v_mfma_f32_16x16x32_bf16 v[68:71], v[132:135], v[206:209], v[68:71]
	v_mfma_f32_16x16x32_bf16 v[64:67], v[140:143], v[206:209], v[64:67]
	s_setprio 0
	s_setprio 1
	v_mfma_f32_16x16x32_bf16 v[28:31], v[144:147], v[160:163], v[28:31]
	v_mfma_f32_16x16x32_bf16 v[24:27], v[152:155], v[160:163], v[24:27]
	v_mfma_f32_16x16x32_bf16 v[20:23], v[144:147], v[186:189], v[20:23]
	v_mfma_f32_16x16x32_bf16 v[16:19], v[152:155], v[186:189], v[16:19]
	v_mfma_f32_16x16x32_bf16 v[12:15], v[144:147], v[194:197], v[12:15]
	v_mfma_f32_16x16x32_bf16 v[8:11], v[152:155], v[194:197], v[8:11]
	v_mfma_f32_16x16x32_bf16 v[4:7], v[144:147], v[202:205], v[4:7]
	v_mfma_f32_16x16x32_bf16 v[0:3], v[152:155], v[202:205], v[0:3]
	v_mfma_f32_16x16x32_bf16 v[28:31], v[148:151], v[164:167], v[28:31]
	v_mfma_f32_16x16x32_bf16 v[24:27], v[156:159], v[164:167], v[24:27]
	v_mfma_f32_16x16x32_bf16 v[20:23], v[148:151], v[190:193], v[20:23]
	v_mfma_f32_16x16x32_bf16 v[16:19], v[156:159], v[190:193], v[16:19]
	s_barrier
	s_setprio 2
	v_mfma_f32_16x16x32_bf16 v[12:15], v[148:151], v[198:201], v[12:15]
	v_mfma_f32_16x16x32_bf16 v[8:11], v[156:159], v[198:201], v[8:11]
	v_mfma_f32_16x16x32_bf16 v[4:7], v[148:151], v[206:209], v[4:7]
	v_mfma_f32_16x16x32_bf16 v[0:3], v[156:159], v[206:209], v[0:3]
	s_setprio 0
	s_add_i32 s76, 0, 0x18000
	s_add_i32 s77, 0, 0x1c000
	v_add_u32_e32 v140, s76, v242
	v_add_u32_e32 v156, s77, v242
	ds_read_b128 v[128:131], v140
	ds_read_b128 v[132:135], v140 offset:1024
	ds_read_b128 v[136:139], v140 offset:2048
	ds_read_b128 v[140:143], v140 offset:3072
	ds_read_b128 v[144:147], v156
	ds_read_b128 v[148:151], v156 offset:1024
	ds_read_b128 v[152:155], v156 offset:2048
	ds_read_b128 v[156:159], v156 offset:3072
	s_add_u32 s28, s28, 0x80000
	s_addc_u32 s29, s29, 0
	s_mov_b32 m0, s40
	ds_read_b128 v[160:163], v245 offset:32768
	ds_read_b128 v[164:167], v245 offset:33792
	ds_read_b128 v[186:189], v245 offset:34816
	ds_read_b128 v[190:193], v245 offset:35840
	ds_read_b128 v[194:197], v245 offset:36864
	ds_read_b128 v[198:201], v245 offset:37888
	ds_read_b128 v[202:205], v245 offset:38912
	ds_read_b128 v[206:209], v245 offset:39936
	global_load_lds_dwordx4 v168, s[28:29]
	s_mov_b32 m0, s41
	s_nop 0
	global_load_lds_dwordx4 v172, s[28:29]
	s_waitcnt vmcnt(8)
	s_waitcnt lgkmcnt(0)
	s_barrier
	s_setprio 1
	s_waitcnt lgkmcnt(0)
	v_mfma_f32_16x16x32_bf16 v[124:127], v[128:131], v[160:163], v[124:127]
	v_mfma_f32_16x16x32_bf16 v[120:123], v[136:139], v[160:163], v[120:123]
	v_mfma_f32_16x16x32_bf16 v[116:119], v[128:131], v[186:189], v[116:119]
	v_mfma_f32_16x16x32_bf16 v[112:115], v[136:139], v[186:189], v[112:115]
	v_mfma_f32_16x16x32_bf16 v[108:111], v[128:131], v[194:197], v[108:111]
	v_mfma_f32_16x16x32_bf16 v[104:107], v[136:139], v[194:197], v[104:107]
	v_mfma_f32_16x16x32_bf16 v[100:103], v[128:131], v[202:205], v[100:103]
	v_mfma_f32_16x16x32_bf16 v[96:99], v[136:139], v[202:205], v[96:99]
	v_mfma_f32_16x16x32_bf16 v[124:127], v[132:135], v[164:167], v[124:127]
	v_mfma_f32_16x16x32_bf16 v[120:123], v[140:143], v[164:167], v[120:123]
	v_mfma_f32_16x16x32_bf16 v[116:119], v[132:135], v[190:193], v[116:119]
	v_mfma_f32_16x16x32_bf16 v[112:115], v[140:143], v[190:193], v[112:115]
	v_mfma_f32_16x16x32_bf16 v[108:111], v[132:135], v[198:201], v[108:111]
	v_mfma_f32_16x16x32_bf16 v[104:107], v[140:143], v[198:201], v[104:107]
	v_mfma_f32_16x16x32_bf16 v[100:103], v[132:135], v[206:209], v[100:103]
	v_mfma_f32_16x16x32_bf16 v[96:99], v[140:143], v[206:209], v[96:99]
	s_setprio 0
	s_setprio 1
	v_mfma_f32_16x16x32_bf16 v[60:63], v[144:147], v[160:163], v[60:63]
	v_mfma_f32_16x16x32_bf16 v[56:59], v[152:155], v[160:163], v[56:59]
	v_mfma_f32_16x16x32_bf16 v[52:55], v[144:147], v[186:189], v[52:55]
	v_mfma_f32_16x16x32_bf16 v[48:51], v[152:155], v[186:189], v[48:51]
	v_mfma_f32_16x16x32_bf16 v[44:47], v[144:147], v[194:197], v[44:47]
	v_mfma_f32_16x16x32_bf16 v[40:43], v[152:155], v[194:197], v[40:43]
	v_mfma_f32_16x16x32_bf16 v[36:39], v[144:147], v[202:205], v[36:39]
	v_mfma_f32_16x16x32_bf16 v[32:35], v[152:155], v[202:205], v[32:35]
	v_mfma_f32_16x16x32_bf16 v[60:63], v[148:151], v[164:167], v[60:63]
	v_mfma_f32_16x16x32_bf16 v[56:59], v[156:159], v[164:167], v[56:59]
	v_mfma_f32_16x16x32_bf16 v[52:55], v[148:151], v[190:193], v[52:55]
	v_mfma_f32_16x16x32_bf16 v[48:51], v[156:159], v[190:193], v[48:51]
	s_barrier
	s_setprio 2
	v_mfma_f32_16x16x32_bf16 v[44:47], v[148:151], v[198:201], v[44:47]
	v_mfma_f32_16x16x32_bf16 v[40:43], v[156:159], v[198:201], v[40:43]
	v_mfma_f32_16x16x32_bf16 v[36:39], v[148:151], v[206:209], v[36:39]
	v_mfma_f32_16x16x32_bf16 v[32:35], v[156:159], v[206:209], v[32:35]
	s_setprio 0
	s_add_i32 s28, s76, s67
	v_lshl_add_u64 v[210:211], v[210:211], 0, s[8:9]
	s_mov_b32 m0, s28
	ds_read_b128 v[160:163], v245 offset:49152
	ds_read_b128 v[164:167], v245 offset:50176
	ds_read_b128 v[186:189], v245 offset:51200
	ds_read_b128 v[190:193], v245 offset:52224
	ds_read_b128 v[194:197], v245 offset:53248
	ds_read_b128 v[198:201], v245 offset:54272
	ds_read_b128 v[202:205], v245 offset:55296
	ds_read_b128 v[206:209], v245 offset:56320
	global_load_lds_dwordx4 v[210:211], off
	s_add_i32 m0, s28, 0x2000
	s_add_u32 s26, s26, 0x80080
	v_lshl_add_u64 v[210:211], v[212:213], 0, s[8:9]
	s_addc_u32 s27, s27, 0
	s_add_i32 s28, s77, s67
	global_load_lds_dwordx4 v[210:211], off
	s_mov_b32 m0, s28
	s_nop 0
	global_load_lds_dwordx4 v170, s[26:27]
	s_add_i32 m0, s28, 0x2000
	s_nop 0
	global_load_lds_dwordx4 v174, s[26:27]
	v_lshl_add_u64 v[210:211], v[214:215], 0, s[8:9]
	s_mov_b32 m0, s55
	s_nop 0
	global_load_lds_dwordx4 v[210:211], off
	v_lshl_add_u64 v[210:211], v[216:217], 0, s[8:9]
	s_mov_b32 m0, s56
	s_nop 0
	global_load_lds_dwordx4 v[210:211], off
	s_waitcnt vmcnt(8)
	s_waitcnt lgkmcnt(0)
	s_barrier
	s_setprio 1
	s_waitcnt lgkmcnt(0)
	v_mfma_f32_16x16x32_bf16 v[92:95], v[128:131], v[160:163], v[92:95]
	v_mfma_f32_16x16x32_bf16 v[88:91], v[136:139], v[160:163], v[88:91]
	v_mfma_f32_16x16x32_bf16 v[84:87], v[128:131], v[186:189], v[84:87]
	v_mfma_f32_16x16x32_bf16 v[80:83], v[136:139], v[186:189], v[80:83]
	v_mfma_f32_16x16x32_bf16 v[76:79], v[128:131], v[194:197], v[76:79]
	v_mfma_f32_16x16x32_bf16 v[72:75], v[136:139], v[194:197], v[72:75]
	v_mfma_f32_16x16x32_bf16 v[68:71], v[128:131], v[202:205], v[68:71]
	v_mfma_f32_16x16x32_bf16 v[64:67], v[136:139], v[202:205], v[64:67]
	v_mfma_f32_16x16x32_bf16 v[92:95], v[132:135], v[164:167], v[92:95]
	v_mfma_f32_16x16x32_bf16 v[88:91], v[140:143], v[164:167], v[88:91]
	v_mfma_f32_16x16x32_bf16 v[84:87], v[132:135], v[190:193], v[84:87]
	v_mfma_f32_16x16x32_bf16 v[80:83], v[140:143], v[190:193], v[80:83]
	v_mfma_f32_16x16x32_bf16 v[76:79], v[132:135], v[198:201], v[76:79]
	v_mfma_f32_16x16x32_bf16 v[72:75], v[140:143], v[198:201], v[72:75]
	v_mfma_f32_16x16x32_bf16 v[68:71], v[132:135], v[206:209], v[68:71]
	v_mfma_f32_16x16x32_bf16 v[64:67], v[140:143], v[206:209], v[64:67]
	s_setprio 0
	s_setprio 1
	v_mfma_f32_16x16x32_bf16 v[28:31], v[144:147], v[160:163], v[28:31]
	v_mfma_f32_16x16x32_bf16 v[24:27], v[152:155], v[160:163], v[24:27]
	v_mfma_f32_16x16x32_bf16 v[20:23], v[144:147], v[186:189], v[20:23]
	v_mfma_f32_16x16x32_bf16 v[16:19], v[152:155], v[186:189], v[16:19]
	v_mfma_f32_16x16x32_bf16 v[12:15], v[144:147], v[194:197], v[12:15]
	v_mfma_f32_16x16x32_bf16 v[8:11], v[152:155], v[194:197], v[8:11]
	v_mfma_f32_16x16x32_bf16 v[4:7], v[144:147], v[202:205], v[4:7]
	v_mfma_f32_16x16x32_bf16 v[0:3], v[152:155], v[202:205], v[0:3]
	v_mfma_f32_16x16x32_bf16 v[28:31], v[148:151], v[164:167], v[28:31]
	v_mfma_f32_16x16x32_bf16 v[24:27], v[156:159], v[164:167], v[24:27]
	v_mfma_f32_16x16x32_bf16 v[20:23], v[148:151], v[190:193], v[20:23]
	v_mfma_f32_16x16x32_bf16 v[16:19], v[156:159], v[190:193], v[16:19]
	s_barrier
	s_setprio 2
	v_mfma_f32_16x16x32_bf16 v[12:15], v[148:151], v[198:201], v[12:15]
	v_mfma_f32_16x16x32_bf16 v[8:11], v[156:159], v[198:201], v[8:11]
	v_mfma_f32_16x16x32_bf16 v[4:7], v[148:151], v[206:209], v[4:7]
	v_mfma_f32_16x16x32_bf16 v[0:3], v[156:159], v[206:209], v[0:3]
	s_setprio 0
	s_add_i32 s75, s75, 2
	s_add_u32 s30, s30, 0x100
	s_addc_u32 s31, s31, 0
	s_add_u32 s24, s24, 0x100
	s_addc_u32 s25, s25, 0
	s_cmp_gt_u32 s75, 29
	s_cbranch_scc0 .LBB0_1661
	s_and_b64 vcc, exec, s[10:11]
	s_cbranch_vccz .LBB0_1664
	s_barrier

.LBB0_1979:
	ds_read_b128 v[130:133], v185
	ds_read_b128 v[134:137], v185 offset:1024
	ds_read_b128 v[138:141], v185 offset:2048
	ds_read_b128 v[142:145], v185 offset:3072
	ds_read_b128 v[146:149], v187
	ds_read_b128 v[150:153], v187 offset:1024
	ds_read_b128 v[154:157], v187 offset:2048
	ds_read_b128 v[192:195], v187 offset:3072
	s_add_u32 s30, s28, 0xfff80080
	s_addc_u32 s31, s29, -1
	s_cmp_eq_u32 s61, 28
	s_cselect_b32 s35, s6, s31
	s_cselect_b32 s34, s21, s30
	s_cselect_b32 s31, s19, s60
	s_cselect_b32 s30, s58, s59
	s_add_i32 m0, s27, 0xc000
	ds_read_b128 v[196:199], v189
	ds_read_b128 v[200:203], v189 offset:1024
	ds_read_b128 v[204:207], v189 offset:2048
	ds_read_b128 v[208:211], v189 offset:3072
	ds_read_b128 v[212:215], v189 offset:4096
	ds_read_b128 v[216:219], v189 offset:5120
	ds_read_b128 v[220:223], v189 offset:6144
	ds_read_b128 v[224:227], v189 offset:7168
	global_load_lds_dwordx4 v174, s[28:29]
	s_add_i32 m0, s27, 0xe000
	s_nop 0
	global_load_lds_dwordx4 v172, s[28:29]
	s_waitcnt vmcnt(8)
	s_waitcnt lgkmcnt(0)
	s_barrier
	s_setprio 1
	s_waitcnt lgkmcnt(0)
	v_mfma_f32_16x16x32_bf16 v[124:127], v[130:133], v[196:199], v[124:127]
	v_mfma_f32_16x16x32_bf16 v[120:123], v[138:141], v[196:199], v[120:123]
	v_mfma_f32_16x16x32_bf16 v[112:115], v[130:133], v[204:207], v[112:115]
	v_mfma_f32_16x16x32_bf16 v[104:107], v[138:141], v[204:207], v[104:107]
	v_mfma_f32_16x16x32_bf16 v[96:99], v[130:133], v[212:215], v[96:99]
	v_mfma_f32_16x16x32_bf16 v[88:91], v[138:141], v[212:215], v[88:91]
	v_mfma_f32_16x16x32_bf16 v[80:83], v[130:133], v[220:223], v[80:83]
	v_mfma_f32_16x16x32_bf16 v[72:75], v[138:141], v[220:223], v[72:75]
	v_mfma_f32_16x16x32_bf16 v[124:127], v[134:137], v[200:203], v[124:127]
	v_mfma_f32_16x16x32_bf16 v[120:123], v[142:145], v[200:203], v[120:123]
	v_mfma_f32_16x16x32_bf16 v[112:115], v[134:137], v[208:211], v[112:115]
	v_mfma_f32_16x16x32_bf16 v[104:107], v[142:145], v[208:211], v[104:107]
	v_mfma_f32_16x16x32_bf16 v[96:99], v[134:137], v[216:219], v[96:99]
	v_mfma_f32_16x16x32_bf16 v[88:91], v[142:145], v[216:219], v[88:91]
	v_mfma_f32_16x16x32_bf16 v[80:83], v[134:137], v[224:227], v[80:83]
	v_mfma_f32_16x16x32_bf16 v[72:75], v[142:145], v[224:227], v[72:75]
	s_setprio 0
	s_setprio 1
	v_mfma_f32_16x16x32_bf16 v[116:119], v[146:149], v[196:199], v[116:119]
	v_mfma_f32_16x16x32_bf16 v[108:111], v[154:157], v[196:199], v[108:111]
	v_mfma_f32_16x16x32_bf16 v[100:103], v[146:149], v[204:207], v[100:103]
	v_mfma_f32_16x16x32_bf16 v[92:95], v[154:157], v[204:207], v[92:95]
	v_mfma_f32_16x16x32_bf16 v[84:87], v[146:149], v[212:215], v[84:87]
	v_mfma_f32_16x16x32_bf16 v[76:79], v[154:157], v[212:215], v[76:79]
	v_mfma_f32_16x16x32_bf16 v[68:71], v[146:149], v[220:223], v[68:71]
	v_mfma_f32_16x16x32_bf16 v[64:67], v[154:157], v[220:223], v[64:67]
	v_mfma_f32_16x16x32_bf16 v[116:119], v[150:153], v[200:203], v[116:119]
	v_mfma_f32_16x16x32_bf16 v[108:111], v[192:195], v[200:203], v[108:111]
	v_mfma_f32_16x16x32_bf16 v[100:103], v[150:153], v[208:211], v[100:103]
	v_mfma_f32_16x16x32_bf16 v[92:95], v[192:195], v[208:211], v[92:95]
	s_barrier
	s_setprio 2
	v_mfma_f32_16x16x32_bf16 v[84:87], v[150:153], v[216:219], v[84:87]
	v_mfma_f32_16x16x32_bf16 v[76:79], v[192:195], v[216:219], v[76:79]
	v_mfma_f32_16x16x32_bf16 v[68:71], v[150:153], v[224:227], v[68:71]
	v_mfma_f32_16x16x32_bf16 v[64:67], v[192:195], v[224:227], v[64:67]
	s_setprio 0
	s_add_i32 s62, s52, s67
	v_lshl_add_u64 v[158:159], s[30:31], 0, v[162:163]
	s_mov_b32 m0, s62
	ds_read_b128 v[196:199], v189 offset:16384
	ds_read_b128 v[200:203], v189 offset:17408
	ds_read_b128 v[204:207], v189 offset:18432
	ds_read_b128 v[208:211], v189 offset:19456
	ds_read_b128 v[212:215], v189 offset:20480
	ds_read_b128 v[216:219], v189 offset:21504
	ds_read_b128 v[220:223], v189 offset:22528
	ds_read_b128 v[224:227], v189 offset:23552
	global_load_lds_dwordx4 v162, s[30:31]
	s_add_i32 m0, s62, 0x2000
	s_add_u32 s62, s30, 0x80000
	v_lshl_add_u64 v[228:229], s[30:31], 0, v[166:167]
	s_addc_u32 s63, s31, 0
	s_add_i32 s64, s53, s67
	global_load_lds_dwordx4 v166, s[30:31]
	s_mov_b32 m0, s64
	v_lshl_add_u64 v[232:233], s[34:35], 0, v[164:165]
	global_load_lds_dwordx4 v162, s[62:63]
	s_add_i32 m0, s64, 0x2000
	s_nop 0
	global_load_lds_dwordx4 v166, s[62:63]
	v_lshl_add_u64 v[230:231], s[34:35], 0, v[160:161]
	s_mov_b32 m0, s27
	s_nop 0
	global_load_lds_dwordx4 v160, s[34:35]
	s_mov_b32 m0, s41
	s_nop 0
	global_load_lds_dwordx4 v164, s[34:35]
	s_waitcnt vmcnt(8)
	s_waitcnt lgkmcnt(0)
	s_barrier
	s_setprio 1
	s_waitcnt lgkmcnt(0)
	v_mfma_f32_16x16x32_bf16 v[60:63], v[130:133], v[196:199], v[60:63]
	v_mfma_f32_16x16x32_bf16 v[56:59], v[138:141], v[196:199], v[56:59]
	v_mfma_f32_16x16x32_bf16 v[48:51], v[130:133], v[204:207], v[48:51]
	v_mfma_f32_16x16x32_bf16 v[40:43], v[138:141], v[204:207], v[40:43]
	v_mfma_f32_16x16x32_bf16 v[32:35], v[130:133], v[212:215], v[32:35]
	v_mfma_f32_16x16x32_bf16 v[24:27], v[138:141], v[212:215], v[24:27]
	v_mfma_f32_16x16x32_bf16 v[16:19], v[130:133], v[220:223], v[16:19]
	v_mfma_f32_16x16x32_bf16 v[8:11], v[138:141], v[220:223], v[8:11]
	v_mfma_f32_16x16x32_bf16 v[60:63], v[134:137], v[200:203], v[60:63]
	v_mfma_f32_16x16x32_bf16 v[56:59], v[142:145], v[200:203], v[56:59]
	v_mfma_f32_16x16x32_bf16 v[48:51], v[134:137], v[208:211], v[48:51]
	v_mfma_f32_16x16x32_bf16 v[40:43], v[142:145], v[208:211], v[40:43]
	v_mfma_f32_16x16x32_bf16 v[32:35], v[134:137], v[216:219], v[32:35]
	v_mfma_f32_16x16x32_bf16 v[24:27], v[142:145], v[216:219], v[24:27]
	v_mfma_f32_16x16x32_bf16 v[16:19], v[134:137], v[224:227], v[16:19]
	v_mfma_f32_16x16x32_bf16 v[8:11], v[142:145], v[224:227], v[8:11]
	s_setprio 0
	s_setprio 1
	v_mfma_f32_16x16x32_bf16 v[52:55], v[146:149], v[196:199], v[52:55]
	v_mfma_f32_16x16x32_bf16 v[44:47], v[154:157], v[196:199], v[44:47]
	v_mfma_f32_16x16x32_bf16 v[36:39], v[146:149], v[204:207], v[36:39]
	v_mfma_f32_16x16x32_bf16 v[28:31], v[154:157], v[204:207], v[28:31]
	v_mfma_f32_16x16x32_bf16 v[20:23], v[146:149], v[212:215], v[20:23]
	v_mfma_f32_16x16x32_bf16 v[12:15], v[154:157], v[212:215], v[12:15]
	v_mfma_f32_16x16x32_bf16 v[4:7], v[146:149], v[220:223], v[4:7]
	v_mfma_f32_16x16x32_bf16 v[0:3], v[154:157], v[220:223], v[0:3]
	v_mfma_f32_16x16x32_bf16 v[52:55], v[150:153], v[200:203], v[52:55]
	v_mfma_f32_16x16x32_bf16 v[44:47], v[192:195], v[200:203], v[44:47]
	v_mfma_f32_16x16x32_bf16 v[36:39], v[150:153], v[208:211], v[36:39]
	v_mfma_f32_16x16x32_bf16 v[28:31], v[192:195], v[208:211], v[28:31]
	s_barrier
	s_setprio 2
	v_mfma_f32_16x16x32_bf16 v[20:23], v[150:153], v[216:219], v[20:23]
	v_mfma_f32_16x16x32_bf16 v[12:15], v[192:195], v[216:219], v[12:15]
	v_mfma_f32_16x16x32_bf16 v[4:7], v[150:153], v[224:227], v[4:7]
	v_mfma_f32_16x16x32_bf16 v[0:3], v[192:195], v[224:227], v[0:3]
	s_setprio 0
	s_add_i32 s62, 0, 0x18000
	v_add_u32_e32 v129, s62, v181
	s_add_i32 s63, 0, 0x1c000
	ds_read_b128 v[130:133], v129
	ds_read_b128 v[134:137], v129 offset:1024
	ds_read_b128 v[138:141], v129 offset:2048
	ds_read_b128 v[142:145], v129 offset:3072
	v_add_u32_e32 v129, s63, v181
	ds_read_b128 v[146:149], v129
	ds_read_b128 v[150:153], v129 offset:1024
	ds_read_b128 v[154:157], v129 offset:2048
	ds_read_b128 v[192:195], v129 offset:3072
	s_add_u32 s34, s34, 0x80000
	s_addc_u32 s35, s35, 0
	s_mov_b32 m0, s42
	ds_read_b128 v[196:199], v189 offset:32768
	ds_read_b128 v[200:203], v189 offset:33792
	ds_read_b128 v[204:207], v189 offset:34816
	ds_read_b128 v[208:211], v189 offset:35840
	ds_read_b128 v[212:215], v189 offset:36864
	ds_read_b128 v[216:219], v189 offset:37888
	ds_read_b128 v[220:223], v189 offset:38912
	ds_read_b128 v[224:227], v189 offset:39936
	global_load_lds_dwordx4 v160, s[34:35]
	s_mov_b32 m0, s43
	s_nop 0
	global_load_lds_dwordx4 v164, s[34:35]
	s_waitcnt vmcnt(8)
	s_waitcnt lgkmcnt(0)
	s_barrier
	s_setprio 1
	s_waitcnt lgkmcnt(0)
	v_mfma_f32_16x16x32_bf16 v[124:127], v[130:133], v[196:199], v[124:127]
	v_mfma_f32_16x16x32_bf16 v[120:123], v[138:141], v[196:199], v[120:123]
	v_mfma_f32_16x16x32_bf16 v[112:115], v[130:133], v[204:207], v[112:115]
	v_mfma_f32_16x16x32_bf16 v[104:107], v[138:141], v[204:207], v[104:107]
	v_mfma_f32_16x16x32_bf16 v[96:99], v[130:133], v[212:215], v[96:99]
	v_mfma_f32_16x16x32_bf16 v[88:91], v[138:141], v[212:215], v[88:91]
	v_mfma_f32_16x16x32_bf16 v[80:83], v[130:133], v[220:223], v[80:83]
	v_mfma_f32_16x16x32_bf16 v[72:75], v[138:141], v[220:223], v[72:75]
	v_mfma_f32_16x16x32_bf16 v[124:127], v[134:137], v[200:203], v[124:127]
	v_mfma_f32_16x16x32_bf16 v[120:123], v[142:145], v[200:203], v[120:123]
	v_mfma_f32_16x16x32_bf16 v[112:115], v[134:137], v[208:211], v[112:115]
	v_mfma_f32_16x16x32_bf16 v[104:107], v[142:145], v[208:211], v[104:107]
	v_mfma_f32_16x16x32_bf16 v[96:99], v[134:137], v[216:219], v[96:99]
	v_mfma_f32_16x16x32_bf16 v[88:91], v[142:145], v[216:219], v[88:91]
	v_mfma_f32_16x16x32_bf16 v[80:83], v[134:137], v[224:227], v[80:83]
	v_mfma_f32_16x16x32_bf16 v[72:75], v[142:145], v[224:227], v[72:75]
	s_setprio 0
	s_setprio 1
	v_mfma_f32_16x16x32_bf16 v[116:119], v[146:149], v[196:199], v[116:119]
	v_mfma_f32_16x16x32_bf16 v[108:111], v[154:157], v[196:199], v[108:111]
	v_mfma_f32_16x16x32_bf16 v[100:103], v[146:149], v[204:207], v[100:103]
	v_mfma_f32_16x16x32_bf16 v[92:95], v[154:157], v[204:207], v[92:95]
	v_mfma_f32_16x16x32_bf16 v[84:87], v[146:149], v[212:215], v[84:87]
	v_mfma_f32_16x16x32_bf16 v[76:79], v[154:157], v[212:215], v[76:79]
	v_mfma_f32_16x16x32_bf16 v[68:71], v[146:149], v[220:223], v[68:71]
	v_mfma_f32_16x16x32_bf16 v[64:67], v[154:157], v[220:223], v[64:67]
	v_mfma_f32_16x16x32_bf16 v[116:119], v[150:153], v[200:203], v[116:119]
	v_mfma_f32_16x16x32_bf16 v[108:111], v[192:195], v[200:203], v[108:111]
	v_mfma_f32_16x16x32_bf16 v[100:103], v[150:153], v[208:211], v[100:103]
	v_mfma_f32_16x16x32_bf16 v[92:95], v[192:195], v[208:211], v[92:95]
	s_barrier
	s_setprio 2
	v_mfma_f32_16x16x32_bf16 v[84:87], v[150:153], v[216:219], v[84:87]
	v_mfma_f32_16x16x32_bf16 v[76:79], v[192:195], v[216:219], v[76:79]
	v_mfma_f32_16x16x32_bf16 v[68:71], v[150:153], v[224:227], v[68:71]
	v_mfma_f32_16x16x32_bf16 v[64:67], v[192:195], v[224:227], v[64:67]
	s_setprio 0
	s_add_i32 s34, s62, s67
	v_lshl_add_u64 v[158:159], v[158:159], 0, s[12:13]
	s_mov_b32 m0, s34
	ds_read_b128 v[196:199], v189 offset:49152
	ds_read_b128 v[200:203], v189 offset:50176
	ds_read_b128 v[204:207], v189 offset:51200
	ds_read_b128 v[208:211], v189 offset:52224
	ds_read_b128 v[212:215], v189 offset:53248
	ds_read_b128 v[216:219], v189 offset:54272
	ds_read_b128 v[220:223], v189 offset:55296
	ds_read_b128 v[224:227], v189 offset:56320
	global_load_lds_dwordx4 v[158:159], off
	s_add_i32 m0, s34, 0x2000
	s_add_u32 s30, s30, 0x80080
	v_lshl_add_u64 v[158:159], v[228:229], 0, s[12:13]
	s_addc_u32 s31, s31, 0
	s_add_i32 s34, s63, s67
	global_load_lds_dwordx4 v[158:159], off
	s_mov_b32 m0, s34
	s_nop 0
	global_load_lds_dwordx4 v162, s[30:31]
	s_add_i32 m0, s34, 0x2000
	s_nop 0
	global_load_lds_dwordx4 v166, s[30:31]
	v_lshl_add_u64 v[158:159], v[230:231], 0, s[12:13]
	s_mov_b32 m0, s44
	s_nop 0
	global_load_lds_dwordx4 v[158:159], off
	v_lshl_add_u64 v[158:159], v[232:233], 0, s[12:13]
	s_mov_b32 m0, s45
	s_nop 0
	global_load_lds_dwordx4 v[158:159], off
	s_waitcnt vmcnt(8)
	s_waitcnt lgkmcnt(0)
	s_barrier
	s_setprio 1
	s_waitcnt lgkmcnt(0)
	v_mfma_f32_16x16x32_bf16 v[60:63], v[130:133], v[196:199], v[60:63]
	v_mfma_f32_16x16x32_bf16 v[56:59], v[138:141], v[196:199], v[56:59]
	v_mfma_f32_16x16x32_bf16 v[48:51], v[130:133], v[204:207], v[48:51]
	v_mfma_f32_16x16x32_bf16 v[40:43], v[138:141], v[204:207], v[40:43]
	v_mfma_f32_16x16x32_bf16 v[32:35], v[130:133], v[212:215], v[32:35]
	v_mfma_f32_16x16x32_bf16 v[24:27], v[138:141], v[212:215], v[24:27]
	v_mfma_f32_16x16x32_bf16 v[16:19], v[130:133], v[220:223], v[16:19]
	v_mfma_f32_16x16x32_bf16 v[8:11], v[138:141], v[220:223], v[8:11]
	v_mfma_f32_16x16x32_bf16 v[60:63], v[134:137], v[200:203], v[60:63]
	v_mfma_f32_16x16x32_bf16 v[56:59], v[142:145], v[200:203], v[56:59]
	v_mfma_f32_16x16x32_bf16 v[48:51], v[134:137], v[208:211], v[48:51]
	v_mfma_f32_16x16x32_bf16 v[40:43], v[142:145], v[208:211], v[40:43]
	v_mfma_f32_16x16x32_bf16 v[32:35], v[134:137], v[216:219], v[32:35]
	v_mfma_f32_16x16x32_bf16 v[24:27], v[142:145], v[216:219], v[24:27]
	v_mfma_f32_16x16x32_bf16 v[16:19], v[134:137], v[224:227], v[16:19]
	v_mfma_f32_16x16x32_bf16 v[8:11], v[142:145], v[224:227], v[8:11]
	s_setprio 0
	s_setprio 1
	v_mfma_f32_16x16x32_bf16 v[52:55], v[146:149], v[196:199], v[52:55]
	v_mfma_f32_16x16x32_bf16 v[44:47], v[154:157], v[196:199], v[44:47]
	v_mfma_f32_16x16x32_bf16 v[36:39], v[146:149], v[204:207], v[36:39]
	v_mfma_f32_16x16x32_bf16 v[28:31], v[154:157], v[204:207], v[28:31]
	v_mfma_f32_16x16x32_bf16 v[20:23], v[146:149], v[212:215], v[20:23]
	v_mfma_f32_16x16x32_bf16 v[12:15], v[154:157], v[212:215], v[12:15]
	v_mfma_f32_16x16x32_bf16 v[4:7], v[146:149], v[220:223], v[4:7]
	v_mfma_f32_16x16x32_bf16 v[0:3], v[154:157], v[220:223], v[0:3]
	v_mfma_f32_16x16x32_bf16 v[52:55], v[150:153], v[200:203], v[52:55]
	v_mfma_f32_16x16x32_bf16 v[44:47], v[192:195], v[200:203], v[44:47]
	v_mfma_f32_16x16x32_bf16 v[36:39], v[150:153], v[208:211], v[36:39]
	v_mfma_f32_16x16x32_bf16 v[28:31], v[192:195], v[208:211], v[28:31]
	s_barrier
	s_setprio 2
	v_mfma_f32_16x16x32_bf16 v[20:23], v[150:153], v[216:219], v[20:23]
	v_mfma_f32_16x16x32_bf16 v[12:15], v[192:195], v[216:219], v[12:15]
	v_mfma_f32_16x16x32_bf16 v[4:7], v[150:153], v[224:227], v[4:7]
	v_mfma_f32_16x16x32_bf16 v[0:3], v[192:195], v[224:227], v[0:3]
	s_setprio 0
	s_add_i32 s61, s61, 2
	s_add_u32 s59, s59, 0x100
	s_addc_u32 s60, s60, 0
	s_add_u32 s28, s28, 0x100
	s_addc_u32 s29, s29, 0
	s_cmp_gt_u32 s61, 29
	s_cbranch_scc0 .LBB0_1979
	s_and_b64 vcc, exec, s[14:15]
	s_cbranch_vccz .LBB0_1982
	s_barrier

.LBB0_2924:
	ds_read_b128 v[124:127], v163
	ds_read_b128 v[156:159], v163 offset:1024
	ds_read_b128 v[170:173], v163 offset:2048
	ds_read_b128 v[174:177], v163 offset:3072
	ds_read_b128 v[178:181], v165
	ds_read_b128 v[182:185], v165 offset:1024
	ds_read_b128 v[186:189], v165 offset:2048
	ds_read_b128 v[190:193], v165 offset:3072
	s_add_u32 s26, s24, 0xfff80080
	s_addc_u32 s27, s25, -1
	s_cmp_eq_u32 s56, 28
	s_cselect_b32 s29, s17, s27
	s_cselect_b32 s28, s52, s26
	s_cselect_b32 s27, s15, s55
	s_cselect_b32 s26, s53, s54
	s_add_i32 m0, s23, 0xc000
	ds_read_b128 v[194:197], v167
	ds_read_b128 v[198:201], v167 offset:1024
	ds_read_b128 v[202:205], v167 offset:2048
	ds_read_b128 v[206:209], v167 offset:3072
	ds_read_b128 v[210:213], v167 offset:4096
	ds_read_b128 v[214:217], v167 offset:5120
	ds_read_b128 v[218:221], v167 offset:6144
	ds_read_b128 v[222:225], v167 offset:7168
	global_load_lds_dwordx4 v148, s[24:25]
	s_add_i32 m0, s23, 0xe000
	s_nop 0
	global_load_lds_dwordx4 v146, s[24:25]
	s_waitcnt vmcnt(8)
	s_waitcnt lgkmcnt(0)
	s_barrier
	s_setprio 1
	s_waitcnt lgkmcnt(0)
	v_mfma_f32_16x16x32_bf16 v[132:135], v[124:127], v[194:197], v[132:135]
	v_mfma_f32_16x16x32_bf16 v[120:123], v[170:173], v[194:197], v[120:123]
	v_mfma_f32_16x16x32_bf16 v[108:111], v[124:127], v[202:205], v[108:111]
	v_mfma_f32_16x16x32_bf16 v[100:103], v[170:173], v[202:205], v[100:103]
	v_mfma_f32_16x16x32_bf16 v[92:95], v[124:127], v[210:213], v[92:95]
	v_mfma_f32_16x16x32_bf16 v[84:87], v[170:173], v[210:213], v[84:87]
	v_mfma_f32_16x16x32_bf16 v[76:79], v[124:127], v[218:221], v[76:79]
	v_mfma_f32_16x16x32_bf16 v[68:71], v[170:173], v[218:221], v[68:71]
	v_mfma_f32_16x16x32_bf16 v[132:135], v[156:159], v[198:201], v[132:135]
	v_mfma_f32_16x16x32_bf16 v[120:123], v[174:177], v[198:201], v[120:123]
	v_mfma_f32_16x16x32_bf16 v[108:111], v[156:159], v[206:209], v[108:111]
	v_mfma_f32_16x16x32_bf16 v[100:103], v[174:177], v[206:209], v[100:103]
	v_mfma_f32_16x16x32_bf16 v[92:95], v[156:159], v[214:217], v[92:95]
	v_mfma_f32_16x16x32_bf16 v[84:87], v[174:177], v[214:217], v[84:87]
	v_mfma_f32_16x16x32_bf16 v[76:79], v[156:159], v[222:225], v[76:79]
	v_mfma_f32_16x16x32_bf16 v[68:71], v[174:177], v[222:225], v[68:71]
	s_setprio 0
	s_setprio 1
	v_mfma_f32_16x16x32_bf16 v[128:131], v[178:181], v[194:197], v[128:131]
	v_mfma_f32_16x16x32_bf16 v[114:117], v[186:189], v[194:197], v[116:119]
	v_mfma_f32_16x16x32_bf16 v[104:107], v[178:181], v[202:205], v[104:107]
	v_mfma_f32_16x16x32_bf16 v[96:99], v[186:189], v[202:205], v[96:99]
	v_mfma_f32_16x16x32_bf16 v[88:91], v[178:181], v[210:213], v[88:91]
	v_mfma_f32_16x16x32_bf16 v[80:83], v[186:189], v[210:213], v[80:83]
	v_mfma_f32_16x16x32_bf16 v[72:75], v[178:181], v[218:221], v[72:75]
	v_mfma_f32_16x16x32_bf16 v[64:67], v[186:189], v[218:221], v[64:67]
	v_mfma_f32_16x16x32_bf16 v[128:131], v[182:185], v[198:201], v[128:131]
	v_mfma_f32_16x16x32_bf16 v[114:117], v[190:193], v[198:201], v[114:117]
	v_mfma_f32_16x16x32_bf16 v[104:107], v[182:185], v[206:209], v[104:107]
	v_mfma_f32_16x16x32_bf16 v[96:99], v[190:193], v[206:209], v[96:99]
	s_barrier
	s_setprio 2
	v_mfma_f32_16x16x32_bf16 v[88:91], v[182:185], v[214:217], v[88:91]
	v_mfma_f32_16x16x32_bf16 v[80:83], v[190:193], v[214:217], v[80:83]
	v_mfma_f32_16x16x32_bf16 v[72:75], v[182:185], v[222:225], v[72:75]
	v_mfma_f32_16x16x32_bf16 v[64:67], v[190:193], v[222:225], v[64:67]
	s_setprio 0
	s_add_i32 s57, s48, s67
	v_lshl_add_u64 v[226:227], s[26:27], 0, v[138:139]
	s_mov_b32 m0, s57
	ds_read_b128 v[194:197], v167 offset:16384
	ds_read_b128 v[198:201], v167 offset:17408
	ds_read_b128 v[202:205], v167 offset:18432
	ds_read_b128 v[206:209], v167 offset:19456
	ds_read_b128 v[210:213], v167 offset:20480
	ds_read_b128 v[214:217], v167 offset:21504
	ds_read_b128 v[218:221], v167 offset:22528
	ds_read_b128 v[222:225], v167 offset:23552
	global_load_lds_dwordx4 v138, s[26:27]
	s_add_i32 m0, s57, 0x2000
	s_add_u32 s58, s26, 0x80000
	v_lshl_add_u64 v[228:229], s[26:27], 0, v[142:143]
	s_addc_u32 s59, s27, 0
	s_add_i32 s57, s49, s67
	global_load_lds_dwordx4 v142, s[26:27]
	s_mov_b32 m0, s57
	v_lshl_add_u64 v[230:231], s[28:29], 0, v[136:137]
	global_load_lds_dwordx4 v138, s[58:59]
	s_add_i32 m0, s57, 0x2000
	v_lshl_add_u64 v[232:233], s[28:29], 0, v[140:141]
	global_load_lds_dwordx4 v142, s[58:59]
	s_mov_b32 m0, s23
	s_nop 0
	global_load_lds_dwordx4 v136, s[28:29]
	s_mov_b32 m0, s37
	s_nop 0
	global_load_lds_dwordx4 v140, s[28:29]
	s_waitcnt vmcnt(8)
	s_waitcnt lgkmcnt(0)
	s_barrier
	s_setprio 1
	s_waitcnt lgkmcnt(0)
	v_mfma_f32_16x16x32_bf16 v[60:63], v[124:127], v[194:197], v[60:63]
	v_mfma_f32_16x16x32_bf16 v[52:55], v[170:173], v[194:197], v[52:55]
	v_mfma_f32_16x16x32_bf16 v[44:47], v[124:127], v[202:205], v[44:47]
	v_mfma_f32_16x16x32_bf16 v[36:39], v[170:173], v[202:205], v[36:39]
	v_mfma_f32_16x16x32_bf16 v[28:31], v[124:127], v[210:213], v[28:31]
	v_mfma_f32_16x16x32_bf16 v[20:23], v[170:173], v[210:213], v[20:23]
	v_mfma_f32_16x16x32_bf16 v[12:15], v[124:127], v[218:221], v[12:15]
	v_mfma_f32_16x16x32_bf16 v[4:7], v[170:173], v[218:221], v[4:7]
	v_mfma_f32_16x16x32_bf16 v[60:63], v[156:159], v[198:201], v[60:63]
	v_mfma_f32_16x16x32_bf16 v[52:55], v[174:177], v[198:201], v[52:55]
	v_mfma_f32_16x16x32_bf16 v[44:47], v[156:159], v[206:209], v[44:47]
	v_mfma_f32_16x16x32_bf16 v[36:39], v[174:177], v[206:209], v[36:39]
	v_mfma_f32_16x16x32_bf16 v[28:31], v[156:159], v[214:217], v[28:31]
	v_mfma_f32_16x16x32_bf16 v[20:23], v[174:177], v[214:217], v[20:23]
	v_mfma_f32_16x16x32_bf16 v[12:15], v[156:159], v[222:225], v[12:15]
	v_mfma_f32_16x16x32_bf16 v[4:7], v[174:177], v[222:225], v[4:7]
	s_setprio 0
	s_setprio 1
	v_mfma_f32_16x16x32_bf16 v[56:59], v[178:181], v[194:197], v[56:59]
	v_mfma_f32_16x16x32_bf16 v[48:51], v[186:189], v[194:197], v[48:51]
	v_mfma_f32_16x16x32_bf16 v[40:43], v[178:181], v[202:205], v[40:43]
	v_mfma_f32_16x16x32_bf16 v[32:35], v[186:189], v[202:205], v[32:35]
	v_mfma_f32_16x16x32_bf16 v[24:27], v[178:181], v[210:213], v[24:27]
	v_mfma_f32_16x16x32_bf16 v[16:19], v[186:189], v[210:213], v[16:19]
	v_mfma_f32_16x16x32_bf16 v[8:11], v[178:181], v[218:221], v[8:11]
	v_mfma_f32_16x16x32_bf16 v[0:3], v[186:189], v[218:221], v[0:3]
	v_mfma_f32_16x16x32_bf16 v[56:59], v[182:185], v[198:201], v[56:59]
	v_mfma_f32_16x16x32_bf16 v[48:51], v[190:193], v[198:201], v[48:51]
	v_mfma_f32_16x16x32_bf16 v[40:43], v[182:185], v[206:209], v[40:43]
	v_mfma_f32_16x16x32_bf16 v[32:35], v[190:193], v[206:209], v[32:35]
	s_barrier
	s_setprio 2
	v_mfma_f32_16x16x32_bf16 v[24:27], v[182:185], v[214:217], v[24:27]
	v_mfma_f32_16x16x32_bf16 v[16:19], v[190:193], v[214:217], v[16:19]
	v_mfma_f32_16x16x32_bf16 v[8:11], v[182:185], v[222:225], v[8:11]
	v_mfma_f32_16x16x32_bf16 v[0:3], v[190:193], v[222:225], v[0:3]
	s_setprio 0
	s_add_i32 s57, 0, 0x18000
	v_add_u32_e32 v113, s57, v155
	s_add_i32 s58, 0, 0x1c000
	ds_read_b128 v[124:127], v113
	ds_read_b128 v[156:159], v113 offset:1024
	ds_read_b128 v[170:173], v113 offset:2048
	ds_read_b128 v[174:177], v113 offset:3072
	v_add_u32_e32 v113, s58, v155
	ds_read_b128 v[178:181], v113
	ds_read_b128 v[182:185], v113 offset:1024
	ds_read_b128 v[186:189], v113 offset:2048
	ds_read_b128 v[190:193], v113 offset:3072
	s_add_u32 s28, s28, 0x80000
	s_addc_u32 s29, s29, 0
	s_mov_b32 m0, s38
	ds_read_b128 v[194:197], v167 offset:32768
	ds_read_b128 v[198:201], v167 offset:33792
	ds_read_b128 v[202:205], v167 offset:34816
	ds_read_b128 v[206:209], v167 offset:35840
	ds_read_b128 v[210:213], v167 offset:36864
	ds_read_b128 v[214:217], v167 offset:37888
	ds_read_b128 v[218:221], v167 offset:38912
	ds_read_b128 v[222:225], v167 offset:39936
	global_load_lds_dwordx4 v136, s[28:29]
	s_mov_b32 m0, s39
	s_nop 0
	global_load_lds_dwordx4 v140, s[28:29]
	s_waitcnt vmcnt(8)
	s_waitcnt lgkmcnt(0)
	s_barrier
	s_setprio 1
	s_waitcnt lgkmcnt(0)
	v_mfma_f32_16x16x32_bf16 v[132:135], v[124:127], v[194:197], v[132:135]
	v_mfma_f32_16x16x32_bf16 v[118:121], v[170:173], v[194:197], v[120:123]
	v_mfma_f32_16x16x32_bf16 v[108:111], v[124:127], v[202:205], v[108:111]
	v_mfma_f32_16x16x32_bf16 v[100:103], v[170:173], v[202:205], v[100:103]
	v_mfma_f32_16x16x32_bf16 v[92:95], v[124:127], v[210:213], v[92:95]
	v_mfma_f32_16x16x32_bf16 v[84:87], v[170:173], v[210:213], v[84:87]
	v_mfma_f32_16x16x32_bf16 v[76:79], v[124:127], v[218:221], v[76:79]
	v_mfma_f32_16x16x32_bf16 v[68:71], v[170:173], v[218:221], v[68:71]
	v_mfma_f32_16x16x32_bf16 v[132:135], v[156:159], v[198:201], v[132:135]
	v_mfma_f32_16x16x32_bf16 v[120:123], v[174:177], v[198:201], v[118:121]
	v_mfma_f32_16x16x32_bf16 v[108:111], v[156:159], v[206:209], v[108:111]
	v_mfma_f32_16x16x32_bf16 v[100:103], v[174:177], v[206:209], v[100:103]
	v_mfma_f32_16x16x32_bf16 v[92:95], v[156:159], v[214:217], v[92:95]
	v_mfma_f32_16x16x32_bf16 v[84:87], v[174:177], v[214:217], v[84:87]
	v_mfma_f32_16x16x32_bf16 v[76:79], v[156:159], v[222:225], v[76:79]
	v_mfma_f32_16x16x32_bf16 v[68:71], v[174:177], v[222:225], v[68:71]
	s_setprio 0
	s_setprio 1
	v_mfma_f32_16x16x32_bf16 v[128:131], v[178:181], v[194:197], v[128:131]
	v_mfma_f32_16x16x32_bf16 v[114:117], v[186:189], v[194:197], v[114:117]
	v_mfma_f32_16x16x32_bf16 v[104:107], v[178:181], v[202:205], v[104:107]
	v_mfma_f32_16x16x32_bf16 v[96:99], v[186:189], v[202:205], v[96:99]
	v_mfma_f32_16x16x32_bf16 v[88:91], v[178:181], v[210:213], v[88:91]
	v_mfma_f32_16x16x32_bf16 v[80:83], v[186:189], v[210:213], v[80:83]
	v_mfma_f32_16x16x32_bf16 v[72:75], v[178:181], v[218:221], v[72:75]
	v_mfma_f32_16x16x32_bf16 v[64:67], v[186:189], v[218:221], v[64:67]
	v_mfma_f32_16x16x32_bf16 v[128:131], v[182:185], v[198:201], v[128:131]
	v_mfma_f32_16x16x32_bf16 v[116:119], v[190:193], v[198:201], v[114:117]
	v_mfma_f32_16x16x32_bf16 v[104:107], v[182:185], v[206:209], v[104:107]
	v_mfma_f32_16x16x32_bf16 v[96:99], v[190:193], v[206:209], v[96:99]
	s_barrier
	s_setprio 2
	v_mfma_f32_16x16x32_bf16 v[88:91], v[182:185], v[214:217], v[88:91]
	v_mfma_f32_16x16x32_bf16 v[80:83], v[190:193], v[214:217], v[80:83]
	v_mfma_f32_16x16x32_bf16 v[72:75], v[182:185], v[222:225], v[72:75]
	v_mfma_f32_16x16x32_bf16 v[64:67], v[190:193], v[222:225], v[64:67]
	s_setprio 0
	s_add_i32 s28, s57, s67
	v_lshl_add_u64 v[114:115], v[226:227], 0, s[10:11]
	s_mov_b32 m0, s28
	ds_read_b128 v[194:197], v167 offset:49152
	ds_read_b128 v[198:201], v167 offset:50176
	ds_read_b128 v[202:205], v167 offset:51200
	ds_read_b128 v[206:209], v167 offset:52224
	ds_read_b128 v[210:213], v167 offset:53248
	ds_read_b128 v[214:217], v167 offset:54272
	ds_read_b128 v[218:221], v167 offset:55296
	ds_read_b128 v[222:225], v167 offset:56320
	global_load_lds_dwordx4 v[114:115], off
	s_add_i32 m0, s28, 0x2000
	s_add_u32 s26, s26, 0x80080
	v_lshl_add_u64 v[114:115], v[228:229], 0, s[10:11]
	s_addc_u32 s27, s27, 0
	s_add_i32 s28, s58, s67
	global_load_lds_dwordx4 v[114:115], off
	s_mov_b32 m0, s28
	s_nop 0
	global_load_lds_dwordx4 v138, s[26:27]
	s_add_i32 m0, s28, 0x2000
	s_nop 0
	global_load_lds_dwordx4 v142, s[26:27]
	v_lshl_add_u64 v[114:115], v[230:231], 0, s[10:11]
	s_mov_b32 m0, s41
	s_nop 0
	global_load_lds_dwordx4 v[114:115], off
	v_lshl_add_u64 v[114:115], v[232:233], 0, s[10:11]
	s_mov_b32 m0, s42
	s_nop 0
	global_load_lds_dwordx4 v[114:115], off
	s_waitcnt vmcnt(8)
	s_waitcnt lgkmcnt(0)
	s_barrier
	s_setprio 1
	s_waitcnt lgkmcnt(0)
	v_mfma_f32_16x16x32_bf16 v[60:63], v[124:127], v[194:197], v[60:63]
	v_mfma_f32_16x16x32_bf16 v[52:55], v[170:173], v[194:197], v[52:55]
	v_mfma_f32_16x16x32_bf16 v[44:47], v[124:127], v[202:205], v[44:47]
	v_mfma_f32_16x16x32_bf16 v[36:39], v[170:173], v[202:205], v[36:39]
	v_mfma_f32_16x16x32_bf16 v[28:31], v[124:127], v[210:213], v[28:31]
	v_mfma_f32_16x16x32_bf16 v[20:23], v[170:173], v[210:213], v[20:23]
	v_mfma_f32_16x16x32_bf16 v[12:15], v[124:127], v[218:221], v[12:15]
	v_mfma_f32_16x16x32_bf16 v[4:7], v[170:173], v[218:221], v[4:7]
	v_mfma_f32_16x16x32_bf16 v[60:63], v[156:159], v[198:201], v[60:63]
	v_mfma_f32_16x16x32_bf16 v[52:55], v[174:177], v[198:201], v[52:55]
	v_mfma_f32_16x16x32_bf16 v[44:47], v[156:159], v[206:209], v[44:47]
	v_mfma_f32_16x16x32_bf16 v[36:39], v[174:177], v[206:209], v[36:39]
	v_mfma_f32_16x16x32_bf16 v[28:31], v[156:159], v[214:217], v[28:31]
	v_mfma_f32_16x16x32_bf16 v[20:23], v[174:177], v[214:217], v[20:23]
	v_mfma_f32_16x16x32_bf16 v[12:15], v[156:159], v[222:225], v[12:15]
	v_mfma_f32_16x16x32_bf16 v[4:7], v[174:177], v[222:225], v[4:7]
	s_setprio 0
	s_setprio 1
	v_mfma_f32_16x16x32_bf16 v[56:59], v[178:181], v[194:197], v[56:59]
	v_mfma_f32_16x16x32_bf16 v[48:51], v[186:189], v[194:197], v[48:51]
	v_mfma_f32_16x16x32_bf16 v[40:43], v[178:181], v[202:205], v[40:43]
	v_mfma_f32_16x16x32_bf16 v[32:35], v[186:189], v[202:205], v[32:35]
	v_mfma_f32_16x16x32_bf16 v[24:27], v[178:181], v[210:213], v[24:27]
	v_mfma_f32_16x16x32_bf16 v[16:19], v[186:189], v[210:213], v[16:19]
	v_mfma_f32_16x16x32_bf16 v[8:11], v[178:181], v[218:221], v[8:11]
	v_mfma_f32_16x16x32_bf16 v[0:3], v[186:189], v[218:221], v[0:3]
	v_mfma_f32_16x16x32_bf16 v[56:59], v[182:185], v[198:201], v[56:59]
	v_mfma_f32_16x16x32_bf16 v[48:51], v[190:193], v[198:201], v[48:51]
	v_mfma_f32_16x16x32_bf16 v[40:43], v[182:185], v[206:209], v[40:43]
	v_mfma_f32_16x16x32_bf16 v[32:35], v[190:193], v[206:209], v[32:35]
	s_barrier
	s_setprio 2
	v_mfma_f32_16x16x32_bf16 v[24:27], v[182:185], v[214:217], v[24:27]
	v_mfma_f32_16x16x32_bf16 v[16:19], v[190:193], v[214:217], v[16:19]
	v_mfma_f32_16x16x32_bf16 v[8:11], v[182:185], v[222:225], v[8:11]
	v_mfma_f32_16x16x32_bf16 v[0:3], v[190:193], v[222:225], v[0:3]
	s_setprio 0
	s_add_i32 s56, s56, 2
	s_add_u32 s54, s54, 0x100
	s_addc_u32 s55, s55, 0
	s_add_u32 s24, s24, 0x100
	s_addc_u32 s25, s25, 0
	s_cmp_gt_u32 s56, 29
	s_cbranch_scc0 .LBB0_2924
	s_and_b64 vcc, exec, s[12:13]
	s_cbranch_vccz .LBB0_2927
	s_barrier

.LBB0_3122:
	ds_read_b128 v[130:133], v177
	ds_read_b128 v[134:137], v177 offset:1024
	ds_read_b128 v[138:141], v177 offset:2048
	ds_read_b128 v[142:145], v177 offset:3072
	ds_read_b128 v[146:149], v179
	ds_read_b128 v[186:189], v179 offset:1024
	ds_read_b128 v[190:193], v179 offset:2048
	ds_read_b128 v[194:197], v179 offset:3072
	s_add_u32 s30, s28, 0xfff80080
	s_addc_u32 s31, s29, -1
	s_cmp_eq_u32 s72, 28
	s_cselect_b32 s35, s6, s31
	s_cselect_b32 s34, s21, s30
	s_cselect_b32 s31, s19, s71
	s_cselect_b32 s30, s27, s70
	s_add_i32 m0, s41, 0xc000
	ds_read_b128 v[198:201], v181
	ds_read_b128 v[202:205], v181 offset:1024
	ds_read_b128 v[206:209], v181 offset:2048
	ds_read_b128 v[210:213], v181 offset:3072
	ds_read_b128 v[214:217], v181 offset:4096
	ds_read_b128 v[218:221], v181 offset:5120
	ds_read_b128 v[222:225], v181 offset:6144
	ds_read_b128 v[226:229], v181 offset:7168
	global_load_lds_dwordx4 v166, s[28:29]
	s_add_i32 m0, s41, 0xe000
	s_nop 0
	global_load_lds_dwordx4 v164, s[28:29]
	s_waitcnt vmcnt(8)
	s_waitcnt lgkmcnt(0)
	s_barrier
	s_setprio 1
	s_waitcnt lgkmcnt(0)
	v_mfma_f32_16x16x32_bf16 v[124:127], v[130:133], v[198:201], v[124:127]
	v_mfma_f32_16x16x32_bf16 v[120:123], v[138:141], v[198:201], v[120:123]
	v_mfma_f32_16x16x32_bf16 v[108:111], v[130:133], v[206:209], v[108:111]
	v_mfma_f32_16x16x32_bf16 v[100:103], v[138:141], v[206:209], v[100:103]
	v_mfma_f32_16x16x32_bf16 v[92:95], v[130:133], v[214:217], v[92:95]
	v_mfma_f32_16x16x32_bf16 v[84:87], v[138:141], v[214:217], v[84:87]
	v_mfma_f32_16x16x32_bf16 v[76:79], v[130:133], v[222:225], v[76:79]
	v_mfma_f32_16x16x32_bf16 v[68:71], v[138:141], v[222:225], v[68:71]
	v_mfma_f32_16x16x32_bf16 v[124:127], v[134:137], v[202:205], v[124:127]
	v_mfma_f32_16x16x32_bf16 v[120:123], v[142:145], v[202:205], v[120:123]
	v_mfma_f32_16x16x32_bf16 v[108:111], v[134:137], v[210:213], v[108:111]
	v_mfma_f32_16x16x32_bf16 v[100:103], v[142:145], v[210:213], v[100:103]
	v_mfma_f32_16x16x32_bf16 v[92:95], v[134:137], v[218:221], v[92:95]
	v_mfma_f32_16x16x32_bf16 v[84:87], v[142:145], v[218:221], v[84:87]
	v_mfma_f32_16x16x32_bf16 v[76:79], v[134:137], v[226:229], v[76:79]
	v_mfma_f32_16x16x32_bf16 v[68:71], v[142:145], v[226:229], v[68:71]
	s_setprio 0
	s_setprio 1
	v_mfma_f32_16x16x32_bf16 v[116:119], v[146:149], v[198:201], v[116:119]
	v_mfma_f32_16x16x32_bf16 v[112:115], v[190:193], v[198:201], v[112:115]
	v_mfma_f32_16x16x32_bf16 v[104:107], v[146:149], v[206:209], v[104:107]
	v_mfma_f32_16x16x32_bf16 v[96:99], v[190:193], v[206:209], v[96:99]
	v_mfma_f32_16x16x32_bf16 v[88:91], v[146:149], v[214:217], v[88:91]
	v_mfma_f32_16x16x32_bf16 v[80:83], v[190:193], v[214:217], v[80:83]
	v_mfma_f32_16x16x32_bf16 v[72:75], v[146:149], v[222:225], v[72:75]
	v_mfma_f32_16x16x32_bf16 v[64:67], v[190:193], v[222:225], v[64:67]
	v_mfma_f32_16x16x32_bf16 v[116:119], v[186:189], v[202:205], v[116:119]
	v_mfma_f32_16x16x32_bf16 v[112:115], v[194:197], v[202:205], v[112:115]
	v_mfma_f32_16x16x32_bf16 v[104:107], v[186:189], v[210:213], v[104:107]
	v_mfma_f32_16x16x32_bf16 v[96:99], v[194:197], v[210:213], v[96:99]
	s_barrier
	s_setprio 2
	v_mfma_f32_16x16x32_bf16 v[88:91], v[186:189], v[218:221], v[88:91]
	v_mfma_f32_16x16x32_bf16 v[80:83], v[194:197], v[218:221], v[80:83]
	v_mfma_f32_16x16x32_bf16 v[72:75], v[186:189], v[226:229], v[72:75]
	v_mfma_f32_16x16x32_bf16 v[64:67], v[194:197], v[226:229], v[64:67]
	s_setprio 0
	s_add_i32 s73, s56, s67
	v_lshl_add_u64 v[150:151], s[30:31], 0, v[154:155]
	s_mov_b32 m0, s73
	ds_read_b128 v[198:201], v181 offset:16384
	ds_read_b128 v[202:205], v181 offset:17408
	ds_read_b128 v[206:209], v181 offset:18432
	ds_read_b128 v[210:213], v181 offset:19456
	ds_read_b128 v[214:217], v181 offset:20480
	ds_read_b128 v[218:221], v181 offset:21504
	ds_read_b128 v[222:225], v181 offset:22528
	ds_read_b128 v[226:229], v181 offset:23552
	global_load_lds_dwordx4 v154, s[30:31]
	s_add_i32 m0, s73, 0x2000
	s_add_u32 s74, s30, 0x80000
	v_lshl_add_u64 v[182:183], s[30:31], 0, v[158:159]
	s_addc_u32 s75, s31, 0
	s_add_i32 s73, s57, s67
	global_load_lds_dwordx4 v158, s[30:31]
	s_mov_b32 m0, s73
	v_lshl_add_u64 v[232:233], s[34:35], 0, v[156:157]
	global_load_lds_dwordx4 v154, s[74:75]
	s_add_i32 m0, s73, 0x2000
	s_nop 0
	global_load_lds_dwordx4 v158, s[74:75]
	v_lshl_add_u64 v[230:231], s[34:35], 0, v[152:153]
	s_mov_b32 m0, s41
	s_nop 0
	global_load_lds_dwordx4 v152, s[34:35]
	s_mov_b32 m0, s42
	s_nop 0
	global_load_lds_dwordx4 v156, s[34:35]
	s_waitcnt vmcnt(8)
	s_waitcnt lgkmcnt(0)
	s_barrier
	s_setprio 1
	s_waitcnt lgkmcnt(0)
	v_mfma_f32_16x16x32_bf16 v[60:63], v[130:133], v[198:201], v[60:63]
	v_mfma_f32_16x16x32_bf16 v[52:55], v[138:141], v[198:201], v[52:55]
	v_mfma_f32_16x16x32_bf16 v[44:47], v[130:133], v[206:209], v[44:47]
	v_mfma_f32_16x16x32_bf16 v[36:39], v[138:141], v[206:209], v[36:39]
	v_mfma_f32_16x16x32_bf16 v[28:31], v[130:133], v[214:217], v[28:31]
	v_mfma_f32_16x16x32_bf16 v[20:23], v[138:141], v[214:217], v[20:23]
	v_mfma_f32_16x16x32_bf16 v[12:15], v[130:133], v[222:225], v[12:15]
	v_mfma_f32_16x16x32_bf16 v[4:7], v[138:141], v[222:225], v[4:7]
	v_mfma_f32_16x16x32_bf16 v[60:63], v[134:137], v[202:205], v[60:63]
	v_mfma_f32_16x16x32_bf16 v[52:55], v[142:145], v[202:205], v[52:55]
	v_mfma_f32_16x16x32_bf16 v[44:47], v[134:137], v[210:213], v[44:47]
	v_mfma_f32_16x16x32_bf16 v[36:39], v[142:145], v[210:213], v[36:39]
	v_mfma_f32_16x16x32_bf16 v[28:31], v[134:137], v[218:221], v[28:31]
	v_mfma_f32_16x16x32_bf16 v[20:23], v[142:145], v[218:221], v[20:23]
	v_mfma_f32_16x16x32_bf16 v[12:15], v[134:137], v[226:229], v[12:15]
	v_mfma_f32_16x16x32_bf16 v[4:7], v[142:145], v[226:229], v[4:7]
	s_setprio 0
	s_setprio 1
	v_mfma_f32_16x16x32_bf16 v[56:59], v[146:149], v[198:201], v[56:59]
	v_mfma_f32_16x16x32_bf16 v[48:51], v[190:193], v[198:201], v[48:51]
	v_mfma_f32_16x16x32_bf16 v[40:43], v[146:149], v[206:209], v[40:43]
	v_mfma_f32_16x16x32_bf16 v[32:35], v[190:193], v[206:209], v[32:35]
	v_mfma_f32_16x16x32_bf16 v[24:27], v[146:149], v[214:217], v[24:27]
	v_mfma_f32_16x16x32_bf16 v[16:19], v[190:193], v[214:217], v[16:19]
	v_mfma_f32_16x16x32_bf16 v[8:11], v[146:149], v[222:225], v[8:11]
	v_mfma_f32_16x16x32_bf16 v[0:3], v[190:193], v[222:225], v[0:3]
	v_mfma_f32_16x16x32_bf16 v[56:59], v[186:189], v[202:205], v[56:59]
	v_mfma_f32_16x16x32_bf16 v[48:51], v[194:197], v[202:205], v[48:51]
	v_mfma_f32_16x16x32_bf16 v[40:43], v[186:189], v[210:213], v[40:43]
	v_mfma_f32_16x16x32_bf16 v[32:35], v[194:197], v[210:213], v[32:35]
	s_barrier
	s_setprio 2
	v_mfma_f32_16x16x32_bf16 v[24:27], v[186:189], v[218:221], v[24:27]
	v_mfma_f32_16x16x32_bf16 v[16:19], v[194:197], v[218:221], v[16:19]
	v_mfma_f32_16x16x32_bf16 v[8:11], v[186:189], v[226:229], v[8:11]
	v_mfma_f32_16x16x32_bf16 v[0:3], v[194:197], v[226:229], v[0:3]
	s_setprio 0
	s_add_i32 s73, 0, 0x18000
	v_add_u32_e32 v129, s73, v173
	s_add_i32 s74, 0, 0x1c000
	ds_read_b128 v[130:133], v129
	ds_read_b128 v[134:137], v129 offset:1024
	ds_read_b128 v[138:141], v129 offset:2048
	ds_read_b128 v[142:145], v129 offset:3072
	v_add_u32_e32 v129, s74, v173
	ds_read_b128 v[146:149], v129
	ds_read_b128 v[186:189], v129 offset:1024
	ds_read_b128 v[190:193], v129 offset:2048
	ds_read_b128 v[194:197], v129 offset:3072
	s_add_u32 s34, s34, 0x80000
	s_addc_u32 s35, s35, 0
	s_mov_b32 m0, s43
	ds_read_b128 v[198:201], v181 offset:32768
	ds_read_b128 v[202:205], v181 offset:33792
	ds_read_b128 v[206:209], v181 offset:34816
	ds_read_b128 v[210:213], v181 offset:35840
	ds_read_b128 v[214:217], v181 offset:36864
	ds_read_b128 v[218:221], v181 offset:37888
	ds_read_b128 v[222:225], v181 offset:38912
	ds_read_b128 v[226:229], v181 offset:39936
	global_load_lds_dwordx4 v152, s[34:35]
	s_mov_b32 m0, s44
	s_nop 0
	global_load_lds_dwordx4 v156, s[34:35]
	s_waitcnt vmcnt(8)
	s_waitcnt lgkmcnt(0)
	s_barrier
	s_setprio 1
	s_waitcnt lgkmcnt(0)
	v_mfma_f32_16x16x32_bf16 v[124:127], v[130:133], v[198:201], v[124:127]
	v_mfma_f32_16x16x32_bf16 v[120:123], v[138:141], v[198:201], v[120:123]
	v_mfma_f32_16x16x32_bf16 v[108:111], v[130:133], v[206:209], v[108:111]
	v_mfma_f32_16x16x32_bf16 v[100:103], v[138:141], v[206:209], v[100:103]
	v_mfma_f32_16x16x32_bf16 v[92:95], v[130:133], v[214:217], v[92:95]
	v_mfma_f32_16x16x32_bf16 v[84:87], v[138:141], v[214:217], v[84:87]
	v_mfma_f32_16x16x32_bf16 v[76:79], v[130:133], v[222:225], v[76:79]
	v_mfma_f32_16x16x32_bf16 v[68:71], v[138:141], v[222:225], v[68:71]
	v_mfma_f32_16x16x32_bf16 v[124:127], v[134:137], v[202:205], v[124:127]
	v_mfma_f32_16x16x32_bf16 v[120:123], v[142:145], v[202:205], v[120:123]
	v_mfma_f32_16x16x32_bf16 v[108:111], v[134:137], v[210:213], v[108:111]
	v_mfma_f32_16x16x32_bf16 v[100:103], v[142:145], v[210:213], v[100:103]
	v_mfma_f32_16x16x32_bf16 v[92:95], v[134:137], v[218:221], v[92:95]
	v_mfma_f32_16x16x32_bf16 v[84:87], v[142:145], v[218:221], v[84:87]
	v_mfma_f32_16x16x32_bf16 v[76:79], v[134:137], v[226:229], v[76:79]
	v_mfma_f32_16x16x32_bf16 v[68:71], v[142:145], v[226:229], v[68:71]
	s_setprio 0
	s_setprio 1
	v_mfma_f32_16x16x32_bf16 v[116:119], v[146:149], v[198:201], v[116:119]
	v_mfma_f32_16x16x32_bf16 v[112:115], v[190:193], v[198:201], v[112:115]
	v_mfma_f32_16x16x32_bf16 v[104:107], v[146:149], v[206:209], v[104:107]
	v_mfma_f32_16x16x32_bf16 v[96:99], v[190:193], v[206:209], v[96:99]
	v_mfma_f32_16x16x32_bf16 v[88:91], v[146:149], v[214:217], v[88:91]
	v_mfma_f32_16x16x32_bf16 v[80:83], v[190:193], v[214:217], v[80:83]
	v_mfma_f32_16x16x32_bf16 v[72:75], v[146:149], v[222:225], v[72:75]
	v_mfma_f32_16x16x32_bf16 v[64:67], v[190:193], v[222:225], v[64:67]
	v_mfma_f32_16x16x32_bf16 v[116:119], v[186:189], v[202:205], v[116:119]
	v_mfma_f32_16x16x32_bf16 v[112:115], v[194:197], v[202:205], v[112:115]
	v_mfma_f32_16x16x32_bf16 v[104:107], v[186:189], v[210:213], v[104:107]
	v_mfma_f32_16x16x32_bf16 v[96:99], v[194:197], v[210:213], v[96:99]
	s_barrier
	s_setprio 2
	v_mfma_f32_16x16x32_bf16 v[88:91], v[186:189], v[218:221], v[88:91]
	v_mfma_f32_16x16x32_bf16 v[80:83], v[194:197], v[218:221], v[80:83]
	v_mfma_f32_16x16x32_bf16 v[72:75], v[186:189], v[226:229], v[72:75]
	v_mfma_f32_16x16x32_bf16 v[64:67], v[194:197], v[226:229], v[64:67]
	s_setprio 0
	s_add_i32 s34, s73, s67
	v_lshl_add_u64 v[150:151], v[150:151], 0, s[12:13]
	s_mov_b32 m0, s34
	ds_read_b128 v[198:201], v181 offset:49152
	ds_read_b128 v[202:205], v181 offset:50176
	ds_read_b128 v[206:209], v181 offset:51200
	ds_read_b128 v[210:213], v181 offset:52224
	ds_read_b128 v[214:217], v181 offset:53248
	ds_read_b128 v[218:221], v181 offset:54272
	ds_read_b128 v[222:225], v181 offset:55296
	ds_read_b128 v[226:229], v181 offset:56320
	global_load_lds_dwordx4 v[150:151], off
	s_add_i32 m0, s34, 0x2000
	s_add_u32 s30, s30, 0x80080
	v_lshl_add_u64 v[150:151], v[182:183], 0, s[12:13]
	s_addc_u32 s31, s31, 0
	s_add_i32 s34, s74, s67
	global_load_lds_dwordx4 v[150:151], off
	s_mov_b32 m0, s34
	s_nop 0
	global_load_lds_dwordx4 v154, s[30:31]
	s_add_i32 m0, s34, 0x2000
	s_nop 0
	global_load_lds_dwordx4 v158, s[30:31]
	v_lshl_add_u64 v[150:151], v[230:231], 0, s[12:13]
	s_mov_b32 m0, s49
	s_nop 0
	global_load_lds_dwordx4 v[150:151], off
	v_lshl_add_u64 v[150:151], v[232:233], 0, s[12:13]
	s_mov_b32 m0, s50
	s_nop 0
	global_load_lds_dwordx4 v[150:151], off
	s_waitcnt vmcnt(8)
	s_waitcnt lgkmcnt(0)
	s_barrier
	s_setprio 1
	s_waitcnt lgkmcnt(0)
	v_mfma_f32_16x16x32_bf16 v[60:63], v[130:133], v[198:201], v[60:63]
	v_mfma_f32_16x16x32_bf16 v[52:55], v[138:141], v[198:201], v[52:55]
	v_mfma_f32_16x16x32_bf16 v[44:47], v[130:133], v[206:209], v[44:47]
	v_mfma_f32_16x16x32_bf16 v[36:39], v[138:141], v[206:209], v[36:39]
	v_mfma_f32_16x16x32_bf16 v[28:31], v[130:133], v[214:217], v[28:31]
	v_mfma_f32_16x16x32_bf16 v[20:23], v[138:141], v[214:217], v[20:23]
	v_mfma_f32_16x16x32_bf16 v[12:15], v[130:133], v[222:225], v[12:15]
	v_mfma_f32_16x16x32_bf16 v[4:7], v[138:141], v[222:225], v[4:7]
	v_mfma_f32_16x16x32_bf16 v[60:63], v[134:137], v[202:205], v[60:63]
	v_mfma_f32_16x16x32_bf16 v[52:55], v[142:145], v[202:205], v[52:55]
	v_mfma_f32_16x16x32_bf16 v[44:47], v[134:137], v[210:213], v[44:47]
	v_mfma_f32_16x16x32_bf16 v[36:39], v[142:145], v[210:213], v[36:39]
	v_mfma_f32_16x16x32_bf16 v[28:31], v[134:137], v[218:221], v[28:31]
	v_mfma_f32_16x16x32_bf16 v[20:23], v[142:145], v[218:221], v[20:23]
	v_mfma_f32_16x16x32_bf16 v[12:15], v[134:137], v[226:229], v[12:15]
	v_mfma_f32_16x16x32_bf16 v[4:7], v[142:145], v[226:229], v[4:7]
	s_setprio 0
	s_setprio 1
	v_mfma_f32_16x16x32_bf16 v[56:59], v[146:149], v[198:201], v[56:59]
	v_mfma_f32_16x16x32_bf16 v[48:51], v[190:193], v[198:201], v[48:51]
	v_mfma_f32_16x16x32_bf16 v[40:43], v[146:149], v[206:209], v[40:43]
	v_mfma_f32_16x16x32_bf16 v[32:35], v[190:193], v[206:209], v[32:35]
	v_mfma_f32_16x16x32_bf16 v[24:27], v[146:149], v[214:217], v[24:27]
	v_mfma_f32_16x16x32_bf16 v[16:19], v[190:193], v[214:217], v[16:19]
	v_mfma_f32_16x16x32_bf16 v[8:11], v[146:149], v[222:225], v[8:11]
	v_mfma_f32_16x16x32_bf16 v[0:3], v[190:193], v[222:225], v[0:3]
	v_mfma_f32_16x16x32_bf16 v[56:59], v[186:189], v[202:205], v[56:59]
	v_mfma_f32_16x16x32_bf16 v[48:51], v[194:197], v[202:205], v[48:51]
	v_mfma_f32_16x16x32_bf16 v[40:43], v[186:189], v[210:213], v[40:43]
	v_mfma_f32_16x16x32_bf16 v[32:35], v[194:197], v[210:213], v[32:35]
	s_barrier
	s_setprio 2
	v_mfma_f32_16x16x32_bf16 v[24:27], v[186:189], v[218:221], v[24:27]
	v_mfma_f32_16x16x32_bf16 v[16:19], v[194:197], v[218:221], v[16:19]
	v_mfma_f32_16x16x32_bf16 v[8:11], v[186:189], v[226:229], v[8:11]
	v_mfma_f32_16x16x32_bf16 v[0:3], v[194:197], v[226:229], v[0:3]
	s_setprio 0
	s_add_i32 s72, s72, 2
	s_add_u32 s70, s70, 0x100
	s_addc_u32 s71, s71, 0
	s_add_u32 s28, s28, 0x100
	s_addc_u32 s29, s29, 0
	s_cmp_gt_u32 s72, 29
	s_cbranch_scc0 .LBB0_3122
	s_and_b64 vcc, exec, s[14:15]
	s_cbranch_vccz .LBB0_3125
	s_barrier

.LBB0_3281:
	ds_read_b128 v[128:131], v231
	ds_read_b128 v[132:135], v231 offset:1024
	ds_read_b128 v[136:139], v231 offset:2048
	ds_read_b128 v[140:143], v231 offset:3072
	ds_read_b128 v[144:147], v232
	ds_read_b128 v[148:151], v232 offset:1024
	ds_read_b128 v[152:155], v232 offset:2048
	ds_read_b128 v[174:177], v232 offset:3072
	s_add_u32 s24, s22, 0xfff80080
	s_addc_u32 s25, s23, -1
	s_cmp_eq_u32 s30, 28
	s_cselect_b32 s27, s3, s25
	s_cselect_b32 s26, s15, s24
	s_cselect_b32 s25, s13, s29
	s_cselect_b32 s24, s21, s28
	s_add_i32 m0, s40, 0xc000
	ds_read_b128 v[178:181], v233
	ds_read_b128 v[182:185], v233 offset:1024
	ds_read_b128 v[186:189], v233 offset:2048
	ds_read_b128 v[190:193], v233 offset:3072
	ds_read_b128 v[194:197], v233 offset:4096
	ds_read_b128 v[198:201], v233 offset:5120
	ds_read_b128 v[202:205], v233 offset:6144
	ds_read_b128 v[206:209], v233 offset:7168
	global_load_lds_dwordx4 v168, s[22:23]
	s_add_i32 m0, s40, 0xe000
	s_nop 0
	global_load_lds_dwordx4 v166, s[22:23]
	s_waitcnt vmcnt(8)
	s_waitcnt lgkmcnt(0)
	s_barrier
	s_setprio 1
	s_waitcnt lgkmcnt(0)
	v_mfma_f32_16x16x32_bf16 v[124:127], v[128:131], v[178:181], v[124:127]
	v_mfma_f32_16x16x32_bf16 v[120:123], v[136:139], v[178:181], v[120:123]
	v_mfma_f32_16x16x32_bf16 v[116:119], v[128:131], v[186:189], v[116:119]
	v_mfma_f32_16x16x32_bf16 v[112:115], v[136:139], v[186:189], v[112:115]
	v_mfma_f32_16x16x32_bf16 v[108:111], v[128:131], v[194:197], v[108:111]
	v_mfma_f32_16x16x32_bf16 v[104:107], v[136:139], v[194:197], v[104:107]
	v_mfma_f32_16x16x32_bf16 v[100:103], v[128:131], v[202:205], v[100:103]
	v_mfma_f32_16x16x32_bf16 v[96:99], v[136:139], v[202:205], v[96:99]
	v_mfma_f32_16x16x32_bf16 v[124:127], v[132:135], v[182:185], v[124:127]
	v_mfma_f32_16x16x32_bf16 v[120:123], v[140:143], v[182:185], v[120:123]
	v_mfma_f32_16x16x32_bf16 v[116:119], v[132:135], v[190:193], v[116:119]
	v_mfma_f32_16x16x32_bf16 v[112:115], v[140:143], v[190:193], v[112:115]
	v_mfma_f32_16x16x32_bf16 v[108:111], v[132:135], v[198:201], v[108:111]
	v_mfma_f32_16x16x32_bf16 v[104:107], v[140:143], v[198:201], v[104:107]
	v_mfma_f32_16x16x32_bf16 v[100:103], v[132:135], v[206:209], v[100:103]
	v_mfma_f32_16x16x32_bf16 v[96:99], v[140:143], v[206:209], v[96:99]
	s_setprio 0
	s_setprio 1
	v_mfma_f32_16x16x32_bf16 v[60:63], v[144:147], v[178:181], v[60:63]
	v_mfma_f32_16x16x32_bf16 v[56:59], v[152:155], v[178:181], v[56:59]
	v_mfma_f32_16x16x32_bf16 v[52:55], v[144:147], v[186:189], v[52:55]
	v_mfma_f32_16x16x32_bf16 v[48:51], v[152:155], v[186:189], v[48:51]
	v_mfma_f32_16x16x32_bf16 v[44:47], v[144:147], v[194:197], v[44:47]
	v_mfma_f32_16x16x32_bf16 v[40:43], v[152:155], v[194:197], v[40:43]
	v_mfma_f32_16x16x32_bf16 v[36:39], v[144:147], v[202:205], v[36:39]
	v_mfma_f32_16x16x32_bf16 v[32:35], v[152:155], v[202:205], v[32:35]
	v_mfma_f32_16x16x32_bf16 v[60:63], v[148:151], v[182:185], v[60:63]
	v_mfma_f32_16x16x32_bf16 v[56:59], v[174:177], v[182:185], v[56:59]
	v_mfma_f32_16x16x32_bf16 v[52:55], v[148:151], v[190:193], v[52:55]
	v_mfma_f32_16x16x32_bf16 v[48:51], v[174:177], v[190:193], v[48:51]
	s_barrier
	s_setprio 2
	v_mfma_f32_16x16x32_bf16 v[44:47], v[148:151], v[198:201], v[44:47]
	v_mfma_f32_16x16x32_bf16 v[40:43], v[174:177], v[198:201], v[40:43]
	v_mfma_f32_16x16x32_bf16 v[36:39], v[148:151], v[206:209], v[36:39]
	v_mfma_f32_16x16x32_bf16 v[32:35], v[174:177], v[206:209], v[32:35]
	s_setprio 0
	s_add_i32 s31, s64, s67
	v_lshl_add_u64 v[210:211], s[24:25], 0, v[158:159]
	s_mov_b32 m0, s31
	ds_read_b128 v[178:181], v233 offset:16384
	ds_read_b128 v[182:185], v233 offset:17408
	ds_read_b128 v[186:189], v233 offset:18432
	ds_read_b128 v[190:193], v233 offset:19456
	ds_read_b128 v[194:197], v233 offset:20480
	ds_read_b128 v[198:201], v233 offset:21504
	ds_read_b128 v[202:205], v233 offset:22528
	ds_read_b128 v[206:209], v233 offset:23552
	global_load_lds_dwordx4 v158, s[24:25]
	s_add_i32 m0, s31, 0x2000
	s_add_u32 s34, s24, 0x80000
	v_lshl_add_u64 v[212:213], s[24:25], 0, v[162:163]
	s_addc_u32 s35, s25, 0
	s_add_i32 s31, s65, s67
	global_load_lds_dwordx4 v162, s[24:25]
	s_mov_b32 m0, s31
	v_lshl_add_u64 v[216:217], s[26:27], 0, v[160:161]
	global_load_lds_dwordx4 v158, s[34:35]
	s_add_i32 m0, s31, 0x2000
	s_nop 0
	global_load_lds_dwordx4 v162, s[34:35]
	v_lshl_add_u64 v[214:215], s[26:27], 0, v[156:157]
	s_mov_b32 m0, s40
	s_nop 0
	global_load_lds_dwordx4 v156, s[26:27]
	s_mov_b32 m0, s41
	s_nop 0
	global_load_lds_dwordx4 v160, s[26:27]
	s_waitcnt vmcnt(8)
	s_waitcnt lgkmcnt(0)
	s_barrier
	s_setprio 1
	s_waitcnt lgkmcnt(0)
	v_mfma_f32_16x16x32_bf16 v[92:95], v[128:131], v[178:181], v[92:95]
	v_mfma_f32_16x16x32_bf16 v[88:91], v[136:139], v[178:181], v[88:91]
	v_mfma_f32_16x16x32_bf16 v[84:87], v[128:131], v[186:189], v[84:87]
	v_mfma_f32_16x16x32_bf16 v[80:83], v[136:139], v[186:189], v[80:83]
	v_mfma_f32_16x16x32_bf16 v[76:79], v[128:131], v[194:197], v[76:79]
	v_mfma_f32_16x16x32_bf16 v[72:75], v[136:139], v[194:197], v[72:75]
	v_mfma_f32_16x16x32_bf16 v[68:71], v[128:131], v[202:205], v[68:71]
	v_mfma_f32_16x16x32_bf16 v[64:67], v[136:139], v[202:205], v[64:67]
	v_mfma_f32_16x16x32_bf16 v[92:95], v[132:135], v[182:185], v[92:95]
	v_mfma_f32_16x16x32_bf16 v[88:91], v[140:143], v[182:185], v[88:91]
	v_mfma_f32_16x16x32_bf16 v[84:87], v[132:135], v[190:193], v[84:87]
	v_mfma_f32_16x16x32_bf16 v[80:83], v[140:143], v[190:193], v[80:83]
	v_mfma_f32_16x16x32_bf16 v[76:79], v[132:135], v[198:201], v[76:79]
	v_mfma_f32_16x16x32_bf16 v[72:75], v[140:143], v[198:201], v[72:75]
	v_mfma_f32_16x16x32_bf16 v[68:71], v[132:135], v[206:209], v[68:71]
	v_mfma_f32_16x16x32_bf16 v[64:67], v[140:143], v[206:209], v[64:67]
	s_setprio 0
	s_setprio 1
	v_mfma_f32_16x16x32_bf16 v[28:31], v[144:147], v[178:181], v[28:31]
	v_mfma_f32_16x16x32_bf16 v[24:27], v[152:155], v[178:181], v[24:27]
	v_mfma_f32_16x16x32_bf16 v[20:23], v[144:147], v[186:189], v[20:23]
	v_mfma_f32_16x16x32_bf16 v[16:19], v[152:155], v[186:189], v[16:19]
	v_mfma_f32_16x16x32_bf16 v[12:15], v[144:147], v[194:197], v[12:15]
	v_mfma_f32_16x16x32_bf16 v[8:11], v[152:155], v[194:197], v[8:11]
	v_mfma_f32_16x16x32_bf16 v[4:7], v[144:147], v[202:205], v[4:7]
	v_mfma_f32_16x16x32_bf16 v[0:3], v[152:155], v[202:205], v[0:3]
	v_mfma_f32_16x16x32_bf16 v[28:31], v[148:151], v[182:185], v[28:31]
	v_mfma_f32_16x16x32_bf16 v[24:27], v[174:177], v[182:185], v[24:27]
	v_mfma_f32_16x16x32_bf16 v[20:23], v[148:151], v[190:193], v[20:23]
	v_mfma_f32_16x16x32_bf16 v[16:19], v[174:177], v[190:193], v[16:19]
	s_barrier
	s_setprio 2
	v_mfma_f32_16x16x32_bf16 v[12:15], v[148:151], v[198:201], v[12:15]
	v_mfma_f32_16x16x32_bf16 v[8:11], v[174:177], v[198:201], v[8:11]
	v_mfma_f32_16x16x32_bf16 v[4:7], v[148:151], v[206:209], v[4:7]
	v_mfma_f32_16x16x32_bf16 v[0:3], v[174:177], v[206:209], v[0:3]
	s_setprio 0
	s_add_i32 s31, 0, 0x18000
	s_add_i32 s34, 0, 0x1c000
	v_add_u32_e32 v140, s31, v230
	v_add_u32_e32 v164, s34, v230
	ds_read_b128 v[128:131], v140
	ds_read_b128 v[132:135], v140 offset:1024
	ds_read_b128 v[136:139], v140 offset:2048
	ds_read_b128 v[140:143], v140 offset:3072
	ds_read_b128 v[144:147], v164
	ds_read_b128 v[148:151], v164 offset:1024
	ds_read_b128 v[152:155], v164 offset:2048
	ds_read_b128 v[174:177], v164 offset:3072
	s_add_u32 s26, s26, 0x80000
	s_addc_u32 s27, s27, 0
	s_mov_b32 m0, s42
	ds_read_b128 v[178:181], v233 offset:32768
	ds_read_b128 v[182:185], v233 offset:33792
	ds_read_b128 v[186:189], v233 offset:34816
	ds_read_b128 v[190:193], v233 offset:35840
	ds_read_b128 v[194:197], v233 offset:36864
	ds_read_b128 v[198:201], v233 offset:37888
	ds_read_b128 v[202:205], v233 offset:38912
	ds_read_b128 v[206:209], v233 offset:39936
	global_load_lds_dwordx4 v156, s[26:27]
	s_mov_b32 m0, s43
	s_nop 0
	global_load_lds_dwordx4 v160, s[26:27]
	s_waitcnt vmcnt(8)
	s_waitcnt lgkmcnt(0)
	s_barrier
	s_setprio 1
	s_waitcnt lgkmcnt(0)
	v_mfma_f32_16x16x32_bf16 v[124:127], v[128:131], v[178:181], v[124:127]
	v_mfma_f32_16x16x32_bf16 v[120:123], v[136:139], v[178:181], v[120:123]
	v_mfma_f32_16x16x32_bf16 v[116:119], v[128:131], v[186:189], v[116:119]
	v_mfma_f32_16x16x32_bf16 v[112:115], v[136:139], v[186:189], v[112:115]
	v_mfma_f32_16x16x32_bf16 v[108:111], v[128:131], v[194:197], v[108:111]
	v_mfma_f32_16x16x32_bf16 v[104:107], v[136:139], v[194:197], v[104:107]
	v_mfma_f32_16x16x32_bf16 v[100:103], v[128:131], v[202:205], v[100:103]
	v_mfma_f32_16x16x32_bf16 v[96:99], v[136:139], v[202:205], v[96:99]
	v_mfma_f32_16x16x32_bf16 v[124:127], v[132:135], v[182:185], v[124:127]
	v_mfma_f32_16x16x32_bf16 v[120:123], v[140:143], v[182:185], v[120:123]
	v_mfma_f32_16x16x32_bf16 v[116:119], v[132:135], v[190:193], v[116:119]
	v_mfma_f32_16x16x32_bf16 v[112:115], v[140:143], v[190:193], v[112:115]
	v_mfma_f32_16x16x32_bf16 v[108:111], v[132:135], v[198:201], v[108:111]
	v_mfma_f32_16x16x32_bf16 v[104:107], v[140:143], v[198:201], v[104:107]
	v_mfma_f32_16x16x32_bf16 v[100:103], v[132:135], v[206:209], v[100:103]
	v_mfma_f32_16x16x32_bf16 v[96:99], v[140:143], v[206:209], v[96:99]
	s_setprio 0
	s_setprio 1
	v_mfma_f32_16x16x32_bf16 v[60:63], v[144:147], v[178:181], v[60:63]
	v_mfma_f32_16x16x32_bf16 v[56:59], v[152:155], v[178:181], v[56:59]
	v_mfma_f32_16x16x32_bf16 v[52:55], v[144:147], v[186:189], v[52:55]
	v_mfma_f32_16x16x32_bf16 v[48:51], v[152:155], v[186:189], v[48:51]
	v_mfma_f32_16x16x32_bf16 v[44:47], v[144:147], v[194:197], v[44:47]
	v_mfma_f32_16x16x32_bf16 v[40:43], v[152:155], v[194:197], v[40:43]
	v_mfma_f32_16x16x32_bf16 v[36:39], v[144:147], v[202:205], v[36:39]
	v_mfma_f32_16x16x32_bf16 v[32:35], v[152:155], v[202:205], v[32:35]
	v_mfma_f32_16x16x32_bf16 v[60:63], v[148:151], v[182:185], v[60:63]
	v_mfma_f32_16x16x32_bf16 v[56:59], v[174:177], v[182:185], v[56:59]
	v_mfma_f32_16x16x32_bf16 v[52:55], v[148:151], v[190:193], v[52:55]
	v_mfma_f32_16x16x32_bf16 v[48:51], v[174:177], v[190:193], v[48:51]
	s_barrier
	s_setprio 2
	v_mfma_f32_16x16x32_bf16 v[44:47], v[148:151], v[198:201], v[44:47]
	v_mfma_f32_16x16x32_bf16 v[40:43], v[174:177], v[198:201], v[40:43]
	v_mfma_f32_16x16x32_bf16 v[36:39], v[148:151], v[206:209], v[36:39]
	v_mfma_f32_16x16x32_bf16 v[32:35], v[174:177], v[206:209], v[32:35]
	s_setprio 0
	s_add_i32 s26, s31, s67
	v_lshl_add_u64 v[210:211], v[210:211], 0, s[6:7]
	s_mov_b32 m0, s26
	ds_read_b128 v[178:181], v233 offset:49152
	ds_read_b128 v[182:185], v233 offset:50176
	ds_read_b128 v[186:189], v233 offset:51200
	ds_read_b128 v[190:193], v233 offset:52224
	ds_read_b128 v[194:197], v233 offset:53248
	ds_read_b128 v[198:201], v233 offset:54272
	ds_read_b128 v[202:205], v233 offset:55296
	ds_read_b128 v[206:209], v233 offset:56320
	global_load_lds_dwordx4 v[210:211], off
	s_add_i32 m0, s26, 0x2000
	s_add_u32 s24, s24, 0x80080
	v_lshl_add_u64 v[210:211], v[212:213], 0, s[6:7]
	s_addc_u32 s25, s25, 0
	s_add_i32 s26, s34, s67
	global_load_lds_dwordx4 v[210:211], off
	s_mov_b32 m0, s26
	s_nop 0
	global_load_lds_dwordx4 v158, s[24:25]
	s_add_i32 m0, s26, 0x2000
	s_nop 0
	global_load_lds_dwordx4 v162, s[24:25]
	v_lshl_add_u64 v[210:211], v[214:215], 0, s[6:7]
	s_mov_b32 m0, s57
	s_nop 0
	global_load_lds_dwordx4 v[210:211], off
	v_lshl_add_u64 v[210:211], v[216:217], 0, s[6:7]
	s_mov_b32 m0, s58
	s_nop 0
	global_load_lds_dwordx4 v[210:211], off
	s_waitcnt vmcnt(8)
	s_waitcnt lgkmcnt(0)
	s_barrier
	s_setprio 1
	s_waitcnt lgkmcnt(0)
	v_mfma_f32_16x16x32_bf16 v[92:95], v[128:131], v[178:181], v[92:95]
	v_mfma_f32_16x16x32_bf16 v[88:91], v[136:139], v[178:181], v[88:91]
	v_mfma_f32_16x16x32_bf16 v[84:87], v[128:131], v[186:189], v[84:87]
	v_mfma_f32_16x16x32_bf16 v[80:83], v[136:139], v[186:189], v[80:83]
	v_mfma_f32_16x16x32_bf16 v[76:79], v[128:131], v[194:197], v[76:79]
	v_mfma_f32_16x16x32_bf16 v[72:75], v[136:139], v[194:197], v[72:75]
	v_mfma_f32_16x16x32_bf16 v[68:71], v[128:131], v[202:205], v[68:71]
	v_mfma_f32_16x16x32_bf16 v[64:67], v[136:139], v[202:205], v[64:67]
	v_mfma_f32_16x16x32_bf16 v[92:95], v[132:135], v[182:185], v[92:95]
	v_mfma_f32_16x16x32_bf16 v[88:91], v[140:143], v[182:185], v[88:91]
	v_mfma_f32_16x16x32_bf16 v[84:87], v[132:135], v[190:193], v[84:87]
	v_mfma_f32_16x16x32_bf16 v[80:83], v[140:143], v[190:193], v[80:83]
	v_mfma_f32_16x16x32_bf16 v[76:79], v[132:135], v[198:201], v[76:79]
	v_mfma_f32_16x16x32_bf16 v[72:75], v[140:143], v[198:201], v[72:75]
	v_mfma_f32_16x16x32_bf16 v[68:71], v[132:135], v[206:209], v[68:71]
	v_mfma_f32_16x16x32_bf16 v[64:67], v[140:143], v[206:209], v[64:67]
	s_setprio 0
	s_setprio 1
	v_mfma_f32_16x16x32_bf16 v[28:31], v[144:147], v[178:181], v[28:31]
	v_mfma_f32_16x16x32_bf16 v[24:27], v[152:155], v[178:181], v[24:27]
	v_mfma_f32_16x16x32_bf16 v[20:23], v[144:147], v[186:189], v[20:23]
	v_mfma_f32_16x16x32_bf16 v[16:19], v[152:155], v[186:189], v[16:19]
	v_mfma_f32_16x16x32_bf16 v[12:15], v[144:147], v[194:197], v[12:15]
	v_mfma_f32_16x16x32_bf16 v[8:11], v[152:155], v[194:197], v[8:11]
	v_mfma_f32_16x16x32_bf16 v[4:7], v[144:147], v[202:205], v[4:7]
	v_mfma_f32_16x16x32_bf16 v[0:3], v[152:155], v[202:205], v[0:3]
	v_mfma_f32_16x16x32_bf16 v[28:31], v[148:151], v[182:185], v[28:31]
	v_mfma_f32_16x16x32_bf16 v[24:27], v[174:177], v[182:185], v[24:27]
	v_mfma_f32_16x16x32_bf16 v[20:23], v[148:151], v[190:193], v[20:23]
	v_mfma_f32_16x16x32_bf16 v[16:19], v[174:177], v[190:193], v[16:19]
	s_barrier
	s_setprio 2
	v_mfma_f32_16x16x32_bf16 v[12:15], v[148:151], v[198:201], v[12:15]
	v_mfma_f32_16x16x32_bf16 v[8:11], v[174:177], v[198:201], v[8:11]
	v_mfma_f32_16x16x32_bf16 v[4:7], v[148:151], v[206:209], v[4:7]
	v_mfma_f32_16x16x32_bf16 v[0:3], v[174:177], v[206:209], v[0:3]
	s_setprio 0
	s_add_i32 s30, s30, 2
	s_add_u32 s28, s28, 0x100
	s_addc_u32 s29, s29, 0
	s_add_u32 s22, s22, 0x100
	s_addc_u32 s23, s23, 0
	s_cmp_gt_u32 s30, 29
	s_cbranch_scc0 .LBB0_3281
	s_and_b64 vcc, exec, s[8:9]
	s_cbranch_vccz .LBB0_3284
	s_barrier

.LBB0_3501:
	ds_read_b128 v[128:131], v201
	ds_read_b128 v[132:135], v201 offset:1024
	ds_read_b128 v[136:139], v201 offset:2048
	ds_read_b128 v[140:143], v201 offset:3072
	ds_read_b128 v[144:147], v202
	ds_read_b128 v[148:151], v202 offset:1024
	ds_read_b128 v[170:173], v202 offset:2048
	ds_read_b128 v[174:177], v202 offset:3072
	s_add_u32 s18, s16, 0x100
	s_addc_u32 s19, s17, 0
	s_cmpk_eq_i32 s68, 0x54
	s_cselect_b32 s23, s3, s19
	s_cselect_b32 s22, s2, s18
	s_cselect_b32 s21, s15, s25
	s_cselect_b32 s20, s14, s24
	v_lshl_add_u64 v[198:199], s[16:17], 0, v[164:165]
	s_add_i32 m0, s30, 0xc000
	ds_read_b128 v[178:181], v203
	ds_read_b128 v[182:185], v203 offset:1024
	ds_read_b128 v[186:189], v203 offset:2048
	ds_read_b128 v[190:193], v203 offset:3072
	ds_read_b128 v[194:197], v203 offset:4096
	ds_read_b128 v[206:209], v203 offset:5120
	ds_read_b128 v[210:213], v203 offset:6144
	ds_read_b128 v[214:217], v203 offset:7168
	global_load_lds_dwordx4 v[198:199], off
	v_lshl_add_u64 v[198:199], s[16:17], 0, v[162:163]
	s_add_i32 m0, s30, 0xe000
	s_nop 0
	global_load_lds_dwordx4 v[198:199], off
	s_waitcnt vmcnt(8)
	s_waitcnt lgkmcnt(0)
	s_barrier
	s_setprio 1
	s_waitcnt lgkmcnt(0)
	v_mfma_f32_16x16x32_bf16 v[124:127], v[128:131], v[178:181], v[124:127]
	v_mfma_f32_16x16x32_bf16 v[120:123], v[136:139], v[178:181], v[120:123]
	v_mfma_f32_16x16x32_bf16 v[116:119], v[128:131], v[186:189], v[116:119]
	v_mfma_f32_16x16x32_bf16 v[112:115], v[136:139], v[186:189], v[112:115]
	v_mfma_f32_16x16x32_bf16 v[108:111], v[128:131], v[194:197], v[108:111]
	v_mfma_f32_16x16x32_bf16 v[104:107], v[136:139], v[194:197], v[104:107]
	v_mfma_f32_16x16x32_bf16 v[100:103], v[128:131], v[210:213], v[100:103]
	v_mfma_f32_16x16x32_bf16 v[96:99], v[136:139], v[210:213], v[96:99]
	v_mfma_f32_16x16x32_bf16 v[124:127], v[132:135], v[182:185], v[124:127]
	v_mfma_f32_16x16x32_bf16 v[120:123], v[140:143], v[182:185], v[120:123]
	v_mfma_f32_16x16x32_bf16 v[116:119], v[132:135], v[190:193], v[116:119]
	v_mfma_f32_16x16x32_bf16 v[112:115], v[140:143], v[190:193], v[112:115]
	v_mfma_f32_16x16x32_bf16 v[108:111], v[132:135], v[206:209], v[108:111]
	v_mfma_f32_16x16x32_bf16 v[104:107], v[140:143], v[206:209], v[104:107]
	v_mfma_f32_16x16x32_bf16 v[100:103], v[132:135], v[214:217], v[100:103]
	v_mfma_f32_16x16x32_bf16 v[96:99], v[140:143], v[214:217], v[96:99]
	s_setprio 0
	s_setprio 1
	v_mfma_f32_16x16x32_bf16 v[60:63], v[144:147], v[178:181], v[60:63]
	v_mfma_f32_16x16x32_bf16 v[56:59], v[170:173], v[178:181], v[56:59]
	v_mfma_f32_16x16x32_bf16 v[52:55], v[144:147], v[186:189], v[52:55]
	v_mfma_f32_16x16x32_bf16 v[48:51], v[170:173], v[186:189], v[48:51]
	v_mfma_f32_16x16x32_bf16 v[44:47], v[144:147], v[194:197], v[44:47]
	v_mfma_f32_16x16x32_bf16 v[40:43], v[170:173], v[194:197], v[40:43]
	v_mfma_f32_16x16x32_bf16 v[36:39], v[144:147], v[210:213], v[36:39]
	v_mfma_f32_16x16x32_bf16 v[32:35], v[170:173], v[210:213], v[32:35]
	v_mfma_f32_16x16x32_bf16 v[60:63], v[148:151], v[182:185], v[60:63]
	v_mfma_f32_16x16x32_bf16 v[56:59], v[174:177], v[182:185], v[56:59]
	v_mfma_f32_16x16x32_bf16 v[52:55], v[148:151], v[190:193], v[52:55]
	v_mfma_f32_16x16x32_bf16 v[48:51], v[174:177], v[190:193], v[48:51]
	s_barrier
	s_setprio 2
	v_mfma_f32_16x16x32_bf16 v[44:47], v[148:151], v[206:209], v[44:47]
	v_mfma_f32_16x16x32_bf16 v[40:43], v[174:177], v[206:209], v[40:43]
	v_mfma_f32_16x16x32_bf16 v[36:39], v[148:151], v[214:217], v[36:39]
	v_mfma_f32_16x16x32_bf16 v[32:35], v[174:177], v[214:217], v[32:35]
	s_setprio 0
	s_add_i32 s16, s52, s67
	v_lshl_add_u64 v[198:199], s[20:21], 0, v[154:155]
	s_mov_b32 m0, s16
	ds_read_b128 v[178:181], v203 offset:16384
	ds_read_b128 v[182:185], v203 offset:17408
	ds_read_b128 v[186:189], v203 offset:18432
	ds_read_b128 v[190:193], v203 offset:19456
	ds_read_b128 v[194:197], v203 offset:20480
	ds_read_b128 v[206:209], v203 offset:21504
	ds_read_b128 v[210:213], v203 offset:22528
	ds_read_b128 v[214:217], v203 offset:23552
	global_load_lds_dwordx4 v154, s[20:21]
	s_add_i32 m0, s16, 0x2000
	s_add_u32 s16, s20, 0x160000
	v_lshl_add_u64 v[218:219], s[20:21], 0, v[158:159]
	s_addc_u32 s17, s21, 0
	s_add_i32 s69, s53, s67
	global_load_lds_dwordx4 v158, s[20:21]
	s_mov_b32 m0, s69
	v_lshl_add_u64 v[222:223], s[22:23], 0, v[156:157]
	global_load_lds_dwordx4 v154, s[16:17]
	s_add_i32 m0, s69, 0x2000
	s_nop 0
	global_load_lds_dwordx4 v158, s[16:17]
	v_lshl_add_u64 v[220:221], s[22:23], 0, v[152:153]
	s_mov_b32 m0, s30
	s_nop 0
	global_load_lds_dwordx4 v152, s[22:23]
	s_mov_b32 m0, s31
	s_nop 0
	global_load_lds_dwordx4 v156, s[22:23]
	s_waitcnt vmcnt(8)
	s_waitcnt lgkmcnt(0)
	s_barrier
	s_setprio 1
	s_waitcnt lgkmcnt(0)
	v_mfma_f32_16x16x32_bf16 v[92:95], v[128:131], v[178:181], v[92:95]
	v_mfma_f32_16x16x32_bf16 v[88:91], v[136:139], v[178:181], v[88:91]
	v_mfma_f32_16x16x32_bf16 v[84:87], v[128:131], v[186:189], v[84:87]
	v_mfma_f32_16x16x32_bf16 v[80:83], v[136:139], v[186:189], v[80:83]
	v_mfma_f32_16x16x32_bf16 v[76:79], v[128:131], v[194:197], v[76:79]
	v_mfma_f32_16x16x32_bf16 v[72:75], v[136:139], v[194:197], v[72:75]
	v_mfma_f32_16x16x32_bf16 v[68:71], v[128:131], v[210:213], v[68:71]
	v_mfma_f32_16x16x32_bf16 v[64:67], v[136:139], v[210:213], v[64:67]
	v_mfma_f32_16x16x32_bf16 v[92:95], v[132:135], v[182:185], v[92:95]
	v_mfma_f32_16x16x32_bf16 v[88:91], v[140:143], v[182:185], v[88:91]
	v_mfma_f32_16x16x32_bf16 v[84:87], v[132:135], v[190:193], v[84:87]
	v_mfma_f32_16x16x32_bf16 v[80:83], v[140:143], v[190:193], v[80:83]
	v_mfma_f32_16x16x32_bf16 v[76:79], v[132:135], v[206:209], v[76:79]
	v_mfma_f32_16x16x32_bf16 v[72:75], v[140:143], v[206:209], v[72:75]
	v_mfma_f32_16x16x32_bf16 v[68:71], v[132:135], v[214:217], v[68:71]
	v_mfma_f32_16x16x32_bf16 v[64:67], v[140:143], v[214:217], v[64:67]
	s_setprio 0
	s_setprio 1
	v_mfma_f32_16x16x32_bf16 v[28:31], v[144:147], v[178:181], v[28:31]
	v_mfma_f32_16x16x32_bf16 v[24:27], v[170:173], v[178:181], v[24:27]
	v_mfma_f32_16x16x32_bf16 v[20:23], v[144:147], v[186:189], v[20:23]
	v_mfma_f32_16x16x32_bf16 v[16:19], v[170:173], v[186:189], v[16:19]
	v_mfma_f32_16x16x32_bf16 v[12:15], v[144:147], v[194:197], v[12:15]
	v_mfma_f32_16x16x32_bf16 v[8:11], v[170:173], v[194:197], v[8:11]
	v_mfma_f32_16x16x32_bf16 v[4:7], v[144:147], v[210:213], v[4:7]
	v_mfma_f32_16x16x32_bf16 v[0:3], v[170:173], v[210:213], v[0:3]
	v_mfma_f32_16x16x32_bf16 v[28:31], v[148:151], v[182:185], v[28:31]
	v_mfma_f32_16x16x32_bf16 v[24:27], v[174:177], v[182:185], v[24:27]
	v_mfma_f32_16x16x32_bf16 v[20:23], v[148:151], v[190:193], v[20:23]
	v_mfma_f32_16x16x32_bf16 v[16:19], v[174:177], v[190:193], v[16:19]
	s_barrier
	s_setprio 2
	v_mfma_f32_16x16x32_bf16 v[12:15], v[148:151], v[206:209], v[12:15]
	v_mfma_f32_16x16x32_bf16 v[8:11], v[174:177], v[206:209], v[8:11]
	v_mfma_f32_16x16x32_bf16 v[4:7], v[148:151], v[214:217], v[4:7]
	v_mfma_f32_16x16x32_bf16 v[0:3], v[174:177], v[214:217], v[0:3]
	s_setprio 0
	s_add_i32 s69, 0, 0x18000
	s_add_i32 s70, 0, 0x1c000
	v_add_u32_e32 v140, s69, v200
	v_add_u32_e32 v160, s70, v200
	ds_read_b128 v[128:131], v140
	ds_read_b128 v[132:135], v140 offset:1024
	ds_read_b128 v[136:139], v140 offset:2048
	ds_read_b128 v[140:143], v140 offset:3072
	ds_read_b128 v[144:147], v160
	ds_read_b128 v[148:151], v160 offset:1024
	ds_read_b128 v[170:173], v160 offset:2048
	ds_read_b128 v[174:177], v160 offset:3072
	s_add_u32 s16, s22, 0x160000
	s_addc_u32 s17, s23, 0
	s_mov_b32 m0, s34
	ds_read_b128 v[178:181], v203 offset:32768
	ds_read_b128 v[182:185], v203 offset:33792
	ds_read_b128 v[186:189], v203 offset:34816
	ds_read_b128 v[190:193], v203 offset:35840
	ds_read_b128 v[194:197], v203 offset:36864
	ds_read_b128 v[206:209], v203 offset:37888
	ds_read_b128 v[210:213], v203 offset:38912
	ds_read_b128 v[214:217], v203 offset:39936
	global_load_lds_dwordx4 v152, s[16:17]
	s_mov_b32 m0, s35
	s_nop 0
	global_load_lds_dwordx4 v156, s[16:17]
	s_waitcnt vmcnt(8)
	s_waitcnt lgkmcnt(0)
	s_barrier
	s_setprio 1
	s_waitcnt lgkmcnt(0)
	v_mfma_f32_16x16x32_bf16 v[124:127], v[128:131], v[178:181], v[124:127]
	v_mfma_f32_16x16x32_bf16 v[120:123], v[136:139], v[178:181], v[120:123]
	v_mfma_f32_16x16x32_bf16 v[116:119], v[128:131], v[186:189], v[116:119]
	v_mfma_f32_16x16x32_bf16 v[112:115], v[136:139], v[186:189], v[112:115]
	v_mfma_f32_16x16x32_bf16 v[108:111], v[128:131], v[194:197], v[108:111]
	v_mfma_f32_16x16x32_bf16 v[104:107], v[136:139], v[194:197], v[104:107]
	v_mfma_f32_16x16x32_bf16 v[100:103], v[128:131], v[210:213], v[100:103]
	v_mfma_f32_16x16x32_bf16 v[96:99], v[136:139], v[210:213], v[96:99]
	v_mfma_f32_16x16x32_bf16 v[124:127], v[132:135], v[182:185], v[124:127]
	v_mfma_f32_16x16x32_bf16 v[120:123], v[140:143], v[182:185], v[120:123]
	v_mfma_f32_16x16x32_bf16 v[116:119], v[132:135], v[190:193], v[116:119]
	v_mfma_f32_16x16x32_bf16 v[112:115], v[140:143], v[190:193], v[112:115]
	v_mfma_f32_16x16x32_bf16 v[108:111], v[132:135], v[206:209], v[108:111]
	v_mfma_f32_16x16x32_bf16 v[104:107], v[140:143], v[206:209], v[104:107]
	v_mfma_f32_16x16x32_bf16 v[100:103], v[132:135], v[214:217], v[100:103]
	v_mfma_f32_16x16x32_bf16 v[96:99], v[140:143], v[214:217], v[96:99]
	s_setprio 0
	s_setprio 1
	v_mfma_f32_16x16x32_bf16 v[60:63], v[144:147], v[178:181], v[60:63]
	v_mfma_f32_16x16x32_bf16 v[56:59], v[170:173], v[178:181], v[56:59]
	v_mfma_f32_16x16x32_bf16 v[52:55], v[144:147], v[186:189], v[52:55]
	v_mfma_f32_16x16x32_bf16 v[48:51], v[170:173], v[186:189], v[48:51]
	v_mfma_f32_16x16x32_bf16 v[44:47], v[144:147], v[194:197], v[44:47]
	v_mfma_f32_16x16x32_bf16 v[40:43], v[170:173], v[194:197], v[40:43]
	v_mfma_f32_16x16x32_bf16 v[36:39], v[144:147], v[210:213], v[36:39]
	v_mfma_f32_16x16x32_bf16 v[32:35], v[170:173], v[210:213], v[32:35]
	v_mfma_f32_16x16x32_bf16 v[60:63], v[148:151], v[182:185], v[60:63]
	v_mfma_f32_16x16x32_bf16 v[56:59], v[174:177], v[182:185], v[56:59]
	v_mfma_f32_16x16x32_bf16 v[52:55], v[148:151], v[190:193], v[52:55]
	v_mfma_f32_16x16x32_bf16 v[48:51], v[174:177], v[190:193], v[48:51]
	s_barrier
	s_setprio 2
	v_mfma_f32_16x16x32_bf16 v[44:47], v[148:151], v[206:209], v[44:47]
	v_mfma_f32_16x16x32_bf16 v[40:43], v[174:177], v[206:209], v[40:43]
	v_mfma_f32_16x16x32_bf16 v[36:39], v[148:151], v[214:217], v[36:39]
	v_mfma_f32_16x16x32_bf16 v[32:35], v[174:177], v[214:217], v[32:35]
	s_setprio 0
	s_add_i32 s16, s69, s67
	v_lshl_add_u64 v[198:199], v[198:199], 0, s[8:9]
	s_mov_b32 m0, s16
	ds_read_b128 v[178:181], v203 offset:49152
	ds_read_b128 v[182:185], v203 offset:50176
	ds_read_b128 v[186:189], v203 offset:51200
	ds_read_b128 v[190:193], v203 offset:52224
	ds_read_b128 v[194:197], v203 offset:53248
	ds_read_b128 v[206:209], v203 offset:54272
	ds_read_b128 v[210:213], v203 offset:55296
	ds_read_b128 v[214:217], v203 offset:56320
	global_load_lds_dwordx4 v[198:199], off
	s_add_i32 m0, s16, 0x2000
	s_add_u32 s16, s20, 0x160080
	v_lshl_add_u64 v[198:199], v[218:219], 0, s[8:9]
	s_addc_u32 s17, s21, 0
	s_add_i32 s20, s70, s67
	global_load_lds_dwordx4 v[198:199], off
	s_mov_b32 m0, s20
	s_nop 0
	global_load_lds_dwordx4 v154, s[16:17]
	s_add_i32 m0, s20, 0x2000
	s_nop 0
	global_load_lds_dwordx4 v158, s[16:17]
	v_lshl_add_u64 v[198:199], v[220:221], 0, s[8:9]
	s_mov_b32 m0, s47
	s_nop 0
	global_load_lds_dwordx4 v[198:199], off
	v_lshl_add_u64 v[198:199], v[222:223], 0, s[8:9]
	s_mov_b32 m0, s48
	s_nop 0
	global_load_lds_dwordx4 v[198:199], off
	s_waitcnt vmcnt(8)
	s_waitcnt lgkmcnt(0)
	s_barrier
	s_setprio 1
	s_waitcnt lgkmcnt(0)
	v_mfma_f32_16x16x32_bf16 v[92:95], v[128:131], v[178:181], v[92:95]
	v_mfma_f32_16x16x32_bf16 v[88:91], v[136:139], v[178:181], v[88:91]
	v_mfma_f32_16x16x32_bf16 v[84:87], v[128:131], v[186:189], v[84:87]
	v_mfma_f32_16x16x32_bf16 v[80:83], v[136:139], v[186:189], v[80:83]
	v_mfma_f32_16x16x32_bf16 v[76:79], v[128:131], v[194:197], v[76:79]
	v_mfma_f32_16x16x32_bf16 v[72:75], v[136:139], v[194:197], v[72:75]
	v_mfma_f32_16x16x32_bf16 v[68:71], v[128:131], v[210:213], v[68:71]
	v_mfma_f32_16x16x32_bf16 v[64:67], v[136:139], v[210:213], v[64:67]
	v_mfma_f32_16x16x32_bf16 v[92:95], v[132:135], v[182:185], v[92:95]
	v_mfma_f32_16x16x32_bf16 v[88:91], v[140:143], v[182:185], v[88:91]
	v_mfma_f32_16x16x32_bf16 v[84:87], v[132:135], v[190:193], v[84:87]
	v_mfma_f32_16x16x32_bf16 v[80:83], v[140:143], v[190:193], v[80:83]
	v_mfma_f32_16x16x32_bf16 v[76:79], v[132:135], v[206:209], v[76:79]
	v_mfma_f32_16x16x32_bf16 v[72:75], v[140:143], v[206:209], v[72:75]
	v_mfma_f32_16x16x32_bf16 v[68:71], v[132:135], v[214:217], v[68:71]
	v_mfma_f32_16x16x32_bf16 v[64:67], v[140:143], v[214:217], v[64:67]
	s_setprio 0
	s_setprio 1
	v_mfma_f32_16x16x32_bf16 v[28:31], v[144:147], v[178:181], v[28:31]
	v_mfma_f32_16x16x32_bf16 v[24:27], v[170:173], v[178:181], v[24:27]
	v_mfma_f32_16x16x32_bf16 v[20:23], v[144:147], v[186:189], v[20:23]
	v_mfma_f32_16x16x32_bf16 v[16:19], v[170:173], v[186:189], v[16:19]
	v_mfma_f32_16x16x32_bf16 v[12:15], v[144:147], v[194:197], v[12:15]
	v_mfma_f32_16x16x32_bf16 v[8:11], v[170:173], v[194:197], v[8:11]
	v_mfma_f32_16x16x32_bf16 v[4:7], v[144:147], v[210:213], v[4:7]
	v_mfma_f32_16x16x32_bf16 v[0:3], v[170:173], v[210:213], v[0:3]
	v_mfma_f32_16x16x32_bf16 v[28:31], v[148:151], v[182:185], v[28:31]
	v_mfma_f32_16x16x32_bf16 v[24:27], v[174:177], v[182:185], v[24:27]
	v_mfma_f32_16x16x32_bf16 v[20:23], v[148:151], v[190:193], v[20:23]
	v_mfma_f32_16x16x32_bf16 v[16:19], v[174:177], v[190:193], v[16:19]
	s_barrier
	s_setprio 2
	v_mfma_f32_16x16x32_bf16 v[12:15], v[148:151], v[206:209], v[12:15]
	v_mfma_f32_16x16x32_bf16 v[8:11], v[174:177], v[206:209], v[8:11]
	v_mfma_f32_16x16x32_bf16 v[4:7], v[148:151], v[214:217], v[4:7]
	v_mfma_f32_16x16x32_bf16 v[0:3], v[174:177], v[214:217], v[0:3]
	s_setprio 0
	s_add_i32 s68, s68, 2
	s_add_u32 s24, s24, 0x100
	s_addc_u32 s25, s25, 0
	s_cmpk_gt_u32 s68, 0x55
	s_mov_b64 s[16:17], s[18:19]
	s_cbranch_scc0 .LBB0_3501
	s_and_b64 vcc, exec, s[10:11]
	s_cbranch_vccz .LBB0_3504
	s_barrier
